# K-loops: last two of the six LDS-DMA loads of each SP2 staging segment issued after the segment barrier (head of MFMA segment); SP2 wait vmcnt(8)->vmcnt(6)
# baseline (speedup 1.0000x reference)
.LBB0_178:
	ds_read_b128 v[148:151], v157
	ds_read_b128 v[162:165], v157 offset:1024
	ds_read_b128 v[166:169], v157 offset:2048
	ds_read_b128 v[170:173], v157 offset:3072
	ds_read_b128 v[174:177], v158
	ds_read_b128 v[178:181], v158 offset:1024
	ds_read_b128 v[182:185], v158 offset:2048
	ds_read_b128 v[186:189], v158 offset:3072
	s_add_u32 s48, s46, 0xfff80080
	s_addc_u32 s49, s47, -1
	s_cmp_eq_u32 s72, 28
	s_cselect_b32 s51, s31, s49
	s_cselect_b32 s50, s66, s48
	s_cselect_b32 s49, s27, s71
	s_cselect_b32 s48, s67, s70
	v_lshl_add_u64 v[152:153], s[46:47], 0, v[142:143]
	s_add_i32 m0, s13, 0xc000
	ds_read_b128 v[190:193], v159
	ds_read_b128 v[194:197], v159 offset:1024
	ds_read_b128 v[198:201], v159 offset:2048
	ds_read_b128 v[202:205], v159 offset:3072
	ds_read_b128 v[206:209], v159 offset:4096
	ds_read_b128 v[210:213], v159 offset:5120
	ds_read_b128 v[214:217], v159 offset:6144
	ds_read_b128 v[218:221], v159 offset:7168
	global_load_lds_dwordx4 v[152:153], off
	v_lshl_add_u64 v[152:153], s[46:47], 0, v[140:141]
	s_add_i32 m0, s13, 0xe000
	s_nop 0
	global_load_lds_dwordx4 v[152:153], off
	s_waitcnt vmcnt(8)
	s_waitcnt lgkmcnt(0)
	s_barrier
	s_setprio 1
	s_waitcnt lgkmcnt(0)
	v_mfma_f32_16x16x32_bf16 v[124:127], v[148:151], v[190:193], v[124:127]
	v_mfma_f32_16x16x32_bf16 v[120:123], v[166:169], v[190:193], v[120:123]
	v_mfma_f32_16x16x32_bf16 v[108:111], v[148:151], v[198:201], v[108:111]
	v_mfma_f32_16x16x32_bf16 v[104:107], v[166:169], v[198:201], v[104:107]
	v_mfma_f32_16x16x32_bf16 v[92:95], v[148:151], v[206:209], v[92:95]
	v_mfma_f32_16x16x32_bf16 v[88:91], v[166:169], v[206:209], v[88:91]
	v_mfma_f32_16x16x32_bf16 v[76:79], v[148:151], v[214:217], v[76:79]
	v_mfma_f32_16x16x32_bf16 v[72:75], v[166:169], v[214:217], v[72:75]
	v_mfma_f32_16x16x32_bf16 v[124:127], v[162:165], v[194:197], v[124:127]
	v_mfma_f32_16x16x32_bf16 v[120:123], v[170:173], v[194:197], v[120:123]
	v_mfma_f32_16x16x32_bf16 v[108:111], v[162:165], v[202:205], v[108:111]
	v_mfma_f32_16x16x32_bf16 v[104:107], v[170:173], v[202:205], v[104:107]
	v_mfma_f32_16x16x32_bf16 v[92:95], v[162:165], v[210:213], v[92:95]
	v_mfma_f32_16x16x32_bf16 v[88:91], v[170:173], v[210:213], v[88:91]
	v_mfma_f32_16x16x32_bf16 v[76:79], v[162:165], v[218:221], v[76:79]
	v_mfma_f32_16x16x32_bf16 v[72:75], v[170:173], v[218:221], v[72:75]
	s_setprio 0
	s_setprio 1
	v_mfma_f32_16x16x32_bf16 v[116:119], v[174:177], v[190:193], v[116:119]
	v_mfma_f32_16x16x32_bf16 v[112:115], v[182:185], v[190:193], v[112:115]
	v_mfma_f32_16x16x32_bf16 v[100:103], v[174:177], v[198:201], v[100:103]
	v_mfma_f32_16x16x32_bf16 v[96:99], v[182:185], v[198:201], v[96:99]
	v_mfma_f32_16x16x32_bf16 v[84:87], v[174:177], v[206:209], v[84:87]
	v_mfma_f32_16x16x32_bf16 v[80:83], v[182:185], v[206:209], v[80:83]
	v_mfma_f32_16x16x32_bf16 v[68:71], v[174:177], v[214:217], v[68:71]
	v_mfma_f32_16x16x32_bf16 v[64:67], v[182:185], v[214:217], v[64:67]
	v_mfma_f32_16x16x32_bf16 v[116:119], v[178:181], v[194:197], v[116:119]
	v_mfma_f32_16x16x32_bf16 v[112:115], v[186:189], v[194:197], v[112:115]
	v_mfma_f32_16x16x32_bf16 v[100:103], v[178:181], v[202:205], v[100:103]
	v_mfma_f32_16x16x32_bf16 v[96:99], v[186:189], v[202:205], v[96:99]
	v_mfma_f32_16x16x32_bf16 v[84:87], v[178:181], v[210:213], v[84:87]
	v_mfma_f32_16x16x32_bf16 v[80:83], v[186:189], v[210:213], v[80:83]
	v_mfma_f32_16x16x32_bf16 v[68:71], v[178:181], v[218:221], v[68:71]
	v_mfma_f32_16x16x32_bf16 v[64:67], v[186:189], v[218:221], v[64:67]
	s_setprio 0
	s_barrier
	s_add_i32 s73, s62, s52
	v_lshl_add_u64 v[152:153], s[48:49], 0, v[130:131]
	s_mov_b32 m0, s73
	ds_read_b128 v[190:193], v159 offset:16384
	ds_read_b128 v[194:197], v159 offset:17408
	ds_read_b128 v[198:201], v159 offset:18432
	ds_read_b128 v[202:205], v159 offset:19456
	ds_read_b128 v[206:209], v159 offset:20480
	ds_read_b128 v[210:213], v159 offset:21504
	ds_read_b128 v[214:217], v159 offset:22528
	ds_read_b128 v[218:221], v159 offset:23552
	global_load_lds_dwordx4 v[152:153], off
	s_add_i32 m0, s73, 0x2000
	s_add_u32 s74, s48, 0x80000
	v_lshl_add_u64 v[222:223], s[48:49], 0, v[134:135]
	s_addc_u32 s75, s49, 0
	s_add_i32 s73, s63, s52
	global_load_lds_dwordx4 v[222:223], off
	v_lshl_add_u64 v[224:225], s[74:75], 0, v[130:131]
	s_mov_b32 m0, s73
	v_lshl_add_u64 v[226:227], s[50:51], 0, v[132:133]
	global_load_lds_dwordx4 v[224:225], off
	v_lshl_add_u64 v[224:225], s[74:75], 0, v[134:135]
	s_add_i32 m0, s73, 0x2000
	s_nop 0
	global_load_lds_dwordx4 v[224:225], off
	s_waitcnt vmcnt(6)
	s_waitcnt lgkmcnt(0)
	s_barrier
	v_lshl_add_u64 v[224:225], s[50:51], 0, v[128:129]
	s_mov_b32 m0, s13
	s_nop 0
	global_load_lds_dwordx4 v[224:225], off
	s_mov_b32 m0, s53
	s_nop 0
	global_load_lds_dwordx4 v[226:227], off
	s_setprio 1
	s_waitcnt lgkmcnt(0)
	v_mfma_f32_16x16x32_bf16 v[60:63], v[148:151], v[190:193], v[60:63]
	v_mfma_f32_16x16x32_bf16 v[56:59], v[166:169], v[190:193], v[56:59]
	v_mfma_f32_16x16x32_bf16 v[44:47], v[148:151], v[198:201], v[44:47]
	v_mfma_f32_16x16x32_bf16 v[40:43], v[166:169], v[198:201], v[40:43]
	v_mfma_f32_16x16x32_bf16 v[28:31], v[148:151], v[206:209], v[28:31]
	v_mfma_f32_16x16x32_bf16 v[24:27], v[166:169], v[206:209], v[24:27]
	v_mfma_f32_16x16x32_bf16 v[12:15], v[148:151], v[214:217], v[12:15]
	v_mfma_f32_16x16x32_bf16 v[8:11], v[166:169], v[214:217], v[8:11]
	v_mfma_f32_16x16x32_bf16 v[60:63], v[162:165], v[194:197], v[60:63]
	v_mfma_f32_16x16x32_bf16 v[56:59], v[170:173], v[194:197], v[56:59]
	v_mfma_f32_16x16x32_bf16 v[44:47], v[162:165], v[202:205], v[44:47]
	v_mfma_f32_16x16x32_bf16 v[40:43], v[170:173], v[202:205], v[40:43]
	v_mfma_f32_16x16x32_bf16 v[28:31], v[162:165], v[210:213], v[28:31]
	v_mfma_f32_16x16x32_bf16 v[24:27], v[170:173], v[210:213], v[24:27]
	v_mfma_f32_16x16x32_bf16 v[12:15], v[162:165], v[218:221], v[12:15]
	v_mfma_f32_16x16x32_bf16 v[8:11], v[170:173], v[218:221], v[8:11]
	s_setprio 0
	s_setprio 1
	v_mfma_f32_16x16x32_bf16 v[52:55], v[174:177], v[190:193], v[52:55]
	v_mfma_f32_16x16x32_bf16 v[48:51], v[182:185], v[190:193], v[48:51]
	v_mfma_f32_16x16x32_bf16 v[36:39], v[174:177], v[198:201], v[36:39]
	v_mfma_f32_16x16x32_bf16 v[32:35], v[182:185], v[198:201], v[32:35]
	v_mfma_f32_16x16x32_bf16 v[20:23], v[174:177], v[206:209], v[20:23]
	v_mfma_f32_16x16x32_bf16 v[16:19], v[182:185], v[206:209], v[16:19]
	v_mfma_f32_16x16x32_bf16 v[4:7], v[174:177], v[214:217], v[4:7]
	v_mfma_f32_16x16x32_bf16 v[0:3], v[182:185], v[214:217], v[0:3]
	v_mfma_f32_16x16x32_bf16 v[52:55], v[178:181], v[194:197], v[52:55]
	v_mfma_f32_16x16x32_bf16 v[48:51], v[186:189], v[194:197], v[48:51]
	v_mfma_f32_16x16x32_bf16 v[36:39], v[178:181], v[202:205], v[36:39]
	v_mfma_f32_16x16x32_bf16 v[32:35], v[186:189], v[202:205], v[32:35]
	v_mfma_f32_16x16x32_bf16 v[20:23], v[178:181], v[210:213], v[20:23]
	v_mfma_f32_16x16x32_bf16 v[16:19], v[186:189], v[210:213], v[16:19]
	v_mfma_f32_16x16x32_bf16 v[4:7], v[178:181], v[218:221], v[4:7]
	v_mfma_f32_16x16x32_bf16 v[0:3], v[186:189], v[218:221], v[0:3]
	s_setprio 0
	s_barrier
	s_add_i32 s73, 0, 0x18000
	v_add_u32_e32 v137, s73, v155
	s_add_i32 s74, 0, 0x1c000
	ds_read_b128 v[148:151], v137
	ds_read_b128 v[162:165], v137 offset:1024
	ds_read_b128 v[166:169], v137 offset:2048
	ds_read_b128 v[170:173], v137 offset:3072
	v_add_u32_e32 v137, s74, v155
	ds_read_b128 v[174:177], v137
	ds_read_b128 v[178:181], v137 offset:1024
	ds_read_b128 v[182:185], v137 offset:2048
	ds_read_b128 v[186:189], v137 offset:3072
	s_add_u32 s50, s50, 0x80000
	s_addc_u32 s51, s51, 0
	s_mov_b32 m0, s54
	v_lshl_add_u64 v[228:229], s[50:51], 0, v[128:129]
	ds_read_b128 v[190:193], v159 offset:32768
	ds_read_b128 v[194:197], v159 offset:33792
	ds_read_b128 v[198:201], v159 offset:34816
	ds_read_b128 v[202:205], v159 offset:35840
	ds_read_b128 v[206:209], v159 offset:36864
	ds_read_b128 v[210:213], v159 offset:37888
	ds_read_b128 v[214:217], v159 offset:38912
	ds_read_b128 v[218:221], v159 offset:39936
	global_load_lds_dwordx4 v[228:229], off
	v_lshl_add_u64 v[228:229], s[50:51], 0, v[132:133]
	s_mov_b32 m0, s55
	s_nop 0
	global_load_lds_dwordx4 v[228:229], off
	s_waitcnt vmcnt(8)
	s_waitcnt lgkmcnt(0)
	s_barrier
	s_setprio 1
	s_waitcnt lgkmcnt(0)
	v_mfma_f32_16x16x32_bf16 v[124:127], v[148:151], v[190:193], v[124:127]
	v_mfma_f32_16x16x32_bf16 v[120:123], v[166:169], v[190:193], v[120:123]
	v_mfma_f32_16x16x32_bf16 v[108:111], v[148:151], v[198:201], v[108:111]
	v_mfma_f32_16x16x32_bf16 v[104:107], v[166:169], v[198:201], v[104:107]
	v_mfma_f32_16x16x32_bf16 v[92:95], v[148:151], v[206:209], v[92:95]
	v_mfma_f32_16x16x32_bf16 v[88:91], v[166:169], v[206:209], v[88:91]
	v_mfma_f32_16x16x32_bf16 v[76:79], v[148:151], v[214:217], v[76:79]
	v_mfma_f32_16x16x32_bf16 v[72:75], v[166:169], v[214:217], v[72:75]
	v_mfma_f32_16x16x32_bf16 v[124:127], v[162:165], v[194:197], v[124:127]
	v_mfma_f32_16x16x32_bf16 v[120:123], v[170:173], v[194:197], v[120:123]
	v_mfma_f32_16x16x32_bf16 v[108:111], v[162:165], v[202:205], v[108:111]
	v_mfma_f32_16x16x32_bf16 v[104:107], v[170:173], v[202:205], v[104:107]
	v_mfma_f32_16x16x32_bf16 v[92:95], v[162:165], v[210:213], v[92:95]
	v_mfma_f32_16x16x32_bf16 v[88:91], v[170:173], v[210:213], v[88:91]
	v_mfma_f32_16x16x32_bf16 v[76:79], v[162:165], v[218:221], v[76:79]
	v_mfma_f32_16x16x32_bf16 v[72:75], v[170:173], v[218:221], v[72:75]
	s_setprio 0
	s_setprio 1
	v_mfma_f32_16x16x32_bf16 v[116:119], v[174:177], v[190:193], v[116:119]
	v_mfma_f32_16x16x32_bf16 v[112:115], v[182:185], v[190:193], v[112:115]
	v_mfma_f32_16x16x32_bf16 v[100:103], v[174:177], v[198:201], v[100:103]
	v_mfma_f32_16x16x32_bf16 v[96:99], v[182:185], v[198:201], v[96:99]
	v_mfma_f32_16x16x32_bf16 v[84:87], v[174:177], v[206:209], v[84:87]
	v_mfma_f32_16x16x32_bf16 v[80:83], v[182:185], v[206:209], v[80:83]
	v_mfma_f32_16x16x32_bf16 v[68:71], v[174:177], v[214:217], v[68:71]
	v_mfma_f32_16x16x32_bf16 v[64:67], v[182:185], v[214:217], v[64:67]
	v_mfma_f32_16x16x32_bf16 v[116:119], v[178:181], v[194:197], v[116:119]
	v_mfma_f32_16x16x32_bf16 v[112:115], v[186:189], v[194:197], v[112:115]
	v_mfma_f32_16x16x32_bf16 v[100:103], v[178:181], v[202:205], v[100:103]
	v_mfma_f32_16x16x32_bf16 v[96:99], v[186:189], v[202:205], v[96:99]
	v_mfma_f32_16x16x32_bf16 v[84:87], v[178:181], v[210:213], v[84:87]
	v_mfma_f32_16x16x32_bf16 v[80:83], v[186:189], v[210:213], v[80:83]
	v_mfma_f32_16x16x32_bf16 v[68:71], v[178:181], v[218:221], v[68:71]
	v_mfma_f32_16x16x32_bf16 v[64:67], v[186:189], v[218:221], v[64:67]
	s_setprio 0
	s_barrier
	s_add_i32 s50, s73, s52
	v_lshl_add_u64 v[152:153], v[152:153], 0, s[22:23]
	s_mov_b32 m0, s50
	ds_read_b128 v[190:193], v159 offset:49152
	ds_read_b128 v[194:197], v159 offset:50176
	ds_read_b128 v[198:201], v159 offset:51200
	ds_read_b128 v[202:205], v159 offset:52224
	ds_read_b128 v[206:209], v159 offset:53248
	ds_read_b128 v[210:213], v159 offset:54272
	ds_read_b128 v[214:217], v159 offset:55296
	ds_read_b128 v[218:221], v159 offset:56320
	global_load_lds_dwordx4 v[152:153], off
	s_add_i32 m0, s50, 0x2000
	s_add_u32 s48, s48, 0x80080
	v_lshl_add_u64 v[152:153], v[222:223], 0, s[22:23]
	s_addc_u32 s49, s49, 0
	s_add_i32 s50, s74, s52
	global_load_lds_dwordx4 v[152:153], off
	v_lshl_add_u64 v[152:153], s[48:49], 0, v[130:131]
	s_mov_b32 m0, s50
	s_nop 0
	global_load_lds_dwordx4 v[152:153], off
	v_lshl_add_u64 v[152:153], s[48:49], 0, v[134:135]
	s_add_i32 m0, s50, 0x2000
	s_nop 0
	global_load_lds_dwordx4 v[152:153], off
	s_waitcnt vmcnt(6)
	s_waitcnt lgkmcnt(0)
	s_barrier
	v_lshl_add_u64 v[152:153], v[224:225], 0, s[22:23]
	s_mov_b32 m0, s57
	s_nop 0
	global_load_lds_dwordx4 v[152:153], off
	v_lshl_add_u64 v[152:153], v[226:227], 0, s[22:23]
	s_mov_b32 m0, s58
	s_nop 0
	global_load_lds_dwordx4 v[152:153], off
	s_setprio 1
	s_waitcnt lgkmcnt(0)
	v_mfma_f32_16x16x32_bf16 v[60:63], v[148:151], v[190:193], v[60:63]
	v_mfma_f32_16x16x32_bf16 v[56:59], v[166:169], v[190:193], v[56:59]
	v_mfma_f32_16x16x32_bf16 v[44:47], v[148:151], v[198:201], v[44:47]
	v_mfma_f32_16x16x32_bf16 v[40:43], v[166:169], v[198:201], v[40:43]
	v_mfma_f32_16x16x32_bf16 v[28:31], v[148:151], v[206:209], v[28:31]
	v_mfma_f32_16x16x32_bf16 v[24:27], v[166:169], v[206:209], v[24:27]
	v_mfma_f32_16x16x32_bf16 v[12:15], v[148:151], v[214:217], v[12:15]
	v_mfma_f32_16x16x32_bf16 v[8:11], v[166:169], v[214:217], v[8:11]
	v_mfma_f32_16x16x32_bf16 v[60:63], v[162:165], v[194:197], v[60:63]
	v_mfma_f32_16x16x32_bf16 v[56:59], v[170:173], v[194:197], v[56:59]
	v_mfma_f32_16x16x32_bf16 v[44:47], v[162:165], v[202:205], v[44:47]
	v_mfma_f32_16x16x32_bf16 v[40:43], v[170:173], v[202:205], v[40:43]
	v_mfma_f32_16x16x32_bf16 v[28:31], v[162:165], v[210:213], v[28:31]
	v_mfma_f32_16x16x32_bf16 v[24:27], v[170:173], v[210:213], v[24:27]
	v_mfma_f32_16x16x32_bf16 v[12:15], v[162:165], v[218:221], v[12:15]
	v_mfma_f32_16x16x32_bf16 v[8:11], v[170:173], v[218:221], v[8:11]
	s_setprio 0
	s_setprio 1
	v_mfma_f32_16x16x32_bf16 v[52:55], v[174:177], v[190:193], v[52:55]
	v_mfma_f32_16x16x32_bf16 v[48:51], v[182:185], v[190:193], v[48:51]
	v_mfma_f32_16x16x32_bf16 v[36:39], v[174:177], v[198:201], v[36:39]
	v_mfma_f32_16x16x32_bf16 v[32:35], v[182:185], v[198:201], v[32:35]
	v_mfma_f32_16x16x32_bf16 v[20:23], v[174:177], v[206:209], v[20:23]
	v_mfma_f32_16x16x32_bf16 v[16:19], v[182:185], v[206:209], v[16:19]
	v_mfma_f32_16x16x32_bf16 v[4:7], v[174:177], v[214:217], v[4:7]
	v_mfma_f32_16x16x32_bf16 v[0:3], v[182:185], v[214:217], v[0:3]
	v_mfma_f32_16x16x32_bf16 v[52:55], v[178:181], v[194:197], v[52:55]
	v_mfma_f32_16x16x32_bf16 v[48:51], v[186:189], v[194:197], v[48:51]
	v_mfma_f32_16x16x32_bf16 v[36:39], v[178:181], v[202:205], v[36:39]
	v_mfma_f32_16x16x32_bf16 v[32:35], v[186:189], v[202:205], v[32:35]
	v_mfma_f32_16x16x32_bf16 v[20:23], v[178:181], v[210:213], v[20:23]
	v_mfma_f32_16x16x32_bf16 v[16:19], v[186:189], v[210:213], v[16:19]
	v_mfma_f32_16x16x32_bf16 v[4:7], v[178:181], v[218:221], v[4:7]
	v_mfma_f32_16x16x32_bf16 v[0:3], v[186:189], v[218:221], v[0:3]
	s_setprio 0
	s_barrier
	s_add_i32 s72, s72, 2
	s_add_u32 s70, s70, 0x100
	s_addc_u32 s71, s71, 0
	s_add_u32 s46, s46, 0x100
	s_addc_u32 s47, s47, 0
	s_cmp_gt_u32 s72, 29
	s_cbranch_scc0 .LBB0_178
	s_and_b64 vcc, exec, s[24:25]
	s_cbranch_vccz .LBB0_181
	s_barrier

.LBB0_337:
	ds_read_b128 v[144:147], v151
	ds_read_b128 v[156:159], v151 offset:1024
	ds_read_b128 v[160:163], v151 offset:2048
	ds_read_b128 v[164:167], v151 offset:3072
	ds_read_b128 v[168:171], v152
	ds_read_b128 v[172:175], v152 offset:1024
	ds_read_b128 v[176:179], v152 offset:2048
	ds_read_b128 v[180:183], v152 offset:3072
	s_add_u32 s50, s48, 0xfff80080
	s_addc_u32 s51, s49, -1
	s_cmp_eq_u32 s75, 28
	s_cselect_b32 s53, s31, s51
	s_cselect_b32 s52, s47, s50
	s_cselect_b32 s51, s27, s74
	s_cselect_b32 s50, s71, s72
	v_lshl_add_u64 v[216:217], s[48:49], 0, v[138:139]
	s_add_i32 m0, s57, 0xc000
	ds_read_b128 v[184:187], v153
	ds_read_b128 v[188:191], v153 offset:1024
	ds_read_b128 v[192:195], v153 offset:2048
	ds_read_b128 v[196:199], v153 offset:3072
	ds_read_b128 v[200:203], v153 offset:4096
	ds_read_b128 v[204:207], v153 offset:5120
	ds_read_b128 v[208:211], v153 offset:6144
	ds_read_b128 v[212:215], v153 offset:7168
	global_load_lds_dwordx4 v[216:217], off
	v_lshl_add_u64 v[216:217], s[48:49], 0, v[136:137]
	s_add_i32 m0, s57, 0xe000
	s_nop 0
	global_load_lds_dwordx4 v[216:217], off
	s_waitcnt vmcnt(8)
	s_waitcnt lgkmcnt(0)
	s_barrier
	s_setprio 1
	s_waitcnt lgkmcnt(0)
	v_mfma_f32_16x16x32_bf16 v[124:127], v[144:147], v[184:187], v[124:127]
	v_mfma_f32_16x16x32_bf16 v[120:123], v[160:163], v[184:187], v[120:123]
	v_mfma_f32_16x16x32_bf16 v[108:111], v[144:147], v[192:195], v[108:111]
	v_mfma_f32_16x16x32_bf16 v[104:107], v[160:163], v[192:195], v[104:107]
	v_mfma_f32_16x16x32_bf16 v[92:95], v[144:147], v[200:203], v[92:95]
	v_mfma_f32_16x16x32_bf16 v[88:91], v[160:163], v[200:203], v[88:91]
	v_mfma_f32_16x16x32_bf16 v[76:79], v[144:147], v[208:211], v[76:79]
	v_mfma_f32_16x16x32_bf16 v[72:75], v[160:163], v[208:211], v[72:75]
	v_mfma_f32_16x16x32_bf16 v[124:127], v[156:159], v[188:191], v[124:127]
	v_mfma_f32_16x16x32_bf16 v[120:123], v[164:167], v[188:191], v[120:123]
	v_mfma_f32_16x16x32_bf16 v[108:111], v[156:159], v[196:199], v[108:111]
	v_mfma_f32_16x16x32_bf16 v[104:107], v[164:167], v[196:199], v[104:107]
	v_mfma_f32_16x16x32_bf16 v[92:95], v[156:159], v[204:207], v[92:95]
	v_mfma_f32_16x16x32_bf16 v[88:91], v[164:167], v[204:207], v[88:91]
	v_mfma_f32_16x16x32_bf16 v[76:79], v[156:159], v[212:215], v[76:79]
	v_mfma_f32_16x16x32_bf16 v[72:75], v[164:167], v[212:215], v[72:75]
	s_setprio 0
	s_setprio 1
	v_mfma_f32_16x16x32_bf16 v[116:119], v[168:171], v[184:187], v[116:119]
	v_mfma_f32_16x16x32_bf16 v[112:115], v[176:179], v[184:187], v[112:115]
	v_mfma_f32_16x16x32_bf16 v[100:103], v[168:171], v[192:195], v[100:103]
	v_mfma_f32_16x16x32_bf16 v[96:99], v[176:179], v[192:195], v[96:99]
	v_mfma_f32_16x16x32_bf16 v[84:87], v[168:171], v[200:203], v[84:87]
	v_mfma_f32_16x16x32_bf16 v[80:83], v[176:179], v[200:203], v[80:83]
	v_mfma_f32_16x16x32_bf16 v[68:71], v[168:171], v[208:211], v[68:71]
	v_mfma_f32_16x16x32_bf16 v[64:67], v[176:179], v[208:211], v[64:67]
	v_mfma_f32_16x16x32_bf16 v[116:119], v[172:175], v[188:191], v[116:119]
	v_mfma_f32_16x16x32_bf16 v[112:115], v[180:183], v[188:191], v[112:115]
	v_mfma_f32_16x16x32_bf16 v[100:103], v[172:175], v[196:199], v[100:103]
	v_mfma_f32_16x16x32_bf16 v[96:99], v[180:183], v[196:199], v[96:99]
	v_mfma_f32_16x16x32_bf16 v[84:87], v[172:175], v[204:207], v[84:87]
	v_mfma_f32_16x16x32_bf16 v[80:83], v[180:183], v[204:207], v[80:83]
	v_mfma_f32_16x16x32_bf16 v[68:71], v[172:175], v[212:215], v[68:71]
	v_mfma_f32_16x16x32_bf16 v[64:67], v[180:183], v[212:215], v[64:67]
	s_setprio 0
	s_barrier
	s_add_i32 s76, s66, s56
	v_lshl_add_u64 v[216:217], s[50:51], 0, v[130:131]
	s_mov_b32 m0, s76
	ds_read_b128 v[184:187], v153 offset:16384
	ds_read_b128 v[188:191], v153 offset:17408
	ds_read_b128 v[192:195], v153 offset:18432
	ds_read_b128 v[196:199], v153 offset:19456
	ds_read_b128 v[200:203], v153 offset:20480
	ds_read_b128 v[204:207], v153 offset:21504
	ds_read_b128 v[208:211], v153 offset:22528
	ds_read_b128 v[212:215], v153 offset:23552
	global_load_lds_dwordx4 v[216:217], off
	s_add_i32 m0, s76, 0x2000
	s_add_u32 s76, s50, 0x80000
	v_lshl_add_u64 v[218:219], s[50:51], 0, v[134:135]
	s_addc_u32 s77, s51, 0
	s_add_i32 s78, s67, s56
	global_load_lds_dwordx4 v[218:219], off
	v_lshl_add_u64 v[220:221], s[76:77], 0, v[130:131]
	s_mov_b32 m0, s78
	v_lshl_add_u64 v[222:223], s[52:53], 0, v[132:133]
	global_load_lds_dwordx4 v[220:221], off
	v_lshl_add_u64 v[220:221], s[76:77], 0, v[134:135]
	s_add_i32 m0, s78, 0x2000
	s_nop 0
	global_load_lds_dwordx4 v[220:221], off
	s_waitcnt vmcnt(6)
	s_waitcnt lgkmcnt(0)
	s_barrier
	v_lshl_add_u64 v[220:221], s[52:53], 0, v[128:129]
	s_mov_b32 m0, s57
	s_nop 0
	global_load_lds_dwordx4 v[220:221], off
	s_mov_b32 m0, s58
	s_nop 0
	global_load_lds_dwordx4 v[222:223], off
	s_setprio 1
	s_waitcnt lgkmcnt(0)
	v_mfma_f32_16x16x32_bf16 v[60:63], v[144:147], v[184:187], v[60:63]
	v_mfma_f32_16x16x32_bf16 v[56:59], v[160:163], v[184:187], v[56:59]
	v_mfma_f32_16x16x32_bf16 v[44:47], v[144:147], v[192:195], v[44:47]
	v_mfma_f32_16x16x32_bf16 v[40:43], v[160:163], v[192:195], v[40:43]
	v_mfma_f32_16x16x32_bf16 v[28:31], v[144:147], v[200:203], v[28:31]
	v_mfma_f32_16x16x32_bf16 v[24:27], v[160:163], v[200:203], v[24:27]
	v_mfma_f32_16x16x32_bf16 v[12:15], v[144:147], v[208:211], v[12:15]
	v_mfma_f32_16x16x32_bf16 v[8:11], v[160:163], v[208:211], v[8:11]
	v_mfma_f32_16x16x32_bf16 v[60:63], v[156:159], v[188:191], v[60:63]
	v_mfma_f32_16x16x32_bf16 v[56:59], v[164:167], v[188:191], v[56:59]
	v_mfma_f32_16x16x32_bf16 v[44:47], v[156:159], v[196:199], v[44:47]
	v_mfma_f32_16x16x32_bf16 v[40:43], v[164:167], v[196:199], v[40:43]
	v_mfma_f32_16x16x32_bf16 v[28:31], v[156:159], v[204:207], v[28:31]
	v_mfma_f32_16x16x32_bf16 v[24:27], v[164:167], v[204:207], v[24:27]
	v_mfma_f32_16x16x32_bf16 v[12:15], v[156:159], v[212:215], v[12:15]
	v_mfma_f32_16x16x32_bf16 v[8:11], v[164:167], v[212:215], v[8:11]
	s_setprio 0
	s_setprio 1
	v_mfma_f32_16x16x32_bf16 v[52:55], v[168:171], v[184:187], v[52:55]
	v_mfma_f32_16x16x32_bf16 v[48:51], v[176:179], v[184:187], v[48:51]
	v_mfma_f32_16x16x32_bf16 v[36:39], v[168:171], v[192:195], v[36:39]
	v_mfma_f32_16x16x32_bf16 v[32:35], v[176:179], v[192:195], v[32:35]
	v_mfma_f32_16x16x32_bf16 v[20:23], v[168:171], v[200:203], v[20:23]
	v_mfma_f32_16x16x32_bf16 v[16:19], v[176:179], v[200:203], v[16:19]
	v_mfma_f32_16x16x32_bf16 v[4:7], v[168:171], v[208:211], v[4:7]
	v_mfma_f32_16x16x32_bf16 v[0:3], v[176:179], v[208:211], v[0:3]
	v_mfma_f32_16x16x32_bf16 v[52:55], v[172:175], v[188:191], v[52:55]
	v_mfma_f32_16x16x32_bf16 v[48:51], v[180:183], v[188:191], v[48:51]
	v_mfma_f32_16x16x32_bf16 v[36:39], v[172:175], v[196:199], v[36:39]
	v_mfma_f32_16x16x32_bf16 v[32:35], v[180:183], v[196:199], v[32:35]
	v_mfma_f32_16x16x32_bf16 v[20:23], v[172:175], v[204:207], v[20:23]
	v_mfma_f32_16x16x32_bf16 v[16:19], v[180:183], v[204:207], v[16:19]
	v_mfma_f32_16x16x32_bf16 v[4:7], v[172:175], v[212:215], v[4:7]
	v_mfma_f32_16x16x32_bf16 v[0:3], v[180:183], v[212:215], v[0:3]
	s_setprio 0
	s_barrier
	s_add_i32 s76, 0, 0x18000
	v_add_u32_e32 v155, s76, v149
	s_add_i32 s77, 0, 0x1c000
	ds_read_b128 v[144:147], v155
	ds_read_b128 v[156:159], v155 offset:1024
	ds_read_b128 v[160:163], v155 offset:2048
	ds_read_b128 v[164:167], v155 offset:3072
	v_add_u32_e32 v155, s77, v149
	ds_read_b128 v[168:171], v155
	ds_read_b128 v[172:175], v155 offset:1024
	ds_read_b128 v[176:179], v155 offset:2048
	ds_read_b128 v[180:183], v155 offset:3072
	s_add_u32 s52, s52, 0x80000
	s_addc_u32 s53, s53, 0
	s_mov_b32 m0, s59
	v_lshl_add_u64 v[224:225], s[52:53], 0, v[128:129]
	ds_read_b128 v[184:187], v153 offset:32768
	ds_read_b128 v[188:191], v153 offset:33792
	ds_read_b128 v[192:195], v153 offset:34816
	ds_read_b128 v[196:199], v153 offset:35840
	ds_read_b128 v[200:203], v153 offset:36864
	ds_read_b128 v[204:207], v153 offset:37888
	ds_read_b128 v[208:211], v153 offset:38912
	ds_read_b128 v[212:215], v153 offset:39936
	global_load_lds_dwordx4 v[224:225], off
	v_lshl_add_u64 v[224:225], s[52:53], 0, v[132:133]
	s_mov_b32 m0, s60
	s_nop 0
	global_load_lds_dwordx4 v[224:225], off
	s_waitcnt vmcnt(8)
	s_waitcnt lgkmcnt(0)
	s_barrier
	s_setprio 1
	s_waitcnt lgkmcnt(0)
	v_mfma_f32_16x16x32_bf16 v[124:127], v[144:147], v[184:187], v[124:127]
	v_mfma_f32_16x16x32_bf16 v[120:123], v[160:163], v[184:187], v[120:123]
	v_mfma_f32_16x16x32_bf16 v[108:111], v[144:147], v[192:195], v[108:111]
	v_mfma_f32_16x16x32_bf16 v[104:107], v[160:163], v[192:195], v[104:107]
	v_mfma_f32_16x16x32_bf16 v[92:95], v[144:147], v[200:203], v[92:95]
	v_mfma_f32_16x16x32_bf16 v[88:91], v[160:163], v[200:203], v[88:91]
	v_mfma_f32_16x16x32_bf16 v[76:79], v[144:147], v[208:211], v[76:79]
	v_mfma_f32_16x16x32_bf16 v[72:75], v[160:163], v[208:211], v[72:75]
	v_mfma_f32_16x16x32_bf16 v[124:127], v[156:159], v[188:191], v[124:127]
	v_mfma_f32_16x16x32_bf16 v[120:123], v[164:167], v[188:191], v[120:123]
	v_mfma_f32_16x16x32_bf16 v[108:111], v[156:159], v[196:199], v[108:111]
	v_mfma_f32_16x16x32_bf16 v[104:107], v[164:167], v[196:199], v[104:107]
	v_mfma_f32_16x16x32_bf16 v[92:95], v[156:159], v[204:207], v[92:95]
	v_mfma_f32_16x16x32_bf16 v[88:91], v[164:167], v[204:207], v[88:91]
	v_mfma_f32_16x16x32_bf16 v[76:79], v[156:159], v[212:215], v[76:79]
	v_mfma_f32_16x16x32_bf16 v[72:75], v[164:167], v[212:215], v[72:75]
	s_setprio 0
	s_setprio 1
	v_mfma_f32_16x16x32_bf16 v[116:119], v[168:171], v[184:187], v[116:119]
	v_mfma_f32_16x16x32_bf16 v[112:115], v[176:179], v[184:187], v[112:115]
	v_mfma_f32_16x16x32_bf16 v[100:103], v[168:171], v[192:195], v[100:103]
	v_mfma_f32_16x16x32_bf16 v[96:99], v[176:179], v[192:195], v[96:99]
	v_mfma_f32_16x16x32_bf16 v[84:87], v[168:171], v[200:203], v[84:87]
	v_mfma_f32_16x16x32_bf16 v[80:83], v[176:179], v[200:203], v[80:83]
	v_mfma_f32_16x16x32_bf16 v[68:71], v[168:171], v[208:211], v[68:71]
	v_mfma_f32_16x16x32_bf16 v[64:67], v[176:179], v[208:211], v[64:67]
	v_mfma_f32_16x16x32_bf16 v[116:119], v[172:175], v[188:191], v[116:119]
	v_mfma_f32_16x16x32_bf16 v[112:115], v[180:183], v[188:191], v[112:115]
	v_mfma_f32_16x16x32_bf16 v[100:103], v[172:175], v[196:199], v[100:103]
	v_mfma_f32_16x16x32_bf16 v[96:99], v[180:183], v[196:199], v[96:99]
	v_mfma_f32_16x16x32_bf16 v[84:87], v[172:175], v[204:207], v[84:87]
	v_mfma_f32_16x16x32_bf16 v[80:83], v[180:183], v[204:207], v[80:83]
	v_mfma_f32_16x16x32_bf16 v[68:71], v[172:175], v[212:215], v[68:71]
	v_mfma_f32_16x16x32_bf16 v[64:67], v[180:183], v[212:215], v[64:67]
	s_setprio 0
	s_barrier
	s_add_i32 s52, s76, s56
	v_lshl_add_u64 v[216:217], v[216:217], 0, s[22:23]
	s_mov_b32 m0, s52
	ds_read_b128 v[184:187], v153 offset:49152
	ds_read_b128 v[188:191], v153 offset:50176
	ds_read_b128 v[192:195], v153 offset:51200
	ds_read_b128 v[196:199], v153 offset:52224
	ds_read_b128 v[200:203], v153 offset:53248
	ds_read_b128 v[204:207], v153 offset:54272
	ds_read_b128 v[208:211], v153 offset:55296
	ds_read_b128 v[212:215], v153 offset:56320
	global_load_lds_dwordx4 v[216:217], off
	s_add_i32 m0, s52, 0x2000
	s_add_u32 s50, s50, 0x80080
	v_lshl_add_u64 v[216:217], v[218:219], 0, s[22:23]
	s_addc_u32 s51, s51, 0
	s_add_i32 s52, s77, s56
	global_load_lds_dwordx4 v[216:217], off
	v_lshl_add_u64 v[216:217], s[50:51], 0, v[130:131]
	s_mov_b32 m0, s52
	s_nop 0
	global_load_lds_dwordx4 v[216:217], off
	v_lshl_add_u64 v[216:217], s[50:51], 0, v[134:135]
	s_add_i32 m0, s52, 0x2000
	s_nop 0
	global_load_lds_dwordx4 v[216:217], off
	s_waitcnt vmcnt(6)
	s_waitcnt lgkmcnt(0)
	s_barrier
	v_lshl_add_u64 v[216:217], v[220:221], 0, s[22:23]
	s_mov_b32 m0, s62
	s_nop 0
	global_load_lds_dwordx4 v[216:217], off
	v_lshl_add_u64 v[216:217], v[222:223], 0, s[22:23]
	s_mov_b32 m0, s63
	s_nop 0
	global_load_lds_dwordx4 v[216:217], off
	s_setprio 1
	s_waitcnt lgkmcnt(0)
	v_mfma_f32_16x16x32_bf16 v[60:63], v[144:147], v[184:187], v[60:63]
	v_mfma_f32_16x16x32_bf16 v[56:59], v[160:163], v[184:187], v[56:59]
	v_mfma_f32_16x16x32_bf16 v[44:47], v[144:147], v[192:195], v[44:47]
	v_mfma_f32_16x16x32_bf16 v[40:43], v[160:163], v[192:195], v[40:43]
	v_mfma_f32_16x16x32_bf16 v[28:31], v[144:147], v[200:203], v[28:31]
	v_mfma_f32_16x16x32_bf16 v[24:27], v[160:163], v[200:203], v[24:27]
	v_mfma_f32_16x16x32_bf16 v[12:15], v[144:147], v[208:211], v[12:15]
	v_mfma_f32_16x16x32_bf16 v[8:11], v[160:163], v[208:211], v[8:11]
	v_mfma_f32_16x16x32_bf16 v[60:63], v[156:159], v[188:191], v[60:63]
	v_mfma_f32_16x16x32_bf16 v[56:59], v[164:167], v[188:191], v[56:59]
	v_mfma_f32_16x16x32_bf16 v[44:47], v[156:159], v[196:199], v[44:47]
	v_mfma_f32_16x16x32_bf16 v[40:43], v[164:167], v[196:199], v[40:43]
	v_mfma_f32_16x16x32_bf16 v[28:31], v[156:159], v[204:207], v[28:31]
	v_mfma_f32_16x16x32_bf16 v[24:27], v[164:167], v[204:207], v[24:27]
	v_mfma_f32_16x16x32_bf16 v[12:15], v[156:159], v[212:215], v[12:15]
	v_mfma_f32_16x16x32_bf16 v[8:11], v[164:167], v[212:215], v[8:11]
	s_setprio 0
	s_setprio 1
	v_mfma_f32_16x16x32_bf16 v[52:55], v[168:171], v[184:187], v[52:55]
	v_mfma_f32_16x16x32_bf16 v[48:51], v[176:179], v[184:187], v[48:51]
	v_mfma_f32_16x16x32_bf16 v[36:39], v[168:171], v[192:195], v[36:39]
	v_mfma_f32_16x16x32_bf16 v[32:35], v[176:179], v[192:195], v[32:35]
	v_mfma_f32_16x16x32_bf16 v[20:23], v[168:171], v[200:203], v[20:23]
	v_mfma_f32_16x16x32_bf16 v[16:19], v[176:179], v[200:203], v[16:19]
	v_mfma_f32_16x16x32_bf16 v[4:7], v[168:171], v[208:211], v[4:7]
	v_mfma_f32_16x16x32_bf16 v[0:3], v[176:179], v[208:211], v[0:3]
	v_mfma_f32_16x16x32_bf16 v[52:55], v[172:175], v[188:191], v[52:55]
	v_mfma_f32_16x16x32_bf16 v[48:51], v[180:183], v[188:191], v[48:51]
	v_mfma_f32_16x16x32_bf16 v[36:39], v[172:175], v[196:199], v[36:39]
	v_mfma_f32_16x16x32_bf16 v[32:35], v[180:183], v[196:199], v[32:35]
	v_mfma_f32_16x16x32_bf16 v[20:23], v[172:175], v[204:207], v[20:23]
	v_mfma_f32_16x16x32_bf16 v[16:19], v[180:183], v[204:207], v[16:19]
	v_mfma_f32_16x16x32_bf16 v[4:7], v[172:175], v[212:215], v[4:7]
	v_mfma_f32_16x16x32_bf16 v[0:3], v[180:183], v[212:215], v[0:3]
	s_setprio 0
	s_barrier
	s_add_i32 s75, s75, 2
	s_add_u32 s72, s72, 0x100
	s_addc_u32 s74, s74, 0
	s_add_u32 s48, s48, 0x100
	s_addc_u32 s49, s49, 0
	s_cmp_gt_u32 s75, 29
	s_cbranch_scc0 .LBB0_337
	s_and_b64 vcc, exec, s[24:25]
	s_cbranch_vccz .LBB0_340
	s_barrier

.LBB0_435:
	ds_read_b128 v[148:151], v222
	ds_read_b128 v[152:155], v222 offset:1024
	ds_read_b128 v[156:159], v222 offset:2048
	ds_read_b128 v[160:163], v222 offset:3072
	ds_read_b128 v[132:135], v223
	ds_read_b128 v[136:139], v223 offset:1024
	ds_read_b128 v[140:143], v223 offset:2048
	ds_read_b128 v[144:147], v223 offset:3072
	s_add_u32 s10, s54, 0xfff80080
	s_addc_u32 s11, s55, -1
	s_cmp_eq_u32 s84, 28
	s_cselect_b32 s59, s25, s11
	s_cselect_b32 s58, s46, s10
	s_cselect_b32 s57, s23, s83
	s_cselect_b32 s56, s47, s82
	v_lshl_add_u64 v[2:3], s[54:55], 0, v[208:209]
	s_add_i32 m0, s37, 0xc000
	s_waitcnt lgkmcnt(0)
	ds_read_b128 v[164:167], v224
	ds_read_b128 v[168:171], v224 offset:1024
	ds_read_b128 v[172:175], v224 offset:2048
	ds_read_b128 v[176:179], v224 offset:3072
	ds_read_b128 v[180:183], v224 offset:4096
	ds_read_b128 v[184:187], v224 offset:5120
	ds_read_b128 v[188:191], v224 offset:6144
	ds_read_b128 v[192:195], v224 offset:7168
	global_load_lds_dwordx4 v[2:3], off
	v_lshl_add_u64 v[2:3], s[54:55], 0, v[206:207]
	s_add_i32 m0, s37, 0xe000
	s_nop 0
	global_load_lds_dwordx4 v[2:3], off
	s_waitcnt vmcnt(8)
	s_waitcnt lgkmcnt(0)
	s_barrier
	s_setprio 1
	s_waitcnt lgkmcnt(0)
	v_mfma_f32_16x16x32_bf16 v[120:123], v[148:151], v[164:167], v[120:123]
	v_mfma_f32_16x16x32_bf16 v[116:119], v[156:159], v[164:167], v[116:119]
	v_mfma_f32_16x16x32_bf16 v[104:107], v[148:151], v[172:175], v[104:107]
	v_mfma_f32_16x16x32_bf16 v[100:103], v[156:159], v[172:175], v[100:103]
	v_mfma_f32_16x16x32_bf16 v[88:91], v[148:151], v[180:183], v[88:91]
	v_mfma_f32_16x16x32_bf16 v[84:87], v[156:159], v[180:183], v[84:87]
	v_mfma_f32_16x16x32_bf16 v[76:79], v[148:151], v[188:191], v[76:79]
	v_mfma_f32_16x16x32_bf16 v[72:75], v[156:159], v[188:191], v[72:75]
	v_mfma_f32_16x16x32_bf16 v[120:123], v[152:155], v[168:171], v[120:123]
	v_mfma_f32_16x16x32_bf16 v[116:119], v[160:163], v[168:171], v[116:119]
	v_mfma_f32_16x16x32_bf16 v[104:107], v[152:155], v[176:179], v[104:107]
	v_mfma_f32_16x16x32_bf16 v[100:103], v[160:163], v[176:179], v[100:103]
	v_mfma_f32_16x16x32_bf16 v[88:91], v[152:155], v[184:187], v[88:91]
	v_mfma_f32_16x16x32_bf16 v[84:87], v[160:163], v[184:187], v[84:87]
	v_mfma_f32_16x16x32_bf16 v[76:79], v[152:155], v[192:195], v[76:79]
	v_mfma_f32_16x16x32_bf16 v[72:75], v[160:163], v[192:195], v[72:75]
	s_setprio 0
	s_setprio 1
	v_mfma_f32_16x16x32_bf16 v[128:131], v[132:135], v[164:167], v[128:131]
	v_mfma_f32_16x16x32_bf16 v[124:127], v[140:143], v[164:167], v[124:127]
	v_mfma_f32_16x16x32_bf16 v[112:115], v[132:135], v[172:175], v[112:115]
	v_mfma_f32_16x16x32_bf16 v[108:111], v[140:143], v[172:175], v[108:111]
	v_mfma_f32_16x16x32_bf16 v[96:99], v[132:135], v[180:183], v[96:99]
	v_mfma_f32_16x16x32_bf16 v[92:95], v[140:143], v[180:183], v[92:95]
	v_mfma_f32_16x16x32_bf16 v[80:83], v[132:135], v[188:191], v[80:83]
	v_mfma_f32_16x16x32_bf16 v[68:71], v[140:143], v[188:191], v[68:71]
	v_mfma_f32_16x16x32_bf16 v[128:131], v[136:139], v[168:171], v[128:131]
	v_mfma_f32_16x16x32_bf16 v[124:127], v[144:147], v[168:171], v[124:127]
	v_mfma_f32_16x16x32_bf16 v[112:115], v[136:139], v[176:179], v[112:115]
	v_mfma_f32_16x16x32_bf16 v[108:111], v[144:147], v[176:179], v[108:111]
	v_mfma_f32_16x16x32_bf16 v[96:99], v[136:139], v[184:187], v[96:99]
	v_mfma_f32_16x16x32_bf16 v[92:95], v[144:147], v[184:187], v[92:95]
	v_mfma_f32_16x16x32_bf16 v[80:83], v[136:139], v[192:195], v[80:83]
	v_mfma_f32_16x16x32_bf16 v[68:71], v[144:147], v[192:195], v[68:71]
	s_setprio 0
	s_barrier
	s_add_i32 s10, s67, s48
	v_lshl_add_u64 v[2:3], s[56:57], 0, v[198:199]
	s_mov_b32 m0, s10
	ds_read_b128 v[188:191], v224 offset:16384
	ds_read_b128 v[192:195], v224 offset:17408
	ds_read_b128 v[180:183], v224 offset:18432
	ds_read_b128 v[184:187], v224 offset:19456
	ds_read_b128 v[172:175], v224 offset:20480
	ds_read_b128 v[176:179], v224 offset:21504
	ds_read_b128 v[164:167], v224 offset:22528
	ds_read_b128 v[168:171], v224 offset:23552
	global_load_lds_dwordx4 v[2:3], off
	s_add_i32 m0, s10, 0x2000
	s_add_u32 s10, s56, 0x80000
	v_lshl_add_u64 v[212:213], s[56:57], 0, v[202:203]
	s_addc_u32 s11, s57, 0
	s_add_i32 s78, s70, s48
	global_load_lds_dwordx4 v[212:213], off
	v_lshl_add_u64 v[214:215], s[10:11], 0, v[198:199]
	s_mov_b32 m0, s78
	v_lshl_add_u64 v[216:217], s[58:59], 0, v[200:201]
	global_load_lds_dwordx4 v[214:215], off
	v_lshl_add_u64 v[214:215], s[10:11], 0, v[202:203]
	s_add_i32 m0, s78, 0x2000
	v_cmp_ne_u32_e64 s[10:11], 1, v227
	global_load_lds_dwordx4 v[214:215], off
	s_andn2_b64 vcc, exec, s[52:53]
	s_waitcnt vmcnt(6)
	s_waitcnt lgkmcnt(0)
	s_barrier
	v_lshl_add_u64 v[214:215], s[58:59], 0, v[196:197]
	s_mov_b32 m0, s37
	s_nop 0
	global_load_lds_dwordx4 v[214:215], off
	s_mov_b32 m0, s60
	s_nop 0
	global_load_lds_dwordx4 v[216:217], off
	s_cbranch_vccnz .LBB0_437
	s_setprio 1
	s_waitcnt lgkmcnt(0)
	v_mfma_f32_16x16x32_bf16 v[56:59], v[148:151], v[188:191], v[56:59]
	v_mfma_f32_16x16x32_bf16 v[52:55], v[156:159], v[188:191], v[52:55]
	v_mfma_f32_16x16x32_bf16 v[40:43], v[148:151], v[180:183], v[40:43]
	v_mfma_f32_16x16x32_bf16 v[36:39], v[156:159], v[180:183], v[36:39]
	v_mfma_f32_16x16x32_bf16 v[24:27], v[148:151], v[172:175], v[24:27]
	v_mfma_f32_16x16x32_bf16 v[20:23], v[156:159], v[172:175], v[20:23]
	v_mfma_f32_16x16x32_bf16 v[8:11], v[148:151], v[164:167], v[8:11]
	v_mfma_f32_16x16x32_bf16 v[4:7], v[156:159], v[164:167], v[4:7]
	v_mfma_f32_16x16x32_bf16 v[56:59], v[152:155], v[192:195], v[56:59]
	v_mfma_f32_16x16x32_bf16 v[52:55], v[160:163], v[192:195], v[52:55]
	v_mfma_f32_16x16x32_bf16 v[40:43], v[152:155], v[184:187], v[40:43]
	v_mfma_f32_16x16x32_bf16 v[36:39], v[160:163], v[184:187], v[36:39]
	v_mfma_f32_16x16x32_bf16 v[24:27], v[152:155], v[176:179], v[24:27]
	v_mfma_f32_16x16x32_bf16 v[20:23], v[160:163], v[176:179], v[20:23]
	v_mfma_f32_16x16x32_bf16 v[8:11], v[152:155], v[168:171], v[8:11]
	v_mfma_f32_16x16x32_bf16 v[4:7], v[160:163], v[168:171], v[4:7]
	s_setprio 0
	s_setprio 1
	v_mfma_f32_16x16x32_bf16 v[64:67], v[132:135], v[188:191], v[64:67]
	v_mfma_f32_16x16x32_bf16 v[60:63], v[140:143], v[188:191], v[60:63]
	v_mfma_f32_16x16x32_bf16 v[48:51], v[132:135], v[180:183], v[48:51]
	v_mfma_f32_16x16x32_bf16 v[44:47], v[140:143], v[180:183], v[44:47]
	v_mfma_f32_16x16x32_bf16 v[32:35], v[132:135], v[172:175], v[32:35]
	v_mfma_f32_16x16x32_bf16 v[28:31], v[140:143], v[172:175], v[28:31]
	v_mfma_f32_16x16x32_bf16 v[16:19], v[132:135], v[164:167], v[16:19]
	v_mfma_f32_16x16x32_bf16 v[12:15], v[140:143], v[164:167], v[12:15]
	v_mfma_f32_16x16x32_bf16 v[64:67], v[136:139], v[192:195], v[64:67]
	v_mfma_f32_16x16x32_bf16 v[60:63], v[144:147], v[192:195], v[60:63]
	v_mfma_f32_16x16x32_bf16 v[48:51], v[136:139], v[184:187], v[48:51]
	v_mfma_f32_16x16x32_bf16 v[44:47], v[144:147], v[184:187], v[44:47]
	v_mfma_f32_16x16x32_bf16 v[32:35], v[136:139], v[176:179], v[32:35]
	v_mfma_f32_16x16x32_bf16 v[28:31], v[144:147], v[176:179], v[28:31]
	v_mfma_f32_16x16x32_bf16 v[16:19], v[136:139], v[168:171], v[16:19]
	v_mfma_f32_16x16x32_bf16 v[12:15], v[144:147], v[168:171], v[12:15]
	s_setprio 0
.LBB0_437:
	s_barrier
	s_add_i32 s78, 0, 0x18000
	v_add_u32_e32 v1, s78, v220
	s_add_i32 s79, 0, 0x1c000
	ds_read_b128 v[148:151], v1
	ds_read_b128 v[152:155], v1 offset:1024
	ds_read_b128 v[156:159], v1 offset:2048
	ds_read_b128 v[160:163], v1 offset:3072
	v_add_u32_e32 v1, s79, v220
	ds_read_b128 v[132:135], v1
	ds_read_b128 v[136:139], v1 offset:1024
	ds_read_b128 v[140:143], v1 offset:2048
	ds_read_b128 v[144:147], v1 offset:3072
	s_add_u32 s58, s58, 0x80000
	s_addc_u32 s59, s59, 0
	s_mov_b32 m0, s61
	v_lshl_add_u64 v[228:229], s[58:59], 0, v[196:197]
	s_waitcnt lgkmcnt(0)
	ds_read_b128 v[164:167], v224 offset:32768
	ds_read_b128 v[168:171], v224 offset:33792
	ds_read_b128 v[172:175], v224 offset:34816
	ds_read_b128 v[176:179], v224 offset:35840
	ds_read_b128 v[180:183], v224 offset:36864
	ds_read_b128 v[184:187], v224 offset:37888
	ds_read_b128 v[188:191], v224 offset:38912
	ds_read_b128 v[192:195], v224 offset:39936
	global_load_lds_dwordx4 v[228:229], off
	v_lshl_add_u64 v[228:229], s[58:59], 0, v[200:201]
	s_mov_b32 m0, s62
	s_nop 0
	global_load_lds_dwordx4 v[228:229], off
	s_waitcnt vmcnt(8)
	s_waitcnt lgkmcnt(0)
	s_barrier
	s_setprio 1
	s_waitcnt lgkmcnt(0)
	v_mfma_f32_16x16x32_bf16 v[120:123], v[148:151], v[164:167], v[120:123]
	v_mfma_f32_16x16x32_bf16 v[116:119], v[156:159], v[164:167], v[116:119]
	v_mfma_f32_16x16x32_bf16 v[104:107], v[148:151], v[172:175], v[104:107]
	v_mfma_f32_16x16x32_bf16 v[100:103], v[156:159], v[172:175], v[100:103]
	v_mfma_f32_16x16x32_bf16 v[88:91], v[148:151], v[180:183], v[88:91]
	v_mfma_f32_16x16x32_bf16 v[84:87], v[156:159], v[180:183], v[84:87]
	v_mfma_f32_16x16x32_bf16 v[76:79], v[148:151], v[188:191], v[76:79]
	v_mfma_f32_16x16x32_bf16 v[72:75], v[156:159], v[188:191], v[72:75]
	v_mfma_f32_16x16x32_bf16 v[120:123], v[152:155], v[168:171], v[120:123]
	v_mfma_f32_16x16x32_bf16 v[116:119], v[160:163], v[168:171], v[116:119]
	v_mfma_f32_16x16x32_bf16 v[104:107], v[152:155], v[176:179], v[104:107]
	v_mfma_f32_16x16x32_bf16 v[100:103], v[160:163], v[176:179], v[100:103]
	v_mfma_f32_16x16x32_bf16 v[88:91], v[152:155], v[184:187], v[88:91]
	v_mfma_f32_16x16x32_bf16 v[84:87], v[160:163], v[184:187], v[84:87]
	v_mfma_f32_16x16x32_bf16 v[76:79], v[152:155], v[192:195], v[76:79]
	v_mfma_f32_16x16x32_bf16 v[72:75], v[160:163], v[192:195], v[72:75]
	s_setprio 0
	s_setprio 1
	v_mfma_f32_16x16x32_bf16 v[128:131], v[132:135], v[164:167], v[128:131]
	v_mfma_f32_16x16x32_bf16 v[124:127], v[140:143], v[164:167], v[124:127]
	v_mfma_f32_16x16x32_bf16 v[112:115], v[132:135], v[172:175], v[112:115]
	v_mfma_f32_16x16x32_bf16 v[108:111], v[140:143], v[172:175], v[108:111]
	v_mfma_f32_16x16x32_bf16 v[96:99], v[132:135], v[180:183], v[96:99]
	v_mfma_f32_16x16x32_bf16 v[92:95], v[140:143], v[180:183], v[92:95]
	v_mfma_f32_16x16x32_bf16 v[80:83], v[132:135], v[188:191], v[80:83]
	v_mfma_f32_16x16x32_bf16 v[68:71], v[140:143], v[188:191], v[68:71]
	v_mfma_f32_16x16x32_bf16 v[128:131], v[136:139], v[168:171], v[128:131]
	v_mfma_f32_16x16x32_bf16 v[124:127], v[144:147], v[168:171], v[124:127]
	v_mfma_f32_16x16x32_bf16 v[112:115], v[136:139], v[176:179], v[112:115]
	v_mfma_f32_16x16x32_bf16 v[108:111], v[144:147], v[176:179], v[108:111]
	v_mfma_f32_16x16x32_bf16 v[96:99], v[136:139], v[184:187], v[96:99]
	v_mfma_f32_16x16x32_bf16 v[92:95], v[144:147], v[184:187], v[92:95]
	v_mfma_f32_16x16x32_bf16 v[80:83], v[136:139], v[192:195], v[80:83]
	v_mfma_f32_16x16x32_bf16 v[68:71], v[144:147], v[192:195], v[68:71]
	s_setprio 0
	s_barrier
	s_add_i32 s58, s78, s48
	v_lshl_add_u64 v[2:3], v[2:3], 0, s[16:17]
	s_mov_b32 m0, s58
	ds_read_b128 v[188:191], v224 offset:49152
	ds_read_b128 v[192:195], v224 offset:50176
	ds_read_b128 v[180:183], v224 offset:51200
	ds_read_b128 v[184:187], v224 offset:52224
	ds_read_b128 v[172:175], v224 offset:53248
	ds_read_b128 v[176:179], v224 offset:54272
	ds_read_b128 v[164:167], v224 offset:55296
	ds_read_b128 v[168:171], v224 offset:56320
	global_load_lds_dwordx4 v[2:3], off
	s_add_i32 m0, s58, 0x2000
	s_add_u32 s56, s56, 0x80080
	v_lshl_add_u64 v[2:3], v[212:213], 0, s[16:17]
	s_addc_u32 s57, s57, 0
	s_add_i32 s58, s79, s48
	global_load_lds_dwordx4 v[2:3], off
	v_lshl_add_u64 v[2:3], s[56:57], 0, v[198:199]
	s_mov_b32 m0, s58
	s_and_b64 vcc, exec, s[10:11]
	global_load_lds_dwordx4 v[2:3], off
	v_lshl_add_u64 v[2:3], s[56:57], 0, v[202:203]
	s_add_i32 m0, s58, 0x2000
	s_nop 0
	global_load_lds_dwordx4 v[2:3], off
	s_waitcnt vmcnt(6)
	s_waitcnt lgkmcnt(0)
	s_barrier
	v_lshl_add_u64 v[2:3], v[214:215], 0, s[16:17]
	s_mov_b32 m0, s63
	s_nop 0
	global_load_lds_dwordx4 v[2:3], off
	v_lshl_add_u64 v[2:3], v[216:217], 0, s[16:17]
	s_mov_b32 m0, s64
	s_nop 0
	global_load_lds_dwordx4 v[2:3], off
	s_cbranch_vccnz .LBB0_434
	s_setprio 1
	s_waitcnt lgkmcnt(0)
	v_mfma_f32_16x16x32_bf16 v[56:59], v[148:151], v[188:191], v[56:59]
	v_mfma_f32_16x16x32_bf16 v[52:55], v[156:159], v[188:191], v[52:55]
	v_mfma_f32_16x16x32_bf16 v[40:43], v[148:151], v[180:183], v[40:43]
	v_mfma_f32_16x16x32_bf16 v[36:39], v[156:159], v[180:183], v[36:39]
	v_mfma_f32_16x16x32_bf16 v[24:27], v[148:151], v[172:175], v[24:27]
	v_mfma_f32_16x16x32_bf16 v[20:23], v[156:159], v[172:175], v[20:23]
	v_mfma_f32_16x16x32_bf16 v[8:11], v[148:151], v[164:167], v[8:11]
	v_mfma_f32_16x16x32_bf16 v[2:5], v[156:159], v[164:167], v[4:7]
	v_mfma_f32_16x16x32_bf16 v[56:59], v[152:155], v[192:195], v[56:59]
	v_mfma_f32_16x16x32_bf16 v[52:55], v[160:163], v[192:195], v[52:55]
	v_mfma_f32_16x16x32_bf16 v[40:43], v[152:155], v[184:187], v[40:43]
	v_mfma_f32_16x16x32_bf16 v[36:39], v[160:163], v[184:187], v[36:39]
	v_mfma_f32_16x16x32_bf16 v[24:27], v[152:155], v[176:179], v[24:27]
	v_mfma_f32_16x16x32_bf16 v[20:23], v[160:163], v[176:179], v[20:23]
	v_mfma_f32_16x16x32_bf16 v[8:11], v[152:155], v[168:171], v[8:11]
	v_mfma_f32_16x16x32_bf16 v[4:7], v[160:163], v[168:171], v[2:5]
	s_setprio 0
	s_setprio 1
	v_mfma_f32_16x16x32_bf16 v[64:67], v[132:135], v[188:191], v[64:67]
	v_mfma_f32_16x16x32_bf16 v[60:63], v[140:143], v[188:191], v[60:63]
	v_mfma_f32_16x16x32_bf16 v[48:51], v[132:135], v[180:183], v[48:51]
	v_mfma_f32_16x16x32_bf16 v[44:47], v[140:143], v[180:183], v[44:47]
	v_mfma_f32_16x16x32_bf16 v[32:35], v[132:135], v[172:175], v[32:35]
	v_mfma_f32_16x16x32_bf16 v[28:31], v[140:143], v[172:175], v[28:31]
	v_mfma_f32_16x16x32_bf16 v[16:19], v[132:135], v[164:167], v[16:19]
	v_mfma_f32_16x16x32_bf16 v[12:15], v[140:143], v[164:167], v[12:15]
	v_mfma_f32_16x16x32_bf16 v[64:67], v[136:139], v[192:195], v[64:67]
	v_mfma_f32_16x16x32_bf16 v[60:63], v[144:147], v[192:195], v[60:63]
	v_mfma_f32_16x16x32_bf16 v[48:51], v[136:139], v[184:187], v[48:51]
	v_mfma_f32_16x16x32_bf16 v[44:47], v[144:147], v[184:187], v[44:47]
	v_mfma_f32_16x16x32_bf16 v[32:35], v[136:139], v[176:179], v[32:35]
	v_mfma_f32_16x16x32_bf16 v[28:31], v[144:147], v[176:179], v[28:31]
	v_mfma_f32_16x16x32_bf16 v[16:19], v[136:139], v[168:171], v[16:19]
	v_mfma_f32_16x16x32_bf16 v[12:15], v[144:147], v[168:171], v[12:15]
	s_setprio 0
	s_branch .LBB0_434

.LBB0_523:
	ds_read_b128 v[144:147], v151
	ds_read_b128 v[156:159], v151 offset:1024
	ds_read_b128 v[160:163], v151 offset:2048
	ds_read_b128 v[164:167], v151 offset:3072
	ds_read_b128 v[168:171], v152
	ds_read_b128 v[172:175], v152 offset:1024
	ds_read_b128 v[176:179], v152 offset:2048
	ds_read_b128 v[180:183], v152 offset:3072
	s_add_u32 s36, s34, 0x100
	s_addc_u32 s37, s35, 0
	s_cmpk_eq_i32 s66, 0x54
	s_cselect_b32 s55, s13, s37
	s_cselect_b32 s54, s12, s36
	s_cselect_b32 s53, s31, s47
	s_cselect_b32 s52, s30, s46
	v_lshl_add_u64 v[216:217], s[34:35], 0, v[138:139]
	s_add_i32 m0, s49, 0xc000
	ds_read_b128 v[184:187], v153
	ds_read_b128 v[188:191], v153 offset:1024
	ds_read_b128 v[192:195], v153 offset:2048
	ds_read_b128 v[196:199], v153 offset:3072
	ds_read_b128 v[200:203], v153 offset:4096
	ds_read_b128 v[204:207], v153 offset:5120
	ds_read_b128 v[208:211], v153 offset:6144
	ds_read_b128 v[212:215], v153 offset:7168
	global_load_lds_dwordx4 v[216:217], off
	v_lshl_add_u64 v[216:217], s[34:35], 0, v[136:137]
	s_add_i32 m0, s49, 0xe000
	s_nop 0
	global_load_lds_dwordx4 v[216:217], off
	s_waitcnt vmcnt(8)
	s_waitcnt lgkmcnt(0)
	s_barrier
	s_setprio 1
	s_waitcnt lgkmcnt(0)
	v_mfma_f32_16x16x32_bf16 v[124:127], v[144:147], v[184:187], v[124:127]
	v_mfma_f32_16x16x32_bf16 v[120:123], v[160:163], v[184:187], v[120:123]
	v_mfma_f32_16x16x32_bf16 v[108:111], v[144:147], v[192:195], v[108:111]
	v_mfma_f32_16x16x32_bf16 v[104:107], v[160:163], v[192:195], v[104:107]
	v_mfma_f32_16x16x32_bf16 v[92:95], v[144:147], v[200:203], v[92:95]
	v_mfma_f32_16x16x32_bf16 v[88:91], v[160:163], v[200:203], v[88:91]
	v_mfma_f32_16x16x32_bf16 v[76:79], v[144:147], v[208:211], v[76:79]
	v_mfma_f32_16x16x32_bf16 v[72:75], v[160:163], v[208:211], v[72:75]
	v_mfma_f32_16x16x32_bf16 v[124:127], v[156:159], v[188:191], v[124:127]
	v_mfma_f32_16x16x32_bf16 v[120:123], v[164:167], v[188:191], v[120:123]
	v_mfma_f32_16x16x32_bf16 v[108:111], v[156:159], v[196:199], v[108:111]
	v_mfma_f32_16x16x32_bf16 v[104:107], v[164:167], v[196:199], v[104:107]
	v_mfma_f32_16x16x32_bf16 v[92:95], v[156:159], v[204:207], v[92:95]
	v_mfma_f32_16x16x32_bf16 v[88:91], v[164:167], v[204:207], v[88:91]
	v_mfma_f32_16x16x32_bf16 v[76:79], v[156:159], v[212:215], v[76:79]
	v_mfma_f32_16x16x32_bf16 v[72:75], v[164:167], v[212:215], v[72:75]
	s_setprio 0
	s_setprio 1
	v_mfma_f32_16x16x32_bf16 v[116:119], v[168:171], v[184:187], v[116:119]
	v_mfma_f32_16x16x32_bf16 v[112:115], v[176:179], v[184:187], v[112:115]
	v_mfma_f32_16x16x32_bf16 v[100:103], v[168:171], v[192:195], v[100:103]
	v_mfma_f32_16x16x32_bf16 v[96:99], v[176:179], v[192:195], v[96:99]
	v_mfma_f32_16x16x32_bf16 v[84:87], v[168:171], v[200:203], v[84:87]
	v_mfma_f32_16x16x32_bf16 v[80:83], v[176:179], v[200:203], v[80:83]
	v_mfma_f32_16x16x32_bf16 v[68:71], v[168:171], v[208:211], v[68:71]
	v_mfma_f32_16x16x32_bf16 v[64:67], v[176:179], v[208:211], v[64:67]
	v_mfma_f32_16x16x32_bf16 v[116:119], v[172:175], v[188:191], v[116:119]
	v_mfma_f32_16x16x32_bf16 v[112:115], v[180:183], v[188:191], v[112:115]
	v_mfma_f32_16x16x32_bf16 v[100:103], v[172:175], v[196:199], v[100:103]
	v_mfma_f32_16x16x32_bf16 v[96:99], v[180:183], v[196:199], v[96:99]
	v_mfma_f32_16x16x32_bf16 v[84:87], v[172:175], v[204:207], v[84:87]
	v_mfma_f32_16x16x32_bf16 v[80:83], v[180:183], v[204:207], v[80:83]
	v_mfma_f32_16x16x32_bf16 v[68:71], v[172:175], v[212:215], v[68:71]
	v_mfma_f32_16x16x32_bf16 v[64:67], v[180:183], v[212:215], v[64:67]
	s_setprio 0
	s_barrier
	s_add_i32 s34, s62, s48
	v_lshl_add_u64 v[216:217], s[52:53], 0, v[130:131]
	s_mov_b32 m0, s34
	ds_read_b128 v[184:187], v153 offset:16384
	ds_read_b128 v[188:191], v153 offset:17408
	ds_read_b128 v[192:195], v153 offset:18432
	ds_read_b128 v[196:199], v153 offset:19456
	ds_read_b128 v[200:203], v153 offset:20480
	ds_read_b128 v[204:207], v153 offset:21504
	ds_read_b128 v[208:211], v153 offset:22528
	ds_read_b128 v[212:215], v153 offset:23552
	global_load_lds_dwordx4 v[216:217], off
	s_add_i32 m0, s34, 0x2000
	s_add_u32 s34, s52, 0x160000
	v_lshl_add_u64 v[218:219], s[52:53], 0, v[134:135]
	s_addc_u32 s35, s53, 0
	s_add_i32 s67, s63, s48
	global_load_lds_dwordx4 v[218:219], off
	v_lshl_add_u64 v[220:221], s[34:35], 0, v[130:131]
	s_mov_b32 m0, s67
	v_lshl_add_u64 v[222:223], s[54:55], 0, v[132:133]
	global_load_lds_dwordx4 v[220:221], off
	v_lshl_add_u64 v[220:221], s[34:35], 0, v[134:135]
	s_add_i32 m0, s67, 0x2000
	s_nop 0
	global_load_lds_dwordx4 v[220:221], off
	s_waitcnt vmcnt(6)
	s_waitcnt lgkmcnt(0)
	s_barrier
	v_lshl_add_u64 v[220:221], s[54:55], 0, v[128:129]
	s_mov_b32 m0, s49
	s_nop 0
	global_load_lds_dwordx4 v[220:221], off
	s_mov_b32 m0, s56
	s_nop 0
	global_load_lds_dwordx4 v[222:223], off
	s_setprio 1
	s_waitcnt lgkmcnt(0)
	v_mfma_f32_16x16x32_bf16 v[60:63], v[144:147], v[184:187], v[60:63]
	v_mfma_f32_16x16x32_bf16 v[56:59], v[160:163], v[184:187], v[56:59]
	v_mfma_f32_16x16x32_bf16 v[44:47], v[144:147], v[192:195], v[44:47]
	v_mfma_f32_16x16x32_bf16 v[40:43], v[160:163], v[192:195], v[40:43]
	v_mfma_f32_16x16x32_bf16 v[28:31], v[144:147], v[200:203], v[28:31]
	v_mfma_f32_16x16x32_bf16 v[24:27], v[160:163], v[200:203], v[24:27]
	v_mfma_f32_16x16x32_bf16 v[12:15], v[144:147], v[208:211], v[12:15]
	v_mfma_f32_16x16x32_bf16 v[8:11], v[160:163], v[208:211], v[8:11]
	v_mfma_f32_16x16x32_bf16 v[60:63], v[156:159], v[188:191], v[60:63]
	v_mfma_f32_16x16x32_bf16 v[56:59], v[164:167], v[188:191], v[56:59]
	v_mfma_f32_16x16x32_bf16 v[44:47], v[156:159], v[196:199], v[44:47]
	v_mfma_f32_16x16x32_bf16 v[40:43], v[164:167], v[196:199], v[40:43]
	v_mfma_f32_16x16x32_bf16 v[28:31], v[156:159], v[204:207], v[28:31]
	v_mfma_f32_16x16x32_bf16 v[24:27], v[164:167], v[204:207], v[24:27]
	v_mfma_f32_16x16x32_bf16 v[12:15], v[156:159], v[212:215], v[12:15]
	v_mfma_f32_16x16x32_bf16 v[8:11], v[164:167], v[212:215], v[8:11]
	s_setprio 0
	s_setprio 1
	v_mfma_f32_16x16x32_bf16 v[52:55], v[168:171], v[184:187], v[52:55]
	v_mfma_f32_16x16x32_bf16 v[48:51], v[176:179], v[184:187], v[48:51]
	v_mfma_f32_16x16x32_bf16 v[36:39], v[168:171], v[192:195], v[36:39]
	v_mfma_f32_16x16x32_bf16 v[32:35], v[176:179], v[192:195], v[32:35]
	v_mfma_f32_16x16x32_bf16 v[20:23], v[168:171], v[200:203], v[20:23]
	v_mfma_f32_16x16x32_bf16 v[16:19], v[176:179], v[200:203], v[16:19]
	v_mfma_f32_16x16x32_bf16 v[4:7], v[168:171], v[208:211], v[4:7]
	v_mfma_f32_16x16x32_bf16 v[0:3], v[176:179], v[208:211], v[0:3]
	v_mfma_f32_16x16x32_bf16 v[52:55], v[172:175], v[188:191], v[52:55]
	v_mfma_f32_16x16x32_bf16 v[48:51], v[180:183], v[188:191], v[48:51]
	v_mfma_f32_16x16x32_bf16 v[36:39], v[172:175], v[196:199], v[36:39]
	v_mfma_f32_16x16x32_bf16 v[32:35], v[180:183], v[196:199], v[32:35]
	v_mfma_f32_16x16x32_bf16 v[20:23], v[172:175], v[204:207], v[20:23]
	v_mfma_f32_16x16x32_bf16 v[16:19], v[180:183], v[204:207], v[16:19]
	v_mfma_f32_16x16x32_bf16 v[4:7], v[172:175], v[212:215], v[4:7]
	v_mfma_f32_16x16x32_bf16 v[0:3], v[180:183], v[212:215], v[0:3]
	s_setprio 0
	s_barrier
	s_add_i32 s67, 0, 0x18000
	v_add_u32_e32 v155, s67, v149
	s_add_i32 s70, 0, 0x1c000
	ds_read_b128 v[144:147], v155
	ds_read_b128 v[156:159], v155 offset:1024
	ds_read_b128 v[160:163], v155 offset:2048
	ds_read_b128 v[164:167], v155 offset:3072
	v_add_u32_e32 v155, s70, v149
	ds_read_b128 v[168:171], v155
	ds_read_b128 v[172:175], v155 offset:1024
	ds_read_b128 v[176:179], v155 offset:2048
	ds_read_b128 v[180:183], v155 offset:3072
	s_add_u32 s34, s54, 0x160000
	s_addc_u32 s35, s55, 0
	s_mov_b32 m0, s57
	v_lshl_add_u64 v[224:225], s[34:35], 0, v[128:129]
	ds_read_b128 v[184:187], v153 offset:32768
	ds_read_b128 v[188:191], v153 offset:33792
	ds_read_b128 v[192:195], v153 offset:34816
	ds_read_b128 v[196:199], v153 offset:35840
	ds_read_b128 v[200:203], v153 offset:36864
	ds_read_b128 v[204:207], v153 offset:37888
	ds_read_b128 v[208:211], v153 offset:38912
	ds_read_b128 v[212:215], v153 offset:39936
	global_load_lds_dwordx4 v[224:225], off
	v_lshl_add_u64 v[224:225], s[34:35], 0, v[132:133]
	s_mov_b32 m0, s58
	s_nop 0
	global_load_lds_dwordx4 v[224:225], off
	s_waitcnt vmcnt(8)
	s_waitcnt lgkmcnt(0)
	s_barrier
	s_setprio 1
	s_waitcnt lgkmcnt(0)
	v_mfma_f32_16x16x32_bf16 v[124:127], v[144:147], v[184:187], v[124:127]
	v_mfma_f32_16x16x32_bf16 v[120:123], v[160:163], v[184:187], v[120:123]
	v_mfma_f32_16x16x32_bf16 v[108:111], v[144:147], v[192:195], v[108:111]
	v_mfma_f32_16x16x32_bf16 v[104:107], v[160:163], v[192:195], v[104:107]
	v_mfma_f32_16x16x32_bf16 v[92:95], v[144:147], v[200:203], v[92:95]
	v_mfma_f32_16x16x32_bf16 v[88:91], v[160:163], v[200:203], v[88:91]
	v_mfma_f32_16x16x32_bf16 v[76:79], v[144:147], v[208:211], v[76:79]
	v_mfma_f32_16x16x32_bf16 v[72:75], v[160:163], v[208:211], v[72:75]
	v_mfma_f32_16x16x32_bf16 v[124:127], v[156:159], v[188:191], v[124:127]
	v_mfma_f32_16x16x32_bf16 v[120:123], v[164:167], v[188:191], v[120:123]
	v_mfma_f32_16x16x32_bf16 v[108:111], v[156:159], v[196:199], v[108:111]
	v_mfma_f32_16x16x32_bf16 v[104:107], v[164:167], v[196:199], v[104:107]
	v_mfma_f32_16x16x32_bf16 v[92:95], v[156:159], v[204:207], v[92:95]
	v_mfma_f32_16x16x32_bf16 v[88:91], v[164:167], v[204:207], v[88:91]
	v_mfma_f32_16x16x32_bf16 v[76:79], v[156:159], v[212:215], v[76:79]
	v_mfma_f32_16x16x32_bf16 v[72:75], v[164:167], v[212:215], v[72:75]
	s_setprio 0
	s_setprio 1
	v_mfma_f32_16x16x32_bf16 v[116:119], v[168:171], v[184:187], v[116:119]
	v_mfma_f32_16x16x32_bf16 v[112:115], v[176:179], v[184:187], v[112:115]
	v_mfma_f32_16x16x32_bf16 v[100:103], v[168:171], v[192:195], v[100:103]
	v_mfma_f32_16x16x32_bf16 v[96:99], v[176:179], v[192:195], v[96:99]
	v_mfma_f32_16x16x32_bf16 v[84:87], v[168:171], v[200:203], v[84:87]
	v_mfma_f32_16x16x32_bf16 v[80:83], v[176:179], v[200:203], v[80:83]
	v_mfma_f32_16x16x32_bf16 v[68:71], v[168:171], v[208:211], v[68:71]
	v_mfma_f32_16x16x32_bf16 v[64:67], v[176:179], v[208:211], v[64:67]
	v_mfma_f32_16x16x32_bf16 v[116:119], v[172:175], v[188:191], v[116:119]
	v_mfma_f32_16x16x32_bf16 v[112:115], v[180:183], v[188:191], v[112:115]
	v_mfma_f32_16x16x32_bf16 v[100:103], v[172:175], v[196:199], v[100:103]
	v_mfma_f32_16x16x32_bf16 v[96:99], v[180:183], v[196:199], v[96:99]
	v_mfma_f32_16x16x32_bf16 v[84:87], v[172:175], v[204:207], v[84:87]
	v_mfma_f32_16x16x32_bf16 v[80:83], v[180:183], v[204:207], v[80:83]
	v_mfma_f32_16x16x32_bf16 v[68:71], v[172:175], v[212:215], v[68:71]
	v_mfma_f32_16x16x32_bf16 v[64:67], v[180:183], v[212:215], v[64:67]
	s_setprio 0
	s_barrier
	s_add_i32 s34, s67, s48
	v_lshl_add_u64 v[216:217], v[216:217], 0, s[24:25]
	s_mov_b32 m0, s34
	ds_read_b128 v[184:187], v153 offset:49152
	ds_read_b128 v[188:191], v153 offset:50176
	ds_read_b128 v[192:195], v153 offset:51200
	ds_read_b128 v[196:199], v153 offset:52224
	ds_read_b128 v[200:203], v153 offset:53248
	ds_read_b128 v[204:207], v153 offset:54272
	ds_read_b128 v[208:211], v153 offset:55296
	ds_read_b128 v[212:215], v153 offset:56320
	global_load_lds_dwordx4 v[216:217], off
	s_add_i32 m0, s34, 0x2000
	s_add_u32 s34, s52, 0x160080
	v_lshl_add_u64 v[216:217], v[218:219], 0, s[24:25]
	s_addc_u32 s35, s53, 0
	s_add_i32 s52, s70, s48
	global_load_lds_dwordx4 v[216:217], off
	v_lshl_add_u64 v[216:217], s[34:35], 0, v[130:131]
	s_mov_b32 m0, s52
	s_nop 0
	global_load_lds_dwordx4 v[216:217], off
	v_lshl_add_u64 v[216:217], s[34:35], 0, v[134:135]
	s_add_i32 m0, s52, 0x2000
	s_nop 0
	global_load_lds_dwordx4 v[216:217], off
	s_waitcnt vmcnt(6)
	s_waitcnt lgkmcnt(0)
	s_barrier
	v_lshl_add_u64 v[216:217], v[220:221], 0, s[24:25]
	s_mov_b32 m0, s60
	s_nop 0
	global_load_lds_dwordx4 v[216:217], off
	v_lshl_add_u64 v[216:217], v[222:223], 0, s[24:25]
	s_mov_b32 m0, s61
	s_nop 0
	global_load_lds_dwordx4 v[216:217], off
	s_setprio 1
	s_waitcnt lgkmcnt(0)
	v_mfma_f32_16x16x32_bf16 v[60:63], v[144:147], v[184:187], v[60:63]
	v_mfma_f32_16x16x32_bf16 v[56:59], v[160:163], v[184:187], v[56:59]
	v_mfma_f32_16x16x32_bf16 v[44:47], v[144:147], v[192:195], v[44:47]
	v_mfma_f32_16x16x32_bf16 v[40:43], v[160:163], v[192:195], v[40:43]
	v_mfma_f32_16x16x32_bf16 v[28:31], v[144:147], v[200:203], v[28:31]
	v_mfma_f32_16x16x32_bf16 v[24:27], v[160:163], v[200:203], v[24:27]
	v_mfma_f32_16x16x32_bf16 v[12:15], v[144:147], v[208:211], v[12:15]
	v_mfma_f32_16x16x32_bf16 v[8:11], v[160:163], v[208:211], v[8:11]
	v_mfma_f32_16x16x32_bf16 v[60:63], v[156:159], v[188:191], v[60:63]
	v_mfma_f32_16x16x32_bf16 v[56:59], v[164:167], v[188:191], v[56:59]
	v_mfma_f32_16x16x32_bf16 v[44:47], v[156:159], v[196:199], v[44:47]
	v_mfma_f32_16x16x32_bf16 v[40:43], v[164:167], v[196:199], v[40:43]
	v_mfma_f32_16x16x32_bf16 v[28:31], v[156:159], v[204:207], v[28:31]
	v_mfma_f32_16x16x32_bf16 v[24:27], v[164:167], v[204:207], v[24:27]
	v_mfma_f32_16x16x32_bf16 v[12:15], v[156:159], v[212:215], v[12:15]
	v_mfma_f32_16x16x32_bf16 v[8:11], v[164:167], v[212:215], v[8:11]
	s_setprio 0
	s_setprio 1
	v_mfma_f32_16x16x32_bf16 v[52:55], v[168:171], v[184:187], v[52:55]
	v_mfma_f32_16x16x32_bf16 v[48:51], v[176:179], v[184:187], v[48:51]
	v_mfma_f32_16x16x32_bf16 v[36:39], v[168:171], v[192:195], v[36:39]
	v_mfma_f32_16x16x32_bf16 v[32:35], v[176:179], v[192:195], v[32:35]
	v_mfma_f32_16x16x32_bf16 v[20:23], v[168:171], v[200:203], v[20:23]
	v_mfma_f32_16x16x32_bf16 v[16:19], v[176:179], v[200:203], v[16:19]
	v_mfma_f32_16x16x32_bf16 v[4:7], v[168:171], v[208:211], v[4:7]
	v_mfma_f32_16x16x32_bf16 v[0:3], v[176:179], v[208:211], v[0:3]
	v_mfma_f32_16x16x32_bf16 v[52:55], v[172:175], v[188:191], v[52:55]
	v_mfma_f32_16x16x32_bf16 v[48:51], v[180:183], v[188:191], v[48:51]
	v_mfma_f32_16x16x32_bf16 v[36:39], v[172:175], v[196:199], v[36:39]
	v_mfma_f32_16x16x32_bf16 v[32:35], v[180:183], v[196:199], v[32:35]
	v_mfma_f32_16x16x32_bf16 v[20:23], v[172:175], v[204:207], v[20:23]
	v_mfma_f32_16x16x32_bf16 v[16:19], v[180:183], v[204:207], v[16:19]
	v_mfma_f32_16x16x32_bf16 v[4:7], v[172:175], v[212:215], v[4:7]
	v_mfma_f32_16x16x32_bf16 v[0:3], v[180:183], v[212:215], v[0:3]
	s_setprio 0
	s_barrier
	s_add_i32 s66, s66, 2
	s_add_u32 s46, s46, 0x100
	s_addc_u32 s47, s47, 0
	s_cmpk_gt_u32 s66, 0x55
	s_mov_b64 s[34:35], s[36:37]
	s_cbranch_scc0 .LBB0_523
	s_and_b64 vcc, exec, s[26:27]
	s_cbranch_vccz .LBB0_526
	s_barrier

.LBB0_617:
	ds_read_b128 v[146:149], v159
	ds_read_b128 v[150:153], v159 offset:1024
	ds_read_b128 v[164:167], v159 offset:2048
	ds_read_b128 v[168:171], v159 offset:3072
	ds_read_b128 v[172:175], v160
	ds_read_b128 v[176:179], v160 offset:1024
	ds_read_b128 v[180:183], v160 offset:2048
	ds_read_b128 v[184:187], v160 offset:3072
	s_add_u32 s58, s56, 0xfff80080
	s_addc_u32 s59, s57, -1
	s_cmp_eq_u32 s55, 28
	s_cselect_b32 s61, s35, s59
	s_cselect_b32 s60, s46, s58
	s_cselect_b32 s59, s31, s51
	s_cselect_b32 s58, s47, s50
	v_lshl_add_u64 v[154:155], s[56:57], 0, v[140:141]
	s_add_i32 m0, s45, 0xc000
	ds_read_b128 v[188:191], v161
	ds_read_b128 v[192:195], v161 offset:1024
	ds_read_b128 v[196:199], v161 offset:2048
	ds_read_b128 v[200:203], v161 offset:3072
	ds_read_b128 v[204:207], v161 offset:4096
	ds_read_b128 v[208:211], v161 offset:5120
	ds_read_b128 v[212:215], v161 offset:6144
	ds_read_b128 v[216:219], v161 offset:7168
	global_load_lds_dwordx4 v[154:155], off
	v_lshl_add_u64 v[154:155], s[56:57], 0, v[138:139]
	s_add_i32 m0, s45, 0xe000
	s_nop 0
	global_load_lds_dwordx4 v[154:155], off
	s_waitcnt vmcnt(8)
	s_waitcnt lgkmcnt(0)
	s_barrier
	s_setprio 1
	s_waitcnt lgkmcnt(0)
	v_mfma_f32_16x16x32_bf16 v[124:127], v[146:149], v[188:191], v[124:127]
	v_mfma_f32_16x16x32_bf16 v[120:123], v[164:167], v[188:191], v[120:123]
	v_mfma_f32_16x16x32_bf16 v[108:111], v[146:149], v[196:199], v[108:111]
	v_mfma_f32_16x16x32_bf16 v[104:107], v[164:167], v[196:199], v[104:107]
	v_mfma_f32_16x16x32_bf16 v[92:95], v[146:149], v[204:207], v[92:95]
	v_mfma_f32_16x16x32_bf16 v[88:91], v[164:167], v[204:207], v[88:91]
	v_mfma_f32_16x16x32_bf16 v[76:79], v[146:149], v[212:215], v[76:79]
	v_mfma_f32_16x16x32_bf16 v[72:75], v[164:167], v[212:215], v[72:75]
	v_mfma_f32_16x16x32_bf16 v[124:127], v[150:153], v[192:195], v[124:127]
	v_mfma_f32_16x16x32_bf16 v[120:123], v[168:171], v[192:195], v[120:123]
	v_mfma_f32_16x16x32_bf16 v[108:111], v[150:153], v[200:203], v[108:111]
	v_mfma_f32_16x16x32_bf16 v[104:107], v[168:171], v[200:203], v[104:107]
	v_mfma_f32_16x16x32_bf16 v[92:95], v[150:153], v[208:211], v[92:95]
	v_mfma_f32_16x16x32_bf16 v[88:91], v[168:171], v[208:211], v[88:91]
	v_mfma_f32_16x16x32_bf16 v[76:79], v[150:153], v[216:219], v[76:79]
	v_mfma_f32_16x16x32_bf16 v[72:75], v[168:171], v[216:219], v[72:75]
	s_setprio 0
	s_setprio 1
	v_mfma_f32_16x16x32_bf16 v[116:119], v[172:175], v[188:191], v[116:119]
	v_mfma_f32_16x16x32_bf16 v[112:115], v[180:183], v[188:191], v[112:115]
	v_mfma_f32_16x16x32_bf16 v[100:103], v[172:175], v[196:199], v[100:103]
	v_mfma_f32_16x16x32_bf16 v[96:99], v[180:183], v[196:199], v[96:99]
	v_mfma_f32_16x16x32_bf16 v[84:87], v[172:175], v[204:207], v[84:87]
	v_mfma_f32_16x16x32_bf16 v[80:83], v[180:183], v[204:207], v[80:83]
	v_mfma_f32_16x16x32_bf16 v[68:71], v[172:175], v[212:215], v[68:71]
	v_mfma_f32_16x16x32_bf16 v[64:67], v[180:183], v[212:215], v[64:67]
	v_mfma_f32_16x16x32_bf16 v[116:119], v[176:179], v[192:195], v[116:119]
	v_mfma_f32_16x16x32_bf16 v[112:115], v[184:187], v[192:195], v[112:115]
	v_mfma_f32_16x16x32_bf16 v[100:103], v[176:179], v[200:203], v[100:103]
	v_mfma_f32_16x16x32_bf16 v[96:99], v[184:187], v[200:203], v[96:99]
	v_mfma_f32_16x16x32_bf16 v[84:87], v[176:179], v[208:211], v[84:87]
	v_mfma_f32_16x16x32_bf16 v[80:83], v[184:187], v[208:211], v[80:83]
	v_mfma_f32_16x16x32_bf16 v[68:71], v[176:179], v[216:219], v[68:71]
	v_mfma_f32_16x16x32_bf16 v[64:67], v[184:187], v[216:219], v[64:67]
	s_setprio 0
	s_barrier
	s_add_i32 s72, s66, s44
	v_lshl_add_u64 v[154:155], s[58:59], 0, v[130:131]
	s_mov_b32 m0, s72
	ds_read_b128 v[188:191], v161 offset:16384
	ds_read_b128 v[192:195], v161 offset:17408
	ds_read_b128 v[196:199], v161 offset:18432
	ds_read_b128 v[200:203], v161 offset:19456
	ds_read_b128 v[204:207], v161 offset:20480
	ds_read_b128 v[208:211], v161 offset:21504
	ds_read_b128 v[212:215], v161 offset:22528
	ds_read_b128 v[216:219], v161 offset:23552
	global_load_lds_dwordx4 v[154:155], off
	s_add_i32 m0, s72, 0x2000
	s_add_u32 s80, s58, 0x80000
	v_lshl_add_u64 v[220:221], s[58:59], 0, v[134:135]
	s_addc_u32 s81, s59, 0
	s_add_i32 s72, s67, s44
	global_load_lds_dwordx4 v[220:221], off
	v_lshl_add_u64 v[222:223], s[80:81], 0, v[130:131]
	s_mov_b32 m0, s72
	v_lshl_add_u64 v[224:225], s[60:61], 0, v[132:133]
	global_load_lds_dwordx4 v[222:223], off
	v_lshl_add_u64 v[222:223], s[80:81], 0, v[134:135]
	s_add_i32 m0, s72, 0x2000
	s_nop 0
	global_load_lds_dwordx4 v[222:223], off
	s_waitcnt vmcnt(6)
	s_waitcnt lgkmcnt(0)
	s_barrier
	v_lshl_add_u64 v[222:223], s[60:61], 0, v[128:129]
	s_mov_b32 m0, s45
	s_nop 0
	global_load_lds_dwordx4 v[222:223], off
	s_mov_b32 m0, s48
	s_nop 0
	global_load_lds_dwordx4 v[224:225], off
	s_setprio 1
	s_waitcnt lgkmcnt(0)
	v_mfma_f32_16x16x32_bf16 v[60:63], v[146:149], v[188:191], v[60:63]
	v_mfma_f32_16x16x32_bf16 v[56:59], v[164:167], v[188:191], v[56:59]
	v_mfma_f32_16x16x32_bf16 v[44:47], v[146:149], v[196:199], v[44:47]
	v_mfma_f32_16x16x32_bf16 v[40:43], v[164:167], v[196:199], v[40:43]
	v_mfma_f32_16x16x32_bf16 v[28:31], v[146:149], v[204:207], v[28:31]
	v_mfma_f32_16x16x32_bf16 v[24:27], v[164:167], v[204:207], v[24:27]
	v_mfma_f32_16x16x32_bf16 v[12:15], v[146:149], v[212:215], v[12:15]
	v_mfma_f32_16x16x32_bf16 v[8:11], v[164:167], v[212:215], v[8:11]
	v_mfma_f32_16x16x32_bf16 v[60:63], v[150:153], v[192:195], v[60:63]
	v_mfma_f32_16x16x32_bf16 v[56:59], v[168:171], v[192:195], v[56:59]
	v_mfma_f32_16x16x32_bf16 v[44:47], v[150:153], v[200:203], v[44:47]
	v_mfma_f32_16x16x32_bf16 v[40:43], v[168:171], v[200:203], v[40:43]
	v_mfma_f32_16x16x32_bf16 v[28:31], v[150:153], v[208:211], v[28:31]
	v_mfma_f32_16x16x32_bf16 v[24:27], v[168:171], v[208:211], v[24:27]
	v_mfma_f32_16x16x32_bf16 v[12:15], v[150:153], v[216:219], v[12:15]
	v_mfma_f32_16x16x32_bf16 v[8:11], v[168:171], v[216:219], v[8:11]
	s_setprio 0
	s_setprio 1
	v_mfma_f32_16x16x32_bf16 v[52:55], v[172:175], v[188:191], v[52:55]
	v_mfma_f32_16x16x32_bf16 v[48:51], v[180:183], v[188:191], v[48:51]
	v_mfma_f32_16x16x32_bf16 v[36:39], v[172:175], v[196:199], v[36:39]
	v_mfma_f32_16x16x32_bf16 v[32:35], v[180:183], v[196:199], v[32:35]
	v_mfma_f32_16x16x32_bf16 v[20:23], v[172:175], v[204:207], v[20:23]
	v_mfma_f32_16x16x32_bf16 v[16:19], v[180:183], v[204:207], v[16:19]
	v_mfma_f32_16x16x32_bf16 v[4:7], v[172:175], v[212:215], v[4:7]
	v_mfma_f32_16x16x32_bf16 v[0:3], v[180:183], v[212:215], v[0:3]
	v_mfma_f32_16x16x32_bf16 v[52:55], v[176:179], v[192:195], v[52:55]
	v_mfma_f32_16x16x32_bf16 v[48:51], v[184:187], v[192:195], v[48:51]
	v_mfma_f32_16x16x32_bf16 v[36:39], v[176:179], v[200:203], v[36:39]
	v_mfma_f32_16x16x32_bf16 v[32:35], v[184:187], v[200:203], v[32:35]
	v_mfma_f32_16x16x32_bf16 v[20:23], v[176:179], v[208:211], v[20:23]
	v_mfma_f32_16x16x32_bf16 v[16:19], v[184:187], v[208:211], v[16:19]
	v_mfma_f32_16x16x32_bf16 v[4:7], v[176:179], v[216:219], v[4:7]
	v_mfma_f32_16x16x32_bf16 v[0:3], v[184:187], v[216:219], v[0:3]
	s_setprio 0
	s_barrier
	s_add_i32 s72, 0, 0x18000
	s_add_i32 s78, 0, 0x1c000
	v_add_u32_e32 v168, s72, v157
	v_add_u32_e32 v184, s78, v157
	ds_read_b128 v[146:149], v168
	ds_read_b128 v[150:153], v168 offset:1024
	ds_read_b128 v[164:167], v168 offset:2048
	ds_read_b128 v[168:171], v168 offset:3072
	ds_read_b128 v[172:175], v184
	ds_read_b128 v[176:179], v184 offset:1024
	ds_read_b128 v[180:183], v184 offset:2048
	ds_read_b128 v[184:187], v184 offset:3072
	s_add_u32 s60, s60, 0x80000
	s_addc_u32 s61, s61, 0
	s_mov_b32 m0, s49
	v_lshl_add_u64 v[226:227], s[60:61], 0, v[128:129]
	ds_read_b128 v[188:191], v161 offset:32768
	ds_read_b128 v[192:195], v161 offset:33792
	ds_read_b128 v[196:199], v161 offset:34816
	ds_read_b128 v[200:203], v161 offset:35840
	ds_read_b128 v[204:207], v161 offset:36864
	ds_read_b128 v[208:211], v161 offset:37888
	ds_read_b128 v[212:215], v161 offset:38912
	ds_read_b128 v[216:219], v161 offset:39936
	global_load_lds_dwordx4 v[226:227], off
	v_lshl_add_u64 v[226:227], s[60:61], 0, v[132:133]
	s_mov_b32 m0, s62
	s_nop 0
	global_load_lds_dwordx4 v[226:227], off
	s_waitcnt vmcnt(8)
	s_waitcnt lgkmcnt(0)
	s_barrier
	s_setprio 1
	s_waitcnt lgkmcnt(0)
	v_mfma_f32_16x16x32_bf16 v[124:127], v[146:149], v[188:191], v[124:127]
	v_mfma_f32_16x16x32_bf16 v[120:123], v[164:167], v[188:191], v[120:123]
	v_mfma_f32_16x16x32_bf16 v[108:111], v[146:149], v[196:199], v[108:111]
	v_mfma_f32_16x16x32_bf16 v[104:107], v[164:167], v[196:199], v[104:107]
	v_mfma_f32_16x16x32_bf16 v[92:95], v[146:149], v[204:207], v[92:95]
	v_mfma_f32_16x16x32_bf16 v[88:91], v[164:167], v[204:207], v[88:91]
	v_mfma_f32_16x16x32_bf16 v[76:79], v[146:149], v[212:215], v[76:79]
	v_mfma_f32_16x16x32_bf16 v[72:75], v[164:167], v[212:215], v[72:75]
	v_mfma_f32_16x16x32_bf16 v[124:127], v[150:153], v[192:195], v[124:127]
	v_mfma_f32_16x16x32_bf16 v[120:123], v[168:171], v[192:195], v[120:123]
	v_mfma_f32_16x16x32_bf16 v[108:111], v[150:153], v[200:203], v[108:111]
	v_mfma_f32_16x16x32_bf16 v[104:107], v[168:171], v[200:203], v[104:107]
	v_mfma_f32_16x16x32_bf16 v[92:95], v[150:153], v[208:211], v[92:95]
	v_mfma_f32_16x16x32_bf16 v[88:91], v[168:171], v[208:211], v[88:91]
	v_mfma_f32_16x16x32_bf16 v[76:79], v[150:153], v[216:219], v[76:79]
	v_mfma_f32_16x16x32_bf16 v[72:75], v[168:171], v[216:219], v[72:75]
	s_setprio 0
	s_setprio 1
	v_mfma_f32_16x16x32_bf16 v[116:119], v[172:175], v[188:191], v[116:119]
	v_mfma_f32_16x16x32_bf16 v[112:115], v[180:183], v[188:191], v[112:115]
	v_mfma_f32_16x16x32_bf16 v[100:103], v[172:175], v[196:199], v[100:103]
	v_mfma_f32_16x16x32_bf16 v[96:99], v[180:183], v[196:199], v[96:99]
	v_mfma_f32_16x16x32_bf16 v[84:87], v[172:175], v[204:207], v[84:87]
	v_mfma_f32_16x16x32_bf16 v[80:83], v[180:183], v[204:207], v[80:83]
	v_mfma_f32_16x16x32_bf16 v[68:71], v[172:175], v[212:215], v[68:71]
	v_mfma_f32_16x16x32_bf16 v[64:67], v[180:183], v[212:215], v[64:67]
	v_mfma_f32_16x16x32_bf16 v[116:119], v[176:179], v[192:195], v[116:119]
	v_mfma_f32_16x16x32_bf16 v[112:115], v[184:187], v[192:195], v[112:115]
	v_mfma_f32_16x16x32_bf16 v[100:103], v[176:179], v[200:203], v[100:103]
	v_mfma_f32_16x16x32_bf16 v[96:99], v[184:187], v[200:203], v[96:99]
	v_mfma_f32_16x16x32_bf16 v[84:87], v[176:179], v[208:211], v[84:87]
	v_mfma_f32_16x16x32_bf16 v[80:83], v[184:187], v[208:211], v[80:83]
	v_mfma_f32_16x16x32_bf16 v[68:71], v[176:179], v[216:219], v[68:71]
	v_mfma_f32_16x16x32_bf16 v[64:67], v[184:187], v[216:219], v[64:67]
	s_setprio 0
	s_barrier
	s_add_i32 s60, s72, s44
	v_lshl_add_u64 v[154:155], v[154:155], 0, s[24:25]
	s_mov_b32 m0, s60
	ds_read_b128 v[188:191], v161 offset:49152
	ds_read_b128 v[192:195], v161 offset:50176
	ds_read_b128 v[196:199], v161 offset:51200
	ds_read_b128 v[200:203], v161 offset:52224
	ds_read_b128 v[204:207], v161 offset:53248
	ds_read_b128 v[208:211], v161 offset:54272
	ds_read_b128 v[212:215], v161 offset:55296
	ds_read_b128 v[216:219], v161 offset:56320
	global_load_lds_dwordx4 v[154:155], off
	s_add_i32 m0, s60, 0x2000
	s_add_u32 s58, s58, 0x80080
	v_lshl_add_u64 v[154:155], v[220:221], 0, s[24:25]
	s_addc_u32 s59, s59, 0
	s_add_i32 s60, s78, s44
	global_load_lds_dwordx4 v[154:155], off
	v_lshl_add_u64 v[154:155], s[58:59], 0, v[130:131]
	s_mov_b32 m0, s60
	s_nop 0
	global_load_lds_dwordx4 v[154:155], off
	v_lshl_add_u64 v[154:155], s[58:59], 0, v[134:135]
	s_add_i32 m0, s60, 0x2000
	s_nop 0
	global_load_lds_dwordx4 v[154:155], off
	s_waitcnt vmcnt(6)
	s_waitcnt lgkmcnt(0)
	s_barrier
	v_lshl_add_u64 v[154:155], v[222:223], 0, s[24:25]
	s_mov_b32 m0, s64
	s_nop 0
	global_load_lds_dwordx4 v[154:155], off
	v_lshl_add_u64 v[154:155], v[224:225], 0, s[24:25]
	s_mov_b32 m0, s65
	s_nop 0
	global_load_lds_dwordx4 v[154:155], off
	s_setprio 1
	s_waitcnt lgkmcnt(0)
	v_mfma_f32_16x16x32_bf16 v[60:63], v[146:149], v[188:191], v[60:63]
	v_mfma_f32_16x16x32_bf16 v[56:59], v[164:167], v[188:191], v[56:59]
	v_mfma_f32_16x16x32_bf16 v[44:47], v[146:149], v[196:199], v[44:47]
	v_mfma_f32_16x16x32_bf16 v[40:43], v[164:167], v[196:199], v[40:43]
	v_mfma_f32_16x16x32_bf16 v[28:31], v[146:149], v[204:207], v[28:31]
	v_mfma_f32_16x16x32_bf16 v[24:27], v[164:167], v[204:207], v[24:27]
	v_mfma_f32_16x16x32_bf16 v[12:15], v[146:149], v[212:215], v[12:15]
	v_mfma_f32_16x16x32_bf16 v[8:11], v[164:167], v[212:215], v[8:11]
	v_mfma_f32_16x16x32_bf16 v[60:63], v[150:153], v[192:195], v[60:63]
	v_mfma_f32_16x16x32_bf16 v[56:59], v[168:171], v[192:195], v[56:59]
	v_mfma_f32_16x16x32_bf16 v[44:47], v[150:153], v[200:203], v[44:47]
	v_mfma_f32_16x16x32_bf16 v[40:43], v[168:171], v[200:203], v[40:43]
	v_mfma_f32_16x16x32_bf16 v[28:31], v[150:153], v[208:211], v[28:31]
	v_mfma_f32_16x16x32_bf16 v[24:27], v[168:171], v[208:211], v[24:27]
	v_mfma_f32_16x16x32_bf16 v[12:15], v[150:153], v[216:219], v[12:15]
	v_mfma_f32_16x16x32_bf16 v[8:11], v[168:171], v[216:219], v[8:11]
	s_setprio 0
	s_setprio 1
	v_mfma_f32_16x16x32_bf16 v[52:55], v[172:175], v[188:191], v[52:55]
	v_mfma_f32_16x16x32_bf16 v[48:51], v[180:183], v[188:191], v[48:51]
	v_mfma_f32_16x16x32_bf16 v[36:39], v[172:175], v[196:199], v[36:39]
	v_mfma_f32_16x16x32_bf16 v[32:35], v[180:183], v[196:199], v[32:35]
	v_mfma_f32_16x16x32_bf16 v[20:23], v[172:175], v[204:207], v[20:23]
	v_mfma_f32_16x16x32_bf16 v[16:19], v[180:183], v[204:207], v[16:19]
	v_mfma_f32_16x16x32_bf16 v[4:7], v[172:175], v[212:215], v[4:7]
	v_mfma_f32_16x16x32_bf16 v[0:3], v[180:183], v[212:215], v[0:3]
	v_mfma_f32_16x16x32_bf16 v[52:55], v[176:179], v[192:195], v[52:55]
	v_mfma_f32_16x16x32_bf16 v[48:51], v[184:187], v[192:195], v[48:51]
	v_mfma_f32_16x16x32_bf16 v[36:39], v[176:179], v[200:203], v[36:39]
	v_mfma_f32_16x16x32_bf16 v[32:35], v[184:187], v[200:203], v[32:35]
	v_mfma_f32_16x16x32_bf16 v[20:23], v[176:179], v[208:211], v[20:23]
	v_mfma_f32_16x16x32_bf16 v[16:19], v[184:187], v[208:211], v[16:19]
	v_mfma_f32_16x16x32_bf16 v[4:7], v[176:179], v[216:219], v[4:7]
	v_mfma_f32_16x16x32_bf16 v[0:3], v[184:187], v[216:219], v[0:3]
	s_setprio 0
	s_barrier
	s_add_i32 s55, s55, 2
	s_add_u32 s50, s50, 0x100
	s_addc_u32 s51, s51, 0
	s_add_u32 s56, s56, 0x100
	s_addc_u32 s57, s57, 0
	s_cmp_gt_u32 s55, 29
	s_cbranch_scc0 .LBB0_617
	s_and_b64 vcc, exec, s[26:27]
	s_cbranch_vccz .LBB0_620
	s_barrier

.LBB0_731:
	ds_read_b128 v[146:149], v153
	ds_read_b128 v[158:161], v153 offset:1024
	ds_read_b128 v[162:165], v153 offset:2048
	ds_read_b128 v[166:169], v153 offset:3072
	ds_read_b128 v[170:173], v154
	ds_read_b128 v[174:177], v154 offset:1024
	ds_read_b128 v[178:181], v154 offset:2048
	ds_read_b128 v[182:185], v154 offset:3072
	s_add_u32 s34, s30, 0xfff80080
	s_addc_u32 s35, s31, -1
	s_cmp_eq_u32 s61, 28
	s_cselect_b32 s37, s21, s35
	s_cselect_b32 s36, s46, s34
	s_cselect_b32 s35, s19, s60
	s_cselect_b32 s34, s47, s59
	v_lshl_add_u64 v[218:219], s[30:31], 0, v[140:141]
	s_add_i32 m0, s27, 0xc000
	ds_read_b128 v[186:189], v155
	ds_read_b128 v[190:193], v155 offset:1024
	ds_read_b128 v[194:197], v155 offset:2048
	ds_read_b128 v[198:201], v155 offset:3072
	ds_read_b128 v[202:205], v155 offset:4096
	ds_read_b128 v[206:209], v155 offset:5120
	ds_read_b128 v[210:213], v155 offset:6144
	ds_read_b128 v[214:217], v155 offset:7168
	global_load_lds_dwordx4 v[218:219], off
	v_lshl_add_u64 v[218:219], s[30:31], 0, v[138:139]
	s_add_i32 m0, s27, 0xe000
	s_nop 0
	global_load_lds_dwordx4 v[218:219], off
	s_waitcnt vmcnt(8)
	s_waitcnt lgkmcnt(0)
	s_barrier
	s_setprio 1
	s_waitcnt lgkmcnt(0)
	v_mfma_f32_16x16x32_bf16 v[124:127], v[146:149], v[186:189], v[124:127]
	v_mfma_f32_16x16x32_bf16 v[120:123], v[162:165], v[186:189], v[120:123]
	v_mfma_f32_16x16x32_bf16 v[108:111], v[146:149], v[194:197], v[108:111]
	v_mfma_f32_16x16x32_bf16 v[104:107], v[162:165], v[194:197], v[104:107]
	v_mfma_f32_16x16x32_bf16 v[92:95], v[146:149], v[202:205], v[92:95]
	v_mfma_f32_16x16x32_bf16 v[88:91], v[162:165], v[202:205], v[88:91]
	v_mfma_f32_16x16x32_bf16 v[76:79], v[146:149], v[210:213], v[76:79]
	v_mfma_f32_16x16x32_bf16 v[72:75], v[162:165], v[210:213], v[72:75]
	v_mfma_f32_16x16x32_bf16 v[124:127], v[158:161], v[190:193], v[124:127]
	v_mfma_f32_16x16x32_bf16 v[120:123], v[166:169], v[190:193], v[120:123]
	v_mfma_f32_16x16x32_bf16 v[108:111], v[158:161], v[198:201], v[108:111]
	v_mfma_f32_16x16x32_bf16 v[104:107], v[166:169], v[198:201], v[104:107]
	v_mfma_f32_16x16x32_bf16 v[92:95], v[158:161], v[206:209], v[92:95]
	v_mfma_f32_16x16x32_bf16 v[88:91], v[166:169], v[206:209], v[88:91]
	v_mfma_f32_16x16x32_bf16 v[76:79], v[158:161], v[214:217], v[76:79]
	v_mfma_f32_16x16x32_bf16 v[72:75], v[166:169], v[214:217], v[72:75]
	s_setprio 0
	s_setprio 1
	v_mfma_f32_16x16x32_bf16 v[116:119], v[170:173], v[186:189], v[116:119]
	v_mfma_f32_16x16x32_bf16 v[112:115], v[178:181], v[186:189], v[112:115]
	v_mfma_f32_16x16x32_bf16 v[100:103], v[170:173], v[194:197], v[100:103]
	v_mfma_f32_16x16x32_bf16 v[96:99], v[178:181], v[194:197], v[96:99]
	v_mfma_f32_16x16x32_bf16 v[84:87], v[170:173], v[202:205], v[84:87]
	v_mfma_f32_16x16x32_bf16 v[80:83], v[178:181], v[202:205], v[80:83]
	v_mfma_f32_16x16x32_bf16 v[68:71], v[170:173], v[210:213], v[68:71]
	v_mfma_f32_16x16x32_bf16 v[64:67], v[178:181], v[210:213], v[64:67]
	v_mfma_f32_16x16x32_bf16 v[116:119], v[174:177], v[190:193], v[116:119]
	v_mfma_f32_16x16x32_bf16 v[112:115], v[182:185], v[190:193], v[112:115]
	v_mfma_f32_16x16x32_bf16 v[100:103], v[174:177], v[198:201], v[100:103]
	v_mfma_f32_16x16x32_bf16 v[96:99], v[182:185], v[198:201], v[96:99]
	v_mfma_f32_16x16x32_bf16 v[84:87], v[174:177], v[206:209], v[84:87]
	v_mfma_f32_16x16x32_bf16 v[80:83], v[182:185], v[206:209], v[80:83]
	v_mfma_f32_16x16x32_bf16 v[68:71], v[174:177], v[214:217], v[68:71]
	v_mfma_f32_16x16x32_bf16 v[64:67], v[182:185], v[214:217], v[64:67]
	s_setprio 0
	s_barrier
	s_add_i32 s62, s55, s48
	v_lshl_add_u64 v[218:219], s[34:35], 0, v[130:131]
	s_mov_b32 m0, s62
	ds_read_b128 v[186:189], v155 offset:16384
	ds_read_b128 v[190:193], v155 offset:17408
	ds_read_b128 v[194:197], v155 offset:18432
	ds_read_b128 v[198:201], v155 offset:19456
	ds_read_b128 v[202:205], v155 offset:20480
	ds_read_b128 v[206:209], v155 offset:21504
	ds_read_b128 v[210:213], v155 offset:22528
	ds_read_b128 v[214:217], v155 offset:23552
	global_load_lds_dwordx4 v[218:219], off
	s_add_i32 m0, s62, 0x2000
	s_add_u32 s62, s34, 0x80000
	v_lshl_add_u64 v[220:221], s[34:35], 0, v[134:135]
	s_addc_u32 s63, s35, 0
	s_add_i32 s64, s56, s48
	global_load_lds_dwordx4 v[220:221], off
	v_lshl_add_u64 v[222:223], s[62:63], 0, v[130:131]
	s_mov_b32 m0, s64
	v_lshl_add_u64 v[224:225], s[36:37], 0, v[132:133]
	global_load_lds_dwordx4 v[222:223], off
	v_lshl_add_u64 v[222:223], s[62:63], 0, v[134:135]
	s_add_i32 m0, s64, 0x2000
	s_nop 0
	global_load_lds_dwordx4 v[222:223], off
	s_waitcnt vmcnt(6)
	s_waitcnt lgkmcnt(0)
	s_barrier
	v_lshl_add_u64 v[222:223], s[36:37], 0, v[128:129]
	s_mov_b32 m0, s27
	s_nop 0
	global_load_lds_dwordx4 v[222:223], off
	s_mov_b32 m0, s49
	s_nop 0
	global_load_lds_dwordx4 v[224:225], off
	s_setprio 1
	s_waitcnt lgkmcnt(0)
	v_mfma_f32_16x16x32_bf16 v[60:63], v[146:149], v[186:189], v[60:63]
	v_mfma_f32_16x16x32_bf16 v[56:59], v[162:165], v[186:189], v[56:59]
	v_mfma_f32_16x16x32_bf16 v[44:47], v[146:149], v[194:197], v[44:47]
	v_mfma_f32_16x16x32_bf16 v[40:43], v[162:165], v[194:197], v[40:43]
	v_mfma_f32_16x16x32_bf16 v[28:31], v[146:149], v[202:205], v[28:31]
	v_mfma_f32_16x16x32_bf16 v[24:27], v[162:165], v[202:205], v[24:27]
	v_mfma_f32_16x16x32_bf16 v[12:15], v[146:149], v[210:213], v[12:15]
	v_mfma_f32_16x16x32_bf16 v[8:11], v[162:165], v[210:213], v[8:11]
	v_mfma_f32_16x16x32_bf16 v[60:63], v[158:161], v[190:193], v[60:63]
	v_mfma_f32_16x16x32_bf16 v[56:59], v[166:169], v[190:193], v[56:59]
	v_mfma_f32_16x16x32_bf16 v[44:47], v[158:161], v[198:201], v[44:47]
	v_mfma_f32_16x16x32_bf16 v[40:43], v[166:169], v[198:201], v[40:43]
	v_mfma_f32_16x16x32_bf16 v[28:31], v[158:161], v[206:209], v[28:31]
	v_mfma_f32_16x16x32_bf16 v[24:27], v[166:169], v[206:209], v[24:27]
	v_mfma_f32_16x16x32_bf16 v[12:15], v[158:161], v[214:217], v[12:15]
	v_mfma_f32_16x16x32_bf16 v[8:11], v[166:169], v[214:217], v[8:11]
	s_setprio 0
	s_setprio 1
	v_mfma_f32_16x16x32_bf16 v[52:55], v[170:173], v[186:189], v[52:55]
	v_mfma_f32_16x16x32_bf16 v[48:51], v[178:181], v[186:189], v[48:51]
	v_mfma_f32_16x16x32_bf16 v[36:39], v[170:173], v[194:197], v[36:39]
	v_mfma_f32_16x16x32_bf16 v[32:35], v[178:181], v[194:197], v[32:35]
	v_mfma_f32_16x16x32_bf16 v[20:23], v[170:173], v[202:205], v[20:23]
	v_mfma_f32_16x16x32_bf16 v[16:19], v[178:181], v[202:205], v[16:19]
	v_mfma_f32_16x16x32_bf16 v[4:7], v[170:173], v[210:213], v[4:7]
	v_mfma_f32_16x16x32_bf16 v[0:3], v[178:181], v[210:213], v[0:3]
	v_mfma_f32_16x16x32_bf16 v[52:55], v[174:177], v[190:193], v[52:55]
	v_mfma_f32_16x16x32_bf16 v[48:51], v[182:185], v[190:193], v[48:51]
	v_mfma_f32_16x16x32_bf16 v[36:39], v[174:177], v[198:201], v[36:39]
	v_mfma_f32_16x16x32_bf16 v[32:35], v[182:185], v[198:201], v[32:35]
	v_mfma_f32_16x16x32_bf16 v[20:23], v[174:177], v[206:209], v[20:23]
	v_mfma_f32_16x16x32_bf16 v[16:19], v[182:185], v[206:209], v[16:19]
	v_mfma_f32_16x16x32_bf16 v[4:7], v[174:177], v[214:217], v[4:7]
	v_mfma_f32_16x16x32_bf16 v[0:3], v[182:185], v[214:217], v[0:3]
	s_setprio 0
	s_barrier
	s_add_i32 s62, 0, 0x18000
	s_add_i32 s63, 0, 0x1c000
	v_add_u32_e32 v166, s62, v151
	v_add_u32_e32 v182, s63, v151
	ds_read_b128 v[146:149], v166
	ds_read_b128 v[158:161], v166 offset:1024
	ds_read_b128 v[162:165], v166 offset:2048
	ds_read_b128 v[166:169], v166 offset:3072
	ds_read_b128 v[170:173], v182
	ds_read_b128 v[174:177], v182 offset:1024
	ds_read_b128 v[178:181], v182 offset:2048
	ds_read_b128 v[182:185], v182 offset:3072
	s_add_u32 s36, s36, 0x80000
	s_addc_u32 s37, s37, 0
	s_mov_b32 m0, s50
	v_lshl_add_u64 v[226:227], s[36:37], 0, v[128:129]
	ds_read_b128 v[186:189], v155 offset:32768
	ds_read_b128 v[190:193], v155 offset:33792
	ds_read_b128 v[194:197], v155 offset:34816
	ds_read_b128 v[198:201], v155 offset:35840
	ds_read_b128 v[202:205], v155 offset:36864
	ds_read_b128 v[206:209], v155 offset:37888
	ds_read_b128 v[210:213], v155 offset:38912
	ds_read_b128 v[214:217], v155 offset:39936
	global_load_lds_dwordx4 v[226:227], off
	v_lshl_add_u64 v[226:227], s[36:37], 0, v[132:133]
	s_mov_b32 m0, s51
	s_nop 0
	global_load_lds_dwordx4 v[226:227], off
	s_waitcnt vmcnt(8)
	s_waitcnt lgkmcnt(0)
	s_barrier
	s_setprio 1
	s_waitcnt lgkmcnt(0)
	v_mfma_f32_16x16x32_bf16 v[124:127], v[146:149], v[186:189], v[124:127]
	v_mfma_f32_16x16x32_bf16 v[120:123], v[162:165], v[186:189], v[120:123]
	v_mfma_f32_16x16x32_bf16 v[108:111], v[146:149], v[194:197], v[108:111]
	v_mfma_f32_16x16x32_bf16 v[104:107], v[162:165], v[194:197], v[104:107]
	v_mfma_f32_16x16x32_bf16 v[92:95], v[146:149], v[202:205], v[92:95]
	v_mfma_f32_16x16x32_bf16 v[88:91], v[162:165], v[202:205], v[88:91]
	v_mfma_f32_16x16x32_bf16 v[76:79], v[146:149], v[210:213], v[76:79]
	v_mfma_f32_16x16x32_bf16 v[72:75], v[162:165], v[210:213], v[72:75]
	v_mfma_f32_16x16x32_bf16 v[124:127], v[158:161], v[190:193], v[124:127]
	v_mfma_f32_16x16x32_bf16 v[120:123], v[166:169], v[190:193], v[120:123]
	v_mfma_f32_16x16x32_bf16 v[108:111], v[158:161], v[198:201], v[108:111]
	v_mfma_f32_16x16x32_bf16 v[104:107], v[166:169], v[198:201], v[104:107]
	v_mfma_f32_16x16x32_bf16 v[92:95], v[158:161], v[206:209], v[92:95]
	v_mfma_f32_16x16x32_bf16 v[88:91], v[166:169], v[206:209], v[88:91]
	v_mfma_f32_16x16x32_bf16 v[76:79], v[158:161], v[214:217], v[76:79]
	v_mfma_f32_16x16x32_bf16 v[72:75], v[166:169], v[214:217], v[72:75]
	s_setprio 0
	s_setprio 1
	v_mfma_f32_16x16x32_bf16 v[116:119], v[170:173], v[186:189], v[116:119]
	v_mfma_f32_16x16x32_bf16 v[112:115], v[178:181], v[186:189], v[112:115]
	v_mfma_f32_16x16x32_bf16 v[100:103], v[170:173], v[194:197], v[100:103]
	v_mfma_f32_16x16x32_bf16 v[96:99], v[178:181], v[194:197], v[96:99]
	v_mfma_f32_16x16x32_bf16 v[84:87], v[170:173], v[202:205], v[84:87]
	v_mfma_f32_16x16x32_bf16 v[80:83], v[178:181], v[202:205], v[80:83]
	v_mfma_f32_16x16x32_bf16 v[68:71], v[170:173], v[210:213], v[68:71]
	v_mfma_f32_16x16x32_bf16 v[64:67], v[178:181], v[210:213], v[64:67]
	v_mfma_f32_16x16x32_bf16 v[116:119], v[174:177], v[190:193], v[116:119]
	v_mfma_f32_16x16x32_bf16 v[112:115], v[182:185], v[190:193], v[112:115]
	v_mfma_f32_16x16x32_bf16 v[100:103], v[174:177], v[198:201], v[100:103]
	v_mfma_f32_16x16x32_bf16 v[96:99], v[182:185], v[198:201], v[96:99]
	v_mfma_f32_16x16x32_bf16 v[84:87], v[174:177], v[206:209], v[84:87]
	v_mfma_f32_16x16x32_bf16 v[80:83], v[182:185], v[206:209], v[80:83]
	v_mfma_f32_16x16x32_bf16 v[68:71], v[174:177], v[214:217], v[68:71]
	v_mfma_f32_16x16x32_bf16 v[64:67], v[182:185], v[214:217], v[64:67]
	s_setprio 0
	s_barrier
	s_add_i32 s36, s62, s48
	v_lshl_add_u64 v[218:219], v[218:219], 0, s[14:15]
	s_mov_b32 m0, s36
	ds_read_b128 v[186:189], v155 offset:49152
	ds_read_b128 v[190:193], v155 offset:50176
	ds_read_b128 v[194:197], v155 offset:51200
	ds_read_b128 v[198:201], v155 offset:52224
	ds_read_b128 v[202:205], v155 offset:53248
	ds_read_b128 v[206:209], v155 offset:54272
	ds_read_b128 v[210:213], v155 offset:55296
	ds_read_b128 v[214:217], v155 offset:56320
	global_load_lds_dwordx4 v[218:219], off
	s_add_i32 m0, s36, 0x2000
	s_add_u32 s34, s34, 0x80080
	v_lshl_add_u64 v[218:219], v[220:221], 0, s[14:15]
	s_addc_u32 s35, s35, 0
	s_add_i32 s36, s63, s48
	global_load_lds_dwordx4 v[218:219], off
	v_lshl_add_u64 v[218:219], s[34:35], 0, v[130:131]
	s_mov_b32 m0, s36
	s_nop 0
	global_load_lds_dwordx4 v[218:219], off
	v_lshl_add_u64 v[218:219], s[34:35], 0, v[134:135]
	s_add_i32 m0, s36, 0x2000
	s_nop 0
	global_load_lds_dwordx4 v[218:219], off
	s_waitcnt vmcnt(6)
	s_waitcnt lgkmcnt(0)
	s_barrier
	v_lshl_add_u64 v[218:219], v[222:223], 0, s[14:15]
	s_mov_b32 m0, s53
	s_nop 0
	global_load_lds_dwordx4 v[218:219], off
	v_lshl_add_u64 v[218:219], v[224:225], 0, s[14:15]
	s_mov_b32 m0, s54
	s_nop 0
	global_load_lds_dwordx4 v[218:219], off
	s_setprio 1
	s_waitcnt lgkmcnt(0)
	v_mfma_f32_16x16x32_bf16 v[60:63], v[146:149], v[186:189], v[60:63]
	v_mfma_f32_16x16x32_bf16 v[56:59], v[162:165], v[186:189], v[56:59]
	v_mfma_f32_16x16x32_bf16 v[44:47], v[146:149], v[194:197], v[44:47]
	v_mfma_f32_16x16x32_bf16 v[40:43], v[162:165], v[194:197], v[40:43]
	v_mfma_f32_16x16x32_bf16 v[28:31], v[146:149], v[202:205], v[28:31]
	v_mfma_f32_16x16x32_bf16 v[24:27], v[162:165], v[202:205], v[24:27]
	v_mfma_f32_16x16x32_bf16 v[12:15], v[146:149], v[210:213], v[12:15]
	v_mfma_f32_16x16x32_bf16 v[8:11], v[162:165], v[210:213], v[8:11]
	v_mfma_f32_16x16x32_bf16 v[60:63], v[158:161], v[190:193], v[60:63]
	v_mfma_f32_16x16x32_bf16 v[56:59], v[166:169], v[190:193], v[56:59]
	v_mfma_f32_16x16x32_bf16 v[44:47], v[158:161], v[198:201], v[44:47]
	v_mfma_f32_16x16x32_bf16 v[40:43], v[166:169], v[198:201], v[40:43]
	v_mfma_f32_16x16x32_bf16 v[28:31], v[158:161], v[206:209], v[28:31]
	v_mfma_f32_16x16x32_bf16 v[24:27], v[166:169], v[206:209], v[24:27]
	v_mfma_f32_16x16x32_bf16 v[12:15], v[158:161], v[214:217], v[12:15]
	v_mfma_f32_16x16x32_bf16 v[8:11], v[166:169], v[214:217], v[8:11]
	s_setprio 0
	s_setprio 1
	v_mfma_f32_16x16x32_bf16 v[52:55], v[170:173], v[186:189], v[52:55]
	v_mfma_f32_16x16x32_bf16 v[48:51], v[178:181], v[186:189], v[48:51]
	v_mfma_f32_16x16x32_bf16 v[36:39], v[170:173], v[194:197], v[36:39]
	v_mfma_f32_16x16x32_bf16 v[32:35], v[178:181], v[194:197], v[32:35]
	v_mfma_f32_16x16x32_bf16 v[20:23], v[170:173], v[202:205], v[20:23]
	v_mfma_f32_16x16x32_bf16 v[16:19], v[178:181], v[202:205], v[16:19]
	v_mfma_f32_16x16x32_bf16 v[4:7], v[170:173], v[210:213], v[4:7]
	v_mfma_f32_16x16x32_bf16 v[0:3], v[178:181], v[210:213], v[0:3]
	v_mfma_f32_16x16x32_bf16 v[52:55], v[174:177], v[190:193], v[52:55]
	v_mfma_f32_16x16x32_bf16 v[48:51], v[182:185], v[190:193], v[48:51]
	v_mfma_f32_16x16x32_bf16 v[36:39], v[174:177], v[198:201], v[36:39]
	v_mfma_f32_16x16x32_bf16 v[32:35], v[182:185], v[198:201], v[32:35]
	v_mfma_f32_16x16x32_bf16 v[20:23], v[174:177], v[206:209], v[20:23]
	v_mfma_f32_16x16x32_bf16 v[16:19], v[182:185], v[206:209], v[16:19]
	v_mfma_f32_16x16x32_bf16 v[4:7], v[174:177], v[214:217], v[4:7]
	v_mfma_f32_16x16x32_bf16 v[0:3], v[182:185], v[214:217], v[0:3]
	s_setprio 0
	s_barrier
	s_add_i32 s61, s61, 2
	s_add_u32 s59, s59, 0x100
	s_addc_u32 s60, s60, 0
	s_add_u32 s30, s30, 0x100
	s_addc_u32 s31, s31, 0
	s_cmp_gt_u32 s61, 29
	s_cbranch_scc0 .LBB0_731
	s_and_b64 vcc, exec, s[16:17]
	s_cbranch_vccz .LBB0_734
	s_barrier

.LBB0_952:
	ds_read_b128 v[144:147], v151
	ds_read_b128 v[156:159], v151 offset:1024
	ds_read_b128 v[160:163], v151 offset:2048
	ds_read_b128 v[164:167], v151 offset:3072
	ds_read_b128 v[168:171], v152
	ds_read_b128 v[172:175], v152 offset:1024
	ds_read_b128 v[176:179], v152 offset:2048
	ds_read_b128 v[180:183], v152 offset:3072
	s_add_u32 s54, s52, 0xfff80080
	s_addc_u32 s55, s53, -1
	s_cmp_eq_u32 s68, 28
	s_cselect_b32 s57, s27, s55
	s_cselect_b32 s56, s37, s54
	s_cselect_b32 s55, s25, s67
	s_cselect_b32 s54, s46, s47
	v_lshl_add_u64 v[216:217], s[52:53], 0, v[138:139]
	s_add_i32 m0, s59, 0xc000
	ds_read_b128 v[184:187], v153
	ds_read_b128 v[188:191], v153 offset:1024
	ds_read_b128 v[192:195], v153 offset:2048
	ds_read_b128 v[196:199], v153 offset:3072
	ds_read_b128 v[200:203], v153 offset:4096
	ds_read_b128 v[204:207], v153 offset:5120
	ds_read_b128 v[208:211], v153 offset:6144
	ds_read_b128 v[212:215], v153 offset:7168
	global_load_lds_dwordx4 v[216:217], off
	v_lshl_add_u64 v[216:217], s[52:53], 0, v[136:137]
	s_add_i32 m0, s59, 0xe000
	s_nop 0
	global_load_lds_dwordx4 v[216:217], off
	s_waitcnt vmcnt(8)
	s_waitcnt lgkmcnt(0)
	s_barrier
	s_setprio 1
	s_waitcnt lgkmcnt(0)
	v_mfma_f32_16x16x32_bf16 v[116:119], v[144:147], v[184:187], v[116:119]
	v_mfma_f32_16x16x32_bf16 v[112:115], v[160:163], v[184:187], v[112:115]
	v_mfma_f32_16x16x32_bf16 v[104:107], v[144:147], v[192:195], v[104:107]
	v_mfma_f32_16x16x32_bf16 v[96:99], v[160:163], v[192:195], v[96:99]
	v_mfma_f32_16x16x32_bf16 v[88:91], v[144:147], v[200:203], v[88:91]
	v_mfma_f32_16x16x32_bf16 v[80:83], v[160:163], v[200:203], v[80:83]
	v_mfma_f32_16x16x32_bf16 v[72:75], v[144:147], v[208:211], v[72:75]
	v_mfma_f32_16x16x32_bf16 v[64:67], v[160:163], v[208:211], v[64:67]
	v_mfma_f32_16x16x32_bf16 v[116:119], v[156:159], v[188:191], v[116:119]
	v_mfma_f32_16x16x32_bf16 v[112:115], v[164:167], v[188:191], v[112:115]
	v_mfma_f32_16x16x32_bf16 v[104:107], v[156:159], v[196:199], v[104:107]
	v_mfma_f32_16x16x32_bf16 v[96:99], v[164:167], v[196:199], v[96:99]
	v_mfma_f32_16x16x32_bf16 v[88:91], v[156:159], v[204:207], v[88:91]
	v_mfma_f32_16x16x32_bf16 v[80:83], v[164:167], v[204:207], v[80:83]
	v_mfma_f32_16x16x32_bf16 v[72:75], v[156:159], v[212:215], v[72:75]
	v_mfma_f32_16x16x32_bf16 v[64:67], v[164:167], v[212:215], v[64:67]
	s_setprio 0
	s_setprio 1
	v_mfma_f32_16x16x32_bf16 v[124:127], v[168:171], v[184:187], v[124:127]
	v_mfma_f32_16x16x32_bf16 v[120:123], v[176:179], v[184:187], v[120:123]
	v_mfma_f32_16x16x32_bf16 v[108:111], v[168:171], v[192:195], v[108:111]
	v_mfma_f32_16x16x32_bf16 v[100:103], v[176:179], v[192:195], v[100:103]
	v_mfma_f32_16x16x32_bf16 v[92:95], v[168:171], v[200:203], v[92:95]
	v_mfma_f32_16x16x32_bf16 v[84:87], v[176:179], v[200:203], v[84:87]
	v_mfma_f32_16x16x32_bf16 v[76:79], v[168:171], v[208:211], v[76:79]
	v_mfma_f32_16x16x32_bf16 v[68:71], v[176:179], v[208:211], v[68:71]
	v_mfma_f32_16x16x32_bf16 v[124:127], v[172:175], v[188:191], v[124:127]
	v_mfma_f32_16x16x32_bf16 v[120:123], v[180:183], v[188:191], v[120:123]
	v_mfma_f32_16x16x32_bf16 v[108:111], v[172:175], v[196:199], v[108:111]
	v_mfma_f32_16x16x32_bf16 v[100:103], v[180:183], v[196:199], v[100:103]
	v_mfma_f32_16x16x32_bf16 v[92:95], v[172:175], v[204:207], v[92:95]
	v_mfma_f32_16x16x32_bf16 v[84:87], v[180:183], v[204:207], v[84:87]
	v_mfma_f32_16x16x32_bf16 v[76:79], v[172:175], v[212:215], v[76:79]
	v_mfma_f32_16x16x32_bf16 v[68:71], v[180:183], v[212:215], v[68:71]
	s_setprio 0
	s_barrier
	s_add_i32 s69, s64, s58
	v_lshl_add_u64 v[216:217], s[54:55], 0, v[130:131]
	s_mov_b32 m0, s69
	ds_read_b128 v[184:187], v153 offset:16384
	ds_read_b128 v[188:191], v153 offset:17408
	ds_read_b128 v[192:195], v153 offset:18432
	ds_read_b128 v[196:199], v153 offset:19456
	ds_read_b128 v[200:203], v153 offset:20480
	ds_read_b128 v[204:207], v153 offset:21504
	ds_read_b128 v[208:211], v153 offset:22528
	ds_read_b128 v[212:215], v153 offset:23552
	global_load_lds_dwordx4 v[216:217], off
	s_add_i32 m0, s69, 0x2000
	s_add_u32 s70, s54, 0x80000
	v_lshl_add_u64 v[218:219], s[54:55], 0, v[134:135]
	s_addc_u32 s71, s55, 0
	s_add_i32 s69, s65, s58
	global_load_lds_dwordx4 v[218:219], off
	v_lshl_add_u64 v[220:221], s[70:71], 0, v[130:131]
	s_mov_b32 m0, s69
	v_lshl_add_u64 v[222:223], s[56:57], 0, v[132:133]
	global_load_lds_dwordx4 v[220:221], off
	v_lshl_add_u64 v[220:221], s[70:71], 0, v[134:135]
	s_add_i32 m0, s69, 0x2000
	s_nop 0
	global_load_lds_dwordx4 v[220:221], off
	s_waitcnt vmcnt(6)
	s_waitcnt lgkmcnt(0)
	s_barrier
	v_lshl_add_u64 v[220:221], s[56:57], 0, v[128:129]
	s_mov_b32 m0, s59
	s_nop 0
	global_load_lds_dwordx4 v[220:221], off
	s_mov_b32 m0, s50
	s_nop 0
	global_load_lds_dwordx4 v[222:223], off
	s_setprio 1
	s_waitcnt lgkmcnt(0)
	v_mfma_f32_16x16x32_bf16 v[56:59], v[144:147], v[184:187], v[56:59]
	v_mfma_f32_16x16x32_bf16 v[48:51], v[160:163], v[184:187], v[48:51]
	v_mfma_f32_16x16x32_bf16 v[40:43], v[144:147], v[192:195], v[40:43]
	v_mfma_f32_16x16x32_bf16 v[32:35], v[160:163], v[192:195], v[32:35]
	v_mfma_f32_16x16x32_bf16 v[24:27], v[144:147], v[200:203], v[24:27]
	v_mfma_f32_16x16x32_bf16 v[16:19], v[160:163], v[200:203], v[16:19]
	v_mfma_f32_16x16x32_bf16 v[8:11], v[144:147], v[208:211], v[8:11]
	v_mfma_f32_16x16x32_bf16 v[0:3], v[160:163], v[208:211], v[0:3]
	v_mfma_f32_16x16x32_bf16 v[56:59], v[156:159], v[188:191], v[56:59]
	v_mfma_f32_16x16x32_bf16 v[48:51], v[164:167], v[188:191], v[48:51]
	v_mfma_f32_16x16x32_bf16 v[40:43], v[156:159], v[196:199], v[40:43]
	v_mfma_f32_16x16x32_bf16 v[32:35], v[164:167], v[196:199], v[32:35]
	v_mfma_f32_16x16x32_bf16 v[24:27], v[156:159], v[204:207], v[24:27]
	v_mfma_f32_16x16x32_bf16 v[16:19], v[164:167], v[204:207], v[16:19]
	v_mfma_f32_16x16x32_bf16 v[8:11], v[156:159], v[212:215], v[8:11]
	v_mfma_f32_16x16x32_bf16 v[0:3], v[164:167], v[212:215], v[0:3]
	s_setprio 0
	s_setprio 1
	v_mfma_f32_16x16x32_bf16 v[60:63], v[168:171], v[184:187], v[60:63]
	v_mfma_f32_16x16x32_bf16 v[52:55], v[176:179], v[184:187], v[52:55]
	v_mfma_f32_16x16x32_bf16 v[44:47], v[168:171], v[192:195], v[44:47]
	v_mfma_f32_16x16x32_bf16 v[36:39], v[176:179], v[192:195], v[36:39]
	v_mfma_f32_16x16x32_bf16 v[28:31], v[168:171], v[200:203], v[28:31]
	v_mfma_f32_16x16x32_bf16 v[20:23], v[176:179], v[200:203], v[20:23]
	v_mfma_f32_16x16x32_bf16 v[12:15], v[168:171], v[208:211], v[12:15]
	v_mfma_f32_16x16x32_bf16 v[4:7], v[176:179], v[208:211], v[4:7]
	v_mfma_f32_16x16x32_bf16 v[60:63], v[172:175], v[188:191], v[60:63]
	v_mfma_f32_16x16x32_bf16 v[52:55], v[180:183], v[188:191], v[52:55]
	v_mfma_f32_16x16x32_bf16 v[44:47], v[172:175], v[196:199], v[44:47]
	v_mfma_f32_16x16x32_bf16 v[36:39], v[180:183], v[196:199], v[36:39]
	v_mfma_f32_16x16x32_bf16 v[28:31], v[172:175], v[204:207], v[28:31]
	v_mfma_f32_16x16x32_bf16 v[20:23], v[180:183], v[204:207], v[20:23]
	v_mfma_f32_16x16x32_bf16 v[12:15], v[172:175], v[212:215], v[12:15]
	v_mfma_f32_16x16x32_bf16 v[4:7], v[180:183], v[212:215], v[4:7]
	s_setprio 0
	s_barrier
	s_add_i32 s69, 0, 0x18000
	v_add_u32_e32 v155, s69, v149
	s_add_i32 s70, 0, 0x1c000
	ds_read_b128 v[144:147], v155
	ds_read_b128 v[156:159], v155 offset:1024
	ds_read_b128 v[160:163], v155 offset:2048
	ds_read_b128 v[164:167], v155 offset:3072
	v_add_u32_e32 v155, s70, v149
	ds_read_b128 v[168:171], v155
	ds_read_b128 v[172:175], v155 offset:1024
	ds_read_b128 v[176:179], v155 offset:2048
	ds_read_b128 v[180:183], v155 offset:3072
	s_add_u32 s56, s56, 0x80000
	s_addc_u32 s57, s57, 0
	s_mov_b32 m0, s51
	v_lshl_add_u64 v[224:225], s[56:57], 0, v[128:129]
	ds_read_b128 v[184:187], v153 offset:32768
	ds_read_b128 v[188:191], v153 offset:33792
	ds_read_b128 v[192:195], v153 offset:34816
	ds_read_b128 v[196:199], v153 offset:35840
	ds_read_b128 v[200:203], v153 offset:36864
	ds_read_b128 v[204:207], v153 offset:37888
	ds_read_b128 v[208:211], v153 offset:38912
	ds_read_b128 v[212:215], v153 offset:39936
	global_load_lds_dwordx4 v[224:225], off
	v_lshl_add_u64 v[224:225], s[56:57], 0, v[132:133]
	s_mov_b32 m0, s60
	s_nop 0
	global_load_lds_dwordx4 v[224:225], off
	s_waitcnt vmcnt(8)
	s_waitcnt lgkmcnt(0)
	s_barrier
	s_setprio 1
	s_waitcnt lgkmcnt(0)
	v_mfma_f32_16x16x32_bf16 v[116:119], v[144:147], v[184:187], v[116:119]
	v_mfma_f32_16x16x32_bf16 v[112:115], v[160:163], v[184:187], v[112:115]
	v_mfma_f32_16x16x32_bf16 v[104:107], v[144:147], v[192:195], v[104:107]
	v_mfma_f32_16x16x32_bf16 v[96:99], v[160:163], v[192:195], v[96:99]
	v_mfma_f32_16x16x32_bf16 v[88:91], v[144:147], v[200:203], v[88:91]
	v_mfma_f32_16x16x32_bf16 v[80:83], v[160:163], v[200:203], v[80:83]
	v_mfma_f32_16x16x32_bf16 v[72:75], v[144:147], v[208:211], v[72:75]
	v_mfma_f32_16x16x32_bf16 v[64:67], v[160:163], v[208:211], v[64:67]
	v_mfma_f32_16x16x32_bf16 v[116:119], v[156:159], v[188:191], v[116:119]
	v_mfma_f32_16x16x32_bf16 v[112:115], v[164:167], v[188:191], v[112:115]
	v_mfma_f32_16x16x32_bf16 v[104:107], v[156:159], v[196:199], v[104:107]
	v_mfma_f32_16x16x32_bf16 v[96:99], v[164:167], v[196:199], v[96:99]
	v_mfma_f32_16x16x32_bf16 v[88:91], v[156:159], v[204:207], v[88:91]
	v_mfma_f32_16x16x32_bf16 v[80:83], v[164:167], v[204:207], v[80:83]
	v_mfma_f32_16x16x32_bf16 v[72:75], v[156:159], v[212:215], v[72:75]
	v_mfma_f32_16x16x32_bf16 v[64:67], v[164:167], v[212:215], v[64:67]
	s_setprio 0
	s_setprio 1
	v_mfma_f32_16x16x32_bf16 v[124:127], v[168:171], v[184:187], v[124:127]
	v_mfma_f32_16x16x32_bf16 v[120:123], v[176:179], v[184:187], v[120:123]
	v_mfma_f32_16x16x32_bf16 v[108:111], v[168:171], v[192:195], v[108:111]
	v_mfma_f32_16x16x32_bf16 v[100:103], v[176:179], v[192:195], v[100:103]
	v_mfma_f32_16x16x32_bf16 v[92:95], v[168:171], v[200:203], v[92:95]
	v_mfma_f32_16x16x32_bf16 v[84:87], v[176:179], v[200:203], v[84:87]
	v_mfma_f32_16x16x32_bf16 v[76:79], v[168:171], v[208:211], v[76:79]
	v_mfma_f32_16x16x32_bf16 v[68:71], v[176:179], v[208:211], v[68:71]
	v_mfma_f32_16x16x32_bf16 v[124:127], v[172:175], v[188:191], v[124:127]
	v_mfma_f32_16x16x32_bf16 v[120:123], v[180:183], v[188:191], v[120:123]
	v_mfma_f32_16x16x32_bf16 v[108:111], v[172:175], v[196:199], v[108:111]
	v_mfma_f32_16x16x32_bf16 v[100:103], v[180:183], v[196:199], v[100:103]
	v_mfma_f32_16x16x32_bf16 v[92:95], v[172:175], v[204:207], v[92:95]
	v_mfma_f32_16x16x32_bf16 v[84:87], v[180:183], v[204:207], v[84:87]
	v_mfma_f32_16x16x32_bf16 v[76:79], v[172:175], v[212:215], v[76:79]
	v_mfma_f32_16x16x32_bf16 v[68:71], v[180:183], v[212:215], v[68:71]
	s_setprio 0
	s_barrier
	s_add_i32 s56, s69, s58
	v_lshl_add_u64 v[216:217], v[216:217], 0, s[20:21]
	s_mov_b32 m0, s56
	ds_read_b128 v[184:187], v153 offset:49152
	ds_read_b128 v[188:191], v153 offset:50176
	ds_read_b128 v[192:195], v153 offset:51200
	ds_read_b128 v[196:199], v153 offset:52224
	ds_read_b128 v[200:203], v153 offset:53248
	ds_read_b128 v[204:207], v153 offset:54272
	ds_read_b128 v[208:211], v153 offset:55296
	ds_read_b128 v[212:215], v153 offset:56320
	global_load_lds_dwordx4 v[216:217], off
	s_add_i32 m0, s56, 0x2000
	s_add_u32 s54, s54, 0x80080
	v_lshl_add_u64 v[216:217], v[218:219], 0, s[20:21]
	s_addc_u32 s55, s55, 0
	s_add_i32 s56, s70, s58
	global_load_lds_dwordx4 v[216:217], off
	v_lshl_add_u64 v[216:217], s[54:55], 0, v[130:131]
	s_mov_b32 m0, s56
	s_nop 0
	global_load_lds_dwordx4 v[216:217], off
	v_lshl_add_u64 v[216:217], s[54:55], 0, v[134:135]
	s_add_i32 m0, s56, 0x2000
	s_nop 0
	global_load_lds_dwordx4 v[216:217], off
	s_waitcnt vmcnt(6)
	s_waitcnt lgkmcnt(0)
	s_barrier
	v_lshl_add_u64 v[216:217], v[220:221], 0, s[20:21]
	s_mov_b32 m0, s62
	s_nop 0
	global_load_lds_dwordx4 v[216:217], off
	v_lshl_add_u64 v[216:217], v[222:223], 0, s[20:21]
	s_mov_b32 m0, s63
	s_nop 0
	global_load_lds_dwordx4 v[216:217], off
	s_setprio 1
	s_waitcnt lgkmcnt(0)
	v_mfma_f32_16x16x32_bf16 v[56:59], v[144:147], v[184:187], v[56:59]
	v_mfma_f32_16x16x32_bf16 v[48:51], v[160:163], v[184:187], v[48:51]
	v_mfma_f32_16x16x32_bf16 v[40:43], v[144:147], v[192:195], v[40:43]
	v_mfma_f32_16x16x32_bf16 v[32:35], v[160:163], v[192:195], v[32:35]
	v_mfma_f32_16x16x32_bf16 v[24:27], v[144:147], v[200:203], v[24:27]
	v_mfma_f32_16x16x32_bf16 v[16:19], v[160:163], v[200:203], v[16:19]
	v_mfma_f32_16x16x32_bf16 v[8:11], v[144:147], v[208:211], v[8:11]
	v_mfma_f32_16x16x32_bf16 v[0:3], v[160:163], v[208:211], v[0:3]
	v_mfma_f32_16x16x32_bf16 v[56:59], v[156:159], v[188:191], v[56:59]
	v_mfma_f32_16x16x32_bf16 v[48:51], v[164:167], v[188:191], v[48:51]
	v_mfma_f32_16x16x32_bf16 v[40:43], v[156:159], v[196:199], v[40:43]
	v_mfma_f32_16x16x32_bf16 v[32:35], v[164:167], v[196:199], v[32:35]
	v_mfma_f32_16x16x32_bf16 v[24:27], v[156:159], v[204:207], v[24:27]
	v_mfma_f32_16x16x32_bf16 v[16:19], v[164:167], v[204:207], v[16:19]
	v_mfma_f32_16x16x32_bf16 v[8:11], v[156:159], v[212:215], v[8:11]
	v_mfma_f32_16x16x32_bf16 v[0:3], v[164:167], v[212:215], v[0:3]
	s_setprio 0
	s_setprio 1
	v_mfma_f32_16x16x32_bf16 v[60:63], v[168:171], v[184:187], v[60:63]
	v_mfma_f32_16x16x32_bf16 v[52:55], v[176:179], v[184:187], v[52:55]
	v_mfma_f32_16x16x32_bf16 v[44:47], v[168:171], v[192:195], v[44:47]
	v_mfma_f32_16x16x32_bf16 v[36:39], v[176:179], v[192:195], v[36:39]
	v_mfma_f32_16x16x32_bf16 v[28:31], v[168:171], v[200:203], v[28:31]
	v_mfma_f32_16x16x32_bf16 v[20:23], v[176:179], v[200:203], v[20:23]
	v_mfma_f32_16x16x32_bf16 v[12:15], v[168:171], v[208:211], v[12:15]
	v_mfma_f32_16x16x32_bf16 v[4:7], v[176:179], v[208:211], v[4:7]
	v_mfma_f32_16x16x32_bf16 v[60:63], v[172:175], v[188:191], v[60:63]
	v_mfma_f32_16x16x32_bf16 v[52:55], v[180:183], v[188:191], v[52:55]
	v_mfma_f32_16x16x32_bf16 v[44:47], v[172:175], v[196:199], v[44:47]
	v_mfma_f32_16x16x32_bf16 v[36:39], v[180:183], v[196:199], v[36:39]
	v_mfma_f32_16x16x32_bf16 v[28:31], v[172:175], v[204:207], v[28:31]
	v_mfma_f32_16x16x32_bf16 v[20:23], v[180:183], v[204:207], v[20:23]
	v_mfma_f32_16x16x32_bf16 v[12:15], v[172:175], v[212:215], v[12:15]
	v_mfma_f32_16x16x32_bf16 v[4:7], v[180:183], v[212:215], v[4:7]
	s_setprio 0
	s_barrier
	s_add_i32 s68, s68, 2
	s_add_u32 s47, s47, 0x100
	s_addc_u32 s67, s67, 0
	s_add_u32 s52, s52, 0x100
	s_addc_u32 s53, s53, 0
	s_cmp_gt_u32 s68, 29
	s_cbranch_scc0 .LBB0_952
	s_and_b64 vcc, exec, s[22:23]
	s_cbranch_vccz .LBB0_955
	s_barrier

.LBB0_1049:
	ds_read_b128 v[148:151], v222
	ds_read_b128 v[152:155], v222 offset:1024
	ds_read_b128 v[156:159], v222 offset:2048
	ds_read_b128 v[160:163], v222 offset:3072
	ds_read_b128 v[132:135], v223
	ds_read_b128 v[136:139], v223 offset:1024
	ds_read_b128 v[140:143], v223 offset:2048
	ds_read_b128 v[144:147], v223 offset:3072
	s_add_u32 s8, s48, 0xfff80080
	s_addc_u32 s9, s49, -1
	s_cmp_eq_u32 s81, 28
	s_cselect_b32 s53, s23, s9
	s_cselect_b32 s52, s46, s8
	s_cselect_b32 s51, s21, s80
	s_cselect_b32 s50, s47, s79
	v_lshl_add_u64 v[2:3], s[48:49], 0, v[208:209]
	s_add_i32 m0, s35, 0xc000
	s_waitcnt lgkmcnt(0)
	ds_read_b128 v[164:167], v224
	ds_read_b128 v[168:171], v224 offset:1024
	ds_read_b128 v[172:175], v224 offset:2048
	ds_read_b128 v[176:179], v224 offset:3072
	ds_read_b128 v[180:183], v224 offset:4096
	ds_read_b128 v[184:187], v224 offset:5120
	ds_read_b128 v[188:191], v224 offset:6144
	ds_read_b128 v[192:195], v224 offset:7168
	global_load_lds_dwordx4 v[2:3], off
	v_lshl_add_u64 v[2:3], s[48:49], 0, v[206:207]
	s_add_i32 m0, s35, 0xe000
	s_nop 0
	global_load_lds_dwordx4 v[2:3], off
	s_waitcnt vmcnt(8)
	s_waitcnt lgkmcnt(0)
	s_barrier
	s_setprio 1
	s_waitcnt lgkmcnt(0)
	v_mfma_f32_16x16x32_bf16 v[124:127], v[148:151], v[164:167], v[124:127]
	v_mfma_f32_16x16x32_bf16 v[120:123], v[156:159], v[164:167], v[120:123]
	v_mfma_f32_16x16x32_bf16 v[104:107], v[148:151], v[172:175], v[104:107]
	v_mfma_f32_16x16x32_bf16 v[100:103], v[156:159], v[172:175], v[100:103]
	v_mfma_f32_16x16x32_bf16 v[88:91], v[148:151], v[180:183], v[88:91]
	v_mfma_f32_16x16x32_bf16 v[84:87], v[156:159], v[180:183], v[84:87]
	v_mfma_f32_16x16x32_bf16 v[76:79], v[148:151], v[188:191], v[76:79]
	v_mfma_f32_16x16x32_bf16 v[72:75], v[156:159], v[188:191], v[72:75]
	v_mfma_f32_16x16x32_bf16 v[124:127], v[152:155], v[168:171], v[124:127]
	v_mfma_f32_16x16x32_bf16 v[120:123], v[160:163], v[168:171], v[120:123]
	v_mfma_f32_16x16x32_bf16 v[104:107], v[152:155], v[176:179], v[104:107]
	v_mfma_f32_16x16x32_bf16 v[100:103], v[160:163], v[176:179], v[100:103]
	v_mfma_f32_16x16x32_bf16 v[88:91], v[152:155], v[184:187], v[88:91]
	v_mfma_f32_16x16x32_bf16 v[84:87], v[160:163], v[184:187], v[84:87]
	v_mfma_f32_16x16x32_bf16 v[76:79], v[152:155], v[192:195], v[76:79]
	v_mfma_f32_16x16x32_bf16 v[72:75], v[160:163], v[192:195], v[72:75]
	s_setprio 0
	s_setprio 1
	v_mfma_f32_16x16x32_bf16 v[128:131], v[132:135], v[164:167], v[128:131]
	v_mfma_f32_16x16x32_bf16 v[116:119], v[140:143], v[164:167], v[116:119]
	v_mfma_f32_16x16x32_bf16 v[112:115], v[132:135], v[172:175], v[112:115]
	v_mfma_f32_16x16x32_bf16 v[108:111], v[140:143], v[172:175], v[108:111]
	v_mfma_f32_16x16x32_bf16 v[96:99], v[132:135], v[180:183], v[96:99]
	v_mfma_f32_16x16x32_bf16 v[92:95], v[140:143], v[180:183], v[92:95]
	v_mfma_f32_16x16x32_bf16 v[80:83], v[132:135], v[188:191], v[80:83]
	v_mfma_f32_16x16x32_bf16 v[68:71], v[140:143], v[188:191], v[68:71]
	v_mfma_f32_16x16x32_bf16 v[128:131], v[136:139], v[168:171], v[128:131]
	v_mfma_f32_16x16x32_bf16 v[116:119], v[144:147], v[168:171], v[116:119]
	v_mfma_f32_16x16x32_bf16 v[112:115], v[136:139], v[176:179], v[112:115]
	v_mfma_f32_16x16x32_bf16 v[108:111], v[144:147], v[176:179], v[108:111]
	v_mfma_f32_16x16x32_bf16 v[96:99], v[136:139], v[184:187], v[96:99]
	v_mfma_f32_16x16x32_bf16 v[92:95], v[144:147], v[184:187], v[92:95]
	v_mfma_f32_16x16x32_bf16 v[80:83], v[136:139], v[192:195], v[80:83]
	v_mfma_f32_16x16x32_bf16 v[68:71], v[144:147], v[192:195], v[68:71]
	s_setprio 0
	s_barrier
	s_add_i32 s8, s65, s56
	v_lshl_add_u64 v[2:3], s[50:51], 0, v[198:199]
	s_mov_b32 m0, s8
	ds_read_b128 v[188:191], v224 offset:16384
	ds_read_b128 v[192:195], v224 offset:17408
	ds_read_b128 v[180:183], v224 offset:18432
	ds_read_b128 v[184:187], v224 offset:19456
	ds_read_b128 v[172:175], v224 offset:20480
	ds_read_b128 v[176:179], v224 offset:21504
	ds_read_b128 v[164:167], v224 offset:22528
	ds_read_b128 v[168:171], v224 offset:23552
	global_load_lds_dwordx4 v[2:3], off
	s_add_i32 m0, s8, 0x2000
	s_add_u32 s8, s50, 0x80000
	v_lshl_add_u64 v[212:213], s[50:51], 0, v[202:203]
	s_addc_u32 s9, s51, 0
	s_add_i32 s78, s66, s56
	global_load_lds_dwordx4 v[212:213], off
	v_lshl_add_u64 v[214:215], s[8:9], 0, v[198:199]
	s_mov_b32 m0, s78
	v_lshl_add_u64 v[216:217], s[52:53], 0, v[200:201]
	global_load_lds_dwordx4 v[214:215], off
	v_lshl_add_u64 v[214:215], s[8:9], 0, v[202:203]
	s_add_i32 m0, s78, 0x2000
	v_cmp_ne_u32_e64 s[8:9], 1, v227
	global_load_lds_dwordx4 v[214:215], off
	s_andn2_b64 vcc, exec, s[36:37]
	s_waitcnt vmcnt(6)
	s_waitcnt lgkmcnt(0)
	s_barrier
	v_lshl_add_u64 v[214:215], s[52:53], 0, v[196:197]
	s_mov_b32 m0, s35
	s_nop 0
	global_load_lds_dwordx4 v[214:215], off
	s_mov_b32 m0, s58
	s_nop 0
	global_load_lds_dwordx4 v[216:217], off
	s_cbranch_vccnz .LBB0_1051
	s_setprio 1
	s_waitcnt lgkmcnt(0)
	v_mfma_f32_16x16x32_bf16 v[56:59], v[148:151], v[188:191], v[56:59]
	v_mfma_f32_16x16x32_bf16 v[52:55], v[156:159], v[188:191], v[52:55]
	v_mfma_f32_16x16x32_bf16 v[40:43], v[148:151], v[180:183], v[40:43]
	v_mfma_f32_16x16x32_bf16 v[36:39], v[156:159], v[180:183], v[36:39]
	v_mfma_f32_16x16x32_bf16 v[24:27], v[148:151], v[172:175], v[24:27]
	v_mfma_f32_16x16x32_bf16 v[20:23], v[156:159], v[172:175], v[20:23]
	v_mfma_f32_16x16x32_bf16 v[8:11], v[148:151], v[164:167], v[8:11]
	v_mfma_f32_16x16x32_bf16 v[4:7], v[156:159], v[164:167], v[4:7]
	v_mfma_f32_16x16x32_bf16 v[56:59], v[152:155], v[192:195], v[56:59]
	v_mfma_f32_16x16x32_bf16 v[52:55], v[160:163], v[192:195], v[52:55]
	v_mfma_f32_16x16x32_bf16 v[40:43], v[152:155], v[184:187], v[40:43]
	v_mfma_f32_16x16x32_bf16 v[36:39], v[160:163], v[184:187], v[36:39]
	v_mfma_f32_16x16x32_bf16 v[24:27], v[152:155], v[176:179], v[24:27]
	v_mfma_f32_16x16x32_bf16 v[20:23], v[160:163], v[176:179], v[20:23]
	v_mfma_f32_16x16x32_bf16 v[8:11], v[152:155], v[168:171], v[8:11]
	v_mfma_f32_16x16x32_bf16 v[4:7], v[160:163], v[168:171], v[4:7]
	s_setprio 0
	s_setprio 1
	v_mfma_f32_16x16x32_bf16 v[64:67], v[132:135], v[188:191], v[64:67]
	v_mfma_f32_16x16x32_bf16 v[60:63], v[140:143], v[188:191], v[60:63]
	v_mfma_f32_16x16x32_bf16 v[48:51], v[132:135], v[180:183], v[48:51]
	v_mfma_f32_16x16x32_bf16 v[44:47], v[140:143], v[180:183], v[44:47]
	v_mfma_f32_16x16x32_bf16 v[32:35], v[132:135], v[172:175], v[32:35]
	v_mfma_f32_16x16x32_bf16 v[28:31], v[140:143], v[172:175], v[28:31]
	v_mfma_f32_16x16x32_bf16 v[16:19], v[132:135], v[164:167], v[16:19]
	v_mfma_f32_16x16x32_bf16 v[12:15], v[140:143], v[164:167], v[12:15]
	v_mfma_f32_16x16x32_bf16 v[64:67], v[136:139], v[192:195], v[64:67]
	v_mfma_f32_16x16x32_bf16 v[60:63], v[144:147], v[192:195], v[60:63]
	v_mfma_f32_16x16x32_bf16 v[48:51], v[136:139], v[184:187], v[48:51]
	v_mfma_f32_16x16x32_bf16 v[44:47], v[144:147], v[184:187], v[44:47]
	v_mfma_f32_16x16x32_bf16 v[32:35], v[136:139], v[176:179], v[32:35]
	v_mfma_f32_16x16x32_bf16 v[28:31], v[144:147], v[176:179], v[28:31]
	v_mfma_f32_16x16x32_bf16 v[16:19], v[136:139], v[168:171], v[16:19]
	v_mfma_f32_16x16x32_bf16 v[12:15], v[144:147], v[168:171], v[12:15]
	s_setprio 0
.LBB0_1051:
	s_barrier
	s_add_i32 s78, 0, 0x18000
	v_add_u32_e32 v1, s78, v220
	s_add_i32 s82, 0, 0x1c000
	ds_read_b128 v[148:151], v1
	ds_read_b128 v[152:155], v1 offset:1024
	ds_read_b128 v[156:159], v1 offset:2048
	ds_read_b128 v[160:163], v1 offset:3072
	v_add_u32_e32 v1, s82, v220
	ds_read_b128 v[132:135], v1
	ds_read_b128 v[136:139], v1 offset:1024
	ds_read_b128 v[140:143], v1 offset:2048
	ds_read_b128 v[144:147], v1 offset:3072
	s_add_u32 s52, s52, 0x80000
	s_addc_u32 s53, s53, 0
	s_mov_b32 m0, s59
	v_lshl_add_u64 v[228:229], s[52:53], 0, v[196:197]
	s_waitcnt lgkmcnt(0)
	ds_read_b128 v[164:167], v224 offset:32768
	ds_read_b128 v[168:171], v224 offset:33792
	ds_read_b128 v[172:175], v224 offset:34816
	ds_read_b128 v[176:179], v224 offset:35840
	ds_read_b128 v[180:183], v224 offset:36864
	ds_read_b128 v[184:187], v224 offset:37888
	ds_read_b128 v[188:191], v224 offset:38912
	ds_read_b128 v[192:195], v224 offset:39936
	global_load_lds_dwordx4 v[228:229], off
	v_lshl_add_u64 v[228:229], s[52:53], 0, v[200:201]
	s_mov_b32 m0, s60
	s_nop 0
	global_load_lds_dwordx4 v[228:229], off
	s_waitcnt vmcnt(8)
	s_waitcnt lgkmcnt(0)
	s_barrier
	s_setprio 1
	s_waitcnt lgkmcnt(0)
	v_mfma_f32_16x16x32_bf16 v[124:127], v[148:151], v[164:167], v[124:127]
	v_mfma_f32_16x16x32_bf16 v[120:123], v[156:159], v[164:167], v[120:123]
	v_mfma_f32_16x16x32_bf16 v[104:107], v[148:151], v[172:175], v[104:107]
	v_mfma_f32_16x16x32_bf16 v[100:103], v[156:159], v[172:175], v[100:103]
	v_mfma_f32_16x16x32_bf16 v[88:91], v[148:151], v[180:183], v[88:91]
	v_mfma_f32_16x16x32_bf16 v[84:87], v[156:159], v[180:183], v[84:87]
	v_mfma_f32_16x16x32_bf16 v[76:79], v[148:151], v[188:191], v[76:79]
	v_mfma_f32_16x16x32_bf16 v[72:75], v[156:159], v[188:191], v[72:75]
	v_mfma_f32_16x16x32_bf16 v[124:127], v[152:155], v[168:171], v[124:127]
	v_mfma_f32_16x16x32_bf16 v[120:123], v[160:163], v[168:171], v[120:123]
	v_mfma_f32_16x16x32_bf16 v[104:107], v[152:155], v[176:179], v[104:107]
	v_mfma_f32_16x16x32_bf16 v[100:103], v[160:163], v[176:179], v[100:103]
	v_mfma_f32_16x16x32_bf16 v[88:91], v[152:155], v[184:187], v[88:91]
	v_mfma_f32_16x16x32_bf16 v[84:87], v[160:163], v[184:187], v[84:87]
	v_mfma_f32_16x16x32_bf16 v[76:79], v[152:155], v[192:195], v[76:79]
	v_mfma_f32_16x16x32_bf16 v[72:75], v[160:163], v[192:195], v[72:75]
	s_setprio 0
	s_setprio 1
	v_mfma_f32_16x16x32_bf16 v[128:131], v[132:135], v[164:167], v[128:131]
	v_mfma_f32_16x16x32_bf16 v[116:119], v[140:143], v[164:167], v[116:119]
	v_mfma_f32_16x16x32_bf16 v[112:115], v[132:135], v[172:175], v[112:115]
	v_mfma_f32_16x16x32_bf16 v[108:111], v[140:143], v[172:175], v[108:111]
	v_mfma_f32_16x16x32_bf16 v[96:99], v[132:135], v[180:183], v[96:99]
	v_mfma_f32_16x16x32_bf16 v[92:95], v[140:143], v[180:183], v[92:95]
	v_mfma_f32_16x16x32_bf16 v[80:83], v[132:135], v[188:191], v[80:83]
	v_mfma_f32_16x16x32_bf16 v[68:71], v[140:143], v[188:191], v[68:71]
	v_mfma_f32_16x16x32_bf16 v[128:131], v[136:139], v[168:171], v[128:131]
	v_mfma_f32_16x16x32_bf16 v[116:119], v[144:147], v[168:171], v[116:119]
	v_mfma_f32_16x16x32_bf16 v[112:115], v[136:139], v[176:179], v[112:115]
	v_mfma_f32_16x16x32_bf16 v[108:111], v[144:147], v[176:179], v[108:111]
	v_mfma_f32_16x16x32_bf16 v[96:99], v[136:139], v[184:187], v[96:99]
	v_mfma_f32_16x16x32_bf16 v[92:95], v[144:147], v[184:187], v[92:95]
	v_mfma_f32_16x16x32_bf16 v[80:83], v[136:139], v[192:195], v[80:83]
	v_mfma_f32_16x16x32_bf16 v[68:71], v[144:147], v[192:195], v[68:71]
	s_setprio 0
	s_barrier
	s_add_i32 s52, s78, s56
	v_lshl_add_u64 v[2:3], v[2:3], 0, s[14:15]
	s_mov_b32 m0, s52
	ds_read_b128 v[188:191], v224 offset:49152
	ds_read_b128 v[192:195], v224 offset:50176
	ds_read_b128 v[180:183], v224 offset:51200
	ds_read_b128 v[184:187], v224 offset:52224
	ds_read_b128 v[172:175], v224 offset:53248
	ds_read_b128 v[176:179], v224 offset:54272
	ds_read_b128 v[164:167], v224 offset:55296
	ds_read_b128 v[168:171], v224 offset:56320
	global_load_lds_dwordx4 v[2:3], off
	s_add_i32 m0, s52, 0x2000
	s_add_u32 s50, s50, 0x80080
	v_lshl_add_u64 v[2:3], v[212:213], 0, s[14:15]
	s_addc_u32 s51, s51, 0
	s_add_i32 s52, s82, s56
	global_load_lds_dwordx4 v[2:3], off
	v_lshl_add_u64 v[2:3], s[50:51], 0, v[198:199]
	s_mov_b32 m0, s52
	s_and_b64 vcc, exec, s[8:9]
	global_load_lds_dwordx4 v[2:3], off
	v_lshl_add_u64 v[2:3], s[50:51], 0, v[202:203]
	s_add_i32 m0, s52, 0x2000
	s_nop 0
	global_load_lds_dwordx4 v[2:3], off
	s_waitcnt vmcnt(6)
	s_waitcnt lgkmcnt(0)
	s_barrier
	v_lshl_add_u64 v[2:3], v[214:215], 0, s[14:15]
	s_mov_b32 m0, s61
	s_nop 0
	global_load_lds_dwordx4 v[2:3], off
	v_lshl_add_u64 v[2:3], v[216:217], 0, s[14:15]
	s_mov_b32 m0, s62
	s_nop 0
	global_load_lds_dwordx4 v[2:3], off
	s_cbranch_vccnz .LBB0_1048
	s_setprio 1
	s_waitcnt lgkmcnt(0)
	v_mfma_f32_16x16x32_bf16 v[56:59], v[148:151], v[188:191], v[56:59]
	v_mfma_f32_16x16x32_bf16 v[52:55], v[156:159], v[188:191], v[52:55]
	v_mfma_f32_16x16x32_bf16 v[40:43], v[148:151], v[180:183], v[40:43]
	v_mfma_f32_16x16x32_bf16 v[36:39], v[156:159], v[180:183], v[36:39]
	v_mfma_f32_16x16x32_bf16 v[24:27], v[148:151], v[172:175], v[24:27]
	v_mfma_f32_16x16x32_bf16 v[20:23], v[156:159], v[172:175], v[20:23]
	v_mfma_f32_16x16x32_bf16 v[8:11], v[148:151], v[164:167], v[8:11]
	v_mfma_f32_16x16x32_bf16 v[2:5], v[156:159], v[164:167], v[4:7]
	v_mfma_f32_16x16x32_bf16 v[56:59], v[152:155], v[192:195], v[56:59]
	v_mfma_f32_16x16x32_bf16 v[52:55], v[160:163], v[192:195], v[52:55]
	v_mfma_f32_16x16x32_bf16 v[40:43], v[152:155], v[184:187], v[40:43]
	v_mfma_f32_16x16x32_bf16 v[36:39], v[160:163], v[184:187], v[36:39]
	v_mfma_f32_16x16x32_bf16 v[24:27], v[152:155], v[176:179], v[24:27]
	v_mfma_f32_16x16x32_bf16 v[20:23], v[160:163], v[176:179], v[20:23]
	v_mfma_f32_16x16x32_bf16 v[8:11], v[152:155], v[168:171], v[8:11]
	v_mfma_f32_16x16x32_bf16 v[4:7], v[160:163], v[168:171], v[2:5]
	s_setprio 0
	s_setprio 1
	v_mfma_f32_16x16x32_bf16 v[64:67], v[132:135], v[188:191], v[64:67]
	v_mfma_f32_16x16x32_bf16 v[60:63], v[140:143], v[188:191], v[60:63]
	v_mfma_f32_16x16x32_bf16 v[48:51], v[132:135], v[180:183], v[48:51]
	v_mfma_f32_16x16x32_bf16 v[44:47], v[140:143], v[180:183], v[44:47]
	v_mfma_f32_16x16x32_bf16 v[32:35], v[132:135], v[172:175], v[32:35]
	v_mfma_f32_16x16x32_bf16 v[28:31], v[140:143], v[172:175], v[28:31]
	v_mfma_f32_16x16x32_bf16 v[16:19], v[132:135], v[164:167], v[16:19]
	v_mfma_f32_16x16x32_bf16 v[12:15], v[140:143], v[164:167], v[12:15]
	v_mfma_f32_16x16x32_bf16 v[64:67], v[136:139], v[192:195], v[64:67]
	v_mfma_f32_16x16x32_bf16 v[60:63], v[144:147], v[192:195], v[60:63]
	v_mfma_f32_16x16x32_bf16 v[48:51], v[136:139], v[184:187], v[48:51]
	v_mfma_f32_16x16x32_bf16 v[44:47], v[144:147], v[184:187], v[44:47]
	v_mfma_f32_16x16x32_bf16 v[32:35], v[136:139], v[176:179], v[32:35]
	v_mfma_f32_16x16x32_bf16 v[28:31], v[144:147], v[176:179], v[28:31]
	v_mfma_f32_16x16x32_bf16 v[16:19], v[136:139], v[168:171], v[16:19]
	v_mfma_f32_16x16x32_bf16 v[12:15], v[144:147], v[168:171], v[12:15]
	s_setprio 0
	s_branch .LBB0_1048

.LBB0_1137:
	ds_read_b128 v[144:147], v151
	ds_read_b128 v[156:159], v151 offset:1024
	ds_read_b128 v[160:163], v151 offset:2048
	ds_read_b128 v[164:167], v151 offset:3072
	ds_read_b128 v[168:171], v152
	ds_read_b128 v[172:175], v152 offset:1024
	ds_read_b128 v[176:179], v152 offset:2048
	ds_read_b128 v[180:183], v152 offset:3072
	s_add_u32 s34, s30, 0x100
	s_addc_u32 s35, s31, 0
	s_cmpk_eq_i32 s66, 0x54
	s_cselect_b32 s49, s11, s35
	s_cselect_b32 s48, s10, s34
	s_cselect_b32 s37, s27, s47
	s_cselect_b32 s36, s26, s46
	v_lshl_add_u64 v[216:217], s[30:31], 0, v[138:139]
	s_add_i32 m0, s53, 0xc000
	ds_read_b128 v[184:187], v153
	ds_read_b128 v[188:191], v153 offset:1024
	ds_read_b128 v[192:195], v153 offset:2048
	ds_read_b128 v[196:199], v153 offset:3072
	ds_read_b128 v[200:203], v153 offset:4096
	ds_read_b128 v[204:207], v153 offset:5120
	ds_read_b128 v[208:211], v153 offset:6144
	ds_read_b128 v[212:215], v153 offset:7168
	global_load_lds_dwordx4 v[216:217], off
	v_lshl_add_u64 v[216:217], s[30:31], 0, v[136:137]
	s_add_i32 m0, s53, 0xe000
	s_nop 0
	global_load_lds_dwordx4 v[216:217], off
	s_waitcnt vmcnt(8)
	s_waitcnt lgkmcnt(0)
	s_barrier
	s_setprio 1
	s_waitcnt lgkmcnt(0)
	v_mfma_f32_16x16x32_bf16 v[124:127], v[144:147], v[184:187], v[124:127]
	v_mfma_f32_16x16x32_bf16 v[120:123], v[160:163], v[184:187], v[120:123]
	v_mfma_f32_16x16x32_bf16 v[108:111], v[144:147], v[192:195], v[108:111]
	v_mfma_f32_16x16x32_bf16 v[104:107], v[160:163], v[192:195], v[104:107]
	v_mfma_f32_16x16x32_bf16 v[92:95], v[144:147], v[200:203], v[92:95]
	v_mfma_f32_16x16x32_bf16 v[88:91], v[160:163], v[200:203], v[88:91]
	v_mfma_f32_16x16x32_bf16 v[76:79], v[144:147], v[208:211], v[76:79]
	v_mfma_f32_16x16x32_bf16 v[72:75], v[160:163], v[208:211], v[72:75]
	v_mfma_f32_16x16x32_bf16 v[124:127], v[156:159], v[188:191], v[124:127]
	v_mfma_f32_16x16x32_bf16 v[120:123], v[164:167], v[188:191], v[120:123]
	v_mfma_f32_16x16x32_bf16 v[108:111], v[156:159], v[196:199], v[108:111]
	v_mfma_f32_16x16x32_bf16 v[104:107], v[164:167], v[196:199], v[104:107]
	v_mfma_f32_16x16x32_bf16 v[92:95], v[156:159], v[204:207], v[92:95]
	v_mfma_f32_16x16x32_bf16 v[88:91], v[164:167], v[204:207], v[88:91]
	v_mfma_f32_16x16x32_bf16 v[76:79], v[156:159], v[212:215], v[76:79]
	v_mfma_f32_16x16x32_bf16 v[72:75], v[164:167], v[212:215], v[72:75]
	s_setprio 0
	s_setprio 1
	v_mfma_f32_16x16x32_bf16 v[116:119], v[168:171], v[184:187], v[116:119]
	v_mfma_f32_16x16x32_bf16 v[112:115], v[176:179], v[184:187], v[112:115]
	v_mfma_f32_16x16x32_bf16 v[100:103], v[168:171], v[192:195], v[100:103]
	v_mfma_f32_16x16x32_bf16 v[96:99], v[176:179], v[192:195], v[96:99]
	v_mfma_f32_16x16x32_bf16 v[84:87], v[168:171], v[200:203], v[84:87]
	v_mfma_f32_16x16x32_bf16 v[80:83], v[176:179], v[200:203], v[80:83]
	v_mfma_f32_16x16x32_bf16 v[68:71], v[168:171], v[208:211], v[68:71]
	v_mfma_f32_16x16x32_bf16 v[64:67], v[176:179], v[208:211], v[64:67]
	v_mfma_f32_16x16x32_bf16 v[116:119], v[172:175], v[188:191], v[116:119]
	v_mfma_f32_16x16x32_bf16 v[112:115], v[180:183], v[188:191], v[112:115]
	v_mfma_f32_16x16x32_bf16 v[100:103], v[172:175], v[196:199], v[100:103]
	v_mfma_f32_16x16x32_bf16 v[96:99], v[180:183], v[196:199], v[96:99]
	v_mfma_f32_16x16x32_bf16 v[84:87], v[172:175], v[204:207], v[84:87]
	v_mfma_f32_16x16x32_bf16 v[80:83], v[180:183], v[204:207], v[80:83]
	v_mfma_f32_16x16x32_bf16 v[68:71], v[172:175], v[212:215], v[68:71]
	v_mfma_f32_16x16x32_bf16 v[64:67], v[180:183], v[212:215], v[64:67]
	s_setprio 0
	s_barrier
	s_add_i32 s30, s60, s52
	v_lshl_add_u64 v[216:217], s[36:37], 0, v[130:131]
	s_mov_b32 m0, s30
	ds_read_b128 v[184:187], v153 offset:16384
	ds_read_b128 v[188:191], v153 offset:17408
	ds_read_b128 v[192:195], v153 offset:18432
	ds_read_b128 v[196:199], v153 offset:19456
	ds_read_b128 v[200:203], v153 offset:20480
	ds_read_b128 v[204:207], v153 offset:21504
	ds_read_b128 v[208:211], v153 offset:22528
	ds_read_b128 v[212:215], v153 offset:23552
	global_load_lds_dwordx4 v[216:217], off
	s_add_i32 m0, s30, 0x2000
	s_add_u32 s30, s36, 0x160000
	v_lshl_add_u64 v[218:219], s[36:37], 0, v[134:135]
	s_addc_u32 s31, s37, 0
	s_add_i32 s67, s61, s52
	global_load_lds_dwordx4 v[218:219], off
	v_lshl_add_u64 v[220:221], s[30:31], 0, v[130:131]
	s_mov_b32 m0, s67
	v_lshl_add_u64 v[222:223], s[48:49], 0, v[132:133]
	global_load_lds_dwordx4 v[220:221], off
	v_lshl_add_u64 v[220:221], s[30:31], 0, v[134:135]
	s_add_i32 m0, s67, 0x2000
	s_nop 0
	global_load_lds_dwordx4 v[220:221], off
	s_waitcnt vmcnt(6)
	s_waitcnt lgkmcnt(0)
	s_barrier
	v_lshl_add_u64 v[220:221], s[48:49], 0, v[128:129]
	s_mov_b32 m0, s53
	s_nop 0
	global_load_lds_dwordx4 v[220:221], off
	s_mov_b32 m0, s54
	s_nop 0
	global_load_lds_dwordx4 v[222:223], off
	s_setprio 1
	s_waitcnt lgkmcnt(0)
	v_mfma_f32_16x16x32_bf16 v[60:63], v[144:147], v[184:187], v[60:63]
	v_mfma_f32_16x16x32_bf16 v[56:59], v[160:163], v[184:187], v[56:59]
	v_mfma_f32_16x16x32_bf16 v[44:47], v[144:147], v[192:195], v[44:47]
	v_mfma_f32_16x16x32_bf16 v[40:43], v[160:163], v[192:195], v[40:43]
	v_mfma_f32_16x16x32_bf16 v[28:31], v[144:147], v[200:203], v[28:31]
	v_mfma_f32_16x16x32_bf16 v[24:27], v[160:163], v[200:203], v[24:27]
	v_mfma_f32_16x16x32_bf16 v[12:15], v[144:147], v[208:211], v[12:15]
	v_mfma_f32_16x16x32_bf16 v[8:11], v[160:163], v[208:211], v[8:11]
	v_mfma_f32_16x16x32_bf16 v[60:63], v[156:159], v[188:191], v[60:63]
	v_mfma_f32_16x16x32_bf16 v[56:59], v[164:167], v[188:191], v[56:59]
	v_mfma_f32_16x16x32_bf16 v[44:47], v[156:159], v[196:199], v[44:47]
	v_mfma_f32_16x16x32_bf16 v[40:43], v[164:167], v[196:199], v[40:43]
	v_mfma_f32_16x16x32_bf16 v[28:31], v[156:159], v[204:207], v[28:31]
	v_mfma_f32_16x16x32_bf16 v[24:27], v[164:167], v[204:207], v[24:27]
	v_mfma_f32_16x16x32_bf16 v[12:15], v[156:159], v[212:215], v[12:15]
	v_mfma_f32_16x16x32_bf16 v[8:11], v[164:167], v[212:215], v[8:11]
	s_setprio 0
	s_setprio 1
	v_mfma_f32_16x16x32_bf16 v[52:55], v[168:171], v[184:187], v[52:55]
	v_mfma_f32_16x16x32_bf16 v[48:51], v[176:179], v[184:187], v[48:51]
	v_mfma_f32_16x16x32_bf16 v[36:39], v[168:171], v[192:195], v[36:39]
	v_mfma_f32_16x16x32_bf16 v[32:35], v[176:179], v[192:195], v[32:35]
	v_mfma_f32_16x16x32_bf16 v[20:23], v[168:171], v[200:203], v[20:23]
	v_mfma_f32_16x16x32_bf16 v[16:19], v[176:179], v[200:203], v[16:19]
	v_mfma_f32_16x16x32_bf16 v[4:7], v[168:171], v[208:211], v[4:7]
	v_mfma_f32_16x16x32_bf16 v[0:3], v[176:179], v[208:211], v[0:3]
	v_mfma_f32_16x16x32_bf16 v[52:55], v[172:175], v[188:191], v[52:55]
	v_mfma_f32_16x16x32_bf16 v[48:51], v[180:183], v[188:191], v[48:51]
	v_mfma_f32_16x16x32_bf16 v[36:39], v[172:175], v[196:199], v[36:39]
	v_mfma_f32_16x16x32_bf16 v[32:35], v[180:183], v[196:199], v[32:35]
	v_mfma_f32_16x16x32_bf16 v[20:23], v[172:175], v[204:207], v[20:23]
	v_mfma_f32_16x16x32_bf16 v[16:19], v[180:183], v[204:207], v[16:19]
	v_mfma_f32_16x16x32_bf16 v[4:7], v[172:175], v[212:215], v[4:7]
	v_mfma_f32_16x16x32_bf16 v[0:3], v[180:183], v[212:215], v[0:3]
	s_setprio 0
	s_barrier
	s_add_i32 s67, 0, 0x18000
	v_add_u32_e32 v155, s67, v149
	s_add_i32 s68, 0, 0x1c000
	ds_read_b128 v[144:147], v155
	ds_read_b128 v[156:159], v155 offset:1024
	ds_read_b128 v[160:163], v155 offset:2048
	ds_read_b128 v[164:167], v155 offset:3072
	v_add_u32_e32 v155, s68, v149
	ds_read_b128 v[168:171], v155
	ds_read_b128 v[172:175], v155 offset:1024
	ds_read_b128 v[176:179], v155 offset:2048
	ds_read_b128 v[180:183], v155 offset:3072
	s_add_u32 s30, s48, 0x160000
	s_addc_u32 s31, s49, 0
	s_mov_b32 m0, s55
	v_lshl_add_u64 v[224:225], s[30:31], 0, v[128:129]
	ds_read_b128 v[184:187], v153 offset:32768
	ds_read_b128 v[188:191], v153 offset:33792
	ds_read_b128 v[192:195], v153 offset:34816
	ds_read_b128 v[196:199], v153 offset:35840
	ds_read_b128 v[200:203], v153 offset:36864
	ds_read_b128 v[204:207], v153 offset:37888
	ds_read_b128 v[208:211], v153 offset:38912
	ds_read_b128 v[212:215], v153 offset:39936
	global_load_lds_dwordx4 v[224:225], off
	v_lshl_add_u64 v[224:225], s[30:31], 0, v[132:133]
	s_mov_b32 m0, s56
	s_nop 0
	global_load_lds_dwordx4 v[224:225], off
	s_waitcnt vmcnt(8)
	s_waitcnt lgkmcnt(0)
	s_barrier
	s_setprio 1
	s_waitcnt lgkmcnt(0)
	v_mfma_f32_16x16x32_bf16 v[124:127], v[144:147], v[184:187], v[124:127]
	v_mfma_f32_16x16x32_bf16 v[120:123], v[160:163], v[184:187], v[120:123]
	v_mfma_f32_16x16x32_bf16 v[108:111], v[144:147], v[192:195], v[108:111]
	v_mfma_f32_16x16x32_bf16 v[104:107], v[160:163], v[192:195], v[104:107]
	v_mfma_f32_16x16x32_bf16 v[92:95], v[144:147], v[200:203], v[92:95]
	v_mfma_f32_16x16x32_bf16 v[88:91], v[160:163], v[200:203], v[88:91]
	v_mfma_f32_16x16x32_bf16 v[76:79], v[144:147], v[208:211], v[76:79]
	v_mfma_f32_16x16x32_bf16 v[72:75], v[160:163], v[208:211], v[72:75]
	v_mfma_f32_16x16x32_bf16 v[124:127], v[156:159], v[188:191], v[124:127]
	v_mfma_f32_16x16x32_bf16 v[120:123], v[164:167], v[188:191], v[120:123]
	v_mfma_f32_16x16x32_bf16 v[108:111], v[156:159], v[196:199], v[108:111]
	v_mfma_f32_16x16x32_bf16 v[104:107], v[164:167], v[196:199], v[104:107]
	v_mfma_f32_16x16x32_bf16 v[92:95], v[156:159], v[204:207], v[92:95]
	v_mfma_f32_16x16x32_bf16 v[88:91], v[164:167], v[204:207], v[88:91]
	v_mfma_f32_16x16x32_bf16 v[76:79], v[156:159], v[212:215], v[76:79]
	v_mfma_f32_16x16x32_bf16 v[72:75], v[164:167], v[212:215], v[72:75]
	s_setprio 0
	s_setprio 1
	v_mfma_f32_16x16x32_bf16 v[116:119], v[168:171], v[184:187], v[116:119]
	v_mfma_f32_16x16x32_bf16 v[112:115], v[176:179], v[184:187], v[112:115]
	v_mfma_f32_16x16x32_bf16 v[100:103], v[168:171], v[192:195], v[100:103]
	v_mfma_f32_16x16x32_bf16 v[96:99], v[176:179], v[192:195], v[96:99]
	v_mfma_f32_16x16x32_bf16 v[84:87], v[168:171], v[200:203], v[84:87]
	v_mfma_f32_16x16x32_bf16 v[80:83], v[176:179], v[200:203], v[80:83]
	v_mfma_f32_16x16x32_bf16 v[68:71], v[168:171], v[208:211], v[68:71]
	v_mfma_f32_16x16x32_bf16 v[64:67], v[176:179], v[208:211], v[64:67]
	v_mfma_f32_16x16x32_bf16 v[116:119], v[172:175], v[188:191], v[116:119]
	v_mfma_f32_16x16x32_bf16 v[112:115], v[180:183], v[188:191], v[112:115]
	v_mfma_f32_16x16x32_bf16 v[100:103], v[172:175], v[196:199], v[100:103]
	v_mfma_f32_16x16x32_bf16 v[96:99], v[180:183], v[196:199], v[96:99]
	v_mfma_f32_16x16x32_bf16 v[84:87], v[172:175], v[204:207], v[84:87]
	v_mfma_f32_16x16x32_bf16 v[80:83], v[180:183], v[204:207], v[80:83]
	v_mfma_f32_16x16x32_bf16 v[68:71], v[172:175], v[212:215], v[68:71]
	v_mfma_f32_16x16x32_bf16 v[64:67], v[180:183], v[212:215], v[64:67]
	s_setprio 0
	s_barrier
	s_add_i32 s30, s67, s52
	v_lshl_add_u64 v[216:217], v[216:217], 0, s[22:23]
	s_mov_b32 m0, s30
	ds_read_b128 v[184:187], v153 offset:49152
	ds_read_b128 v[188:191], v153 offset:50176
	ds_read_b128 v[192:195], v153 offset:51200
	ds_read_b128 v[196:199], v153 offset:52224
	ds_read_b128 v[200:203], v153 offset:53248
	ds_read_b128 v[204:207], v153 offset:54272
	ds_read_b128 v[208:211], v153 offset:55296
	ds_read_b128 v[212:215], v153 offset:56320
	global_load_lds_dwordx4 v[216:217], off
	s_add_i32 m0, s30, 0x2000
	s_add_u32 s30, s36, 0x160080
	v_lshl_add_u64 v[216:217], v[218:219], 0, s[22:23]
	s_addc_u32 s31, s37, 0
	s_add_i32 s36, s68, s52
	global_load_lds_dwordx4 v[216:217], off
	v_lshl_add_u64 v[216:217], s[30:31], 0, v[130:131]
	s_mov_b32 m0, s36
	s_nop 0
	global_load_lds_dwordx4 v[216:217], off
	v_lshl_add_u64 v[216:217], s[30:31], 0, v[134:135]
	s_add_i32 m0, s36, 0x2000
	s_nop 0
	global_load_lds_dwordx4 v[216:217], off
	s_waitcnt vmcnt(6)
	s_waitcnt lgkmcnt(0)
	s_barrier
	v_lshl_add_u64 v[216:217], v[220:221], 0, s[22:23]
	s_mov_b32 m0, s58
	s_nop 0
	global_load_lds_dwordx4 v[216:217], off
	v_lshl_add_u64 v[216:217], v[222:223], 0, s[22:23]
	s_mov_b32 m0, s59
	s_nop 0
	global_load_lds_dwordx4 v[216:217], off
	s_setprio 1
	s_waitcnt lgkmcnt(0)
	v_mfma_f32_16x16x32_bf16 v[60:63], v[144:147], v[184:187], v[60:63]
	v_mfma_f32_16x16x32_bf16 v[56:59], v[160:163], v[184:187], v[56:59]
	v_mfma_f32_16x16x32_bf16 v[44:47], v[144:147], v[192:195], v[44:47]
	v_mfma_f32_16x16x32_bf16 v[40:43], v[160:163], v[192:195], v[40:43]
	v_mfma_f32_16x16x32_bf16 v[28:31], v[144:147], v[200:203], v[28:31]
	v_mfma_f32_16x16x32_bf16 v[24:27], v[160:163], v[200:203], v[24:27]
	v_mfma_f32_16x16x32_bf16 v[12:15], v[144:147], v[208:211], v[12:15]
	v_mfma_f32_16x16x32_bf16 v[8:11], v[160:163], v[208:211], v[8:11]
	v_mfma_f32_16x16x32_bf16 v[60:63], v[156:159], v[188:191], v[60:63]
	v_mfma_f32_16x16x32_bf16 v[56:59], v[164:167], v[188:191], v[56:59]
	v_mfma_f32_16x16x32_bf16 v[44:47], v[156:159], v[196:199], v[44:47]
	v_mfma_f32_16x16x32_bf16 v[40:43], v[164:167], v[196:199], v[40:43]
	v_mfma_f32_16x16x32_bf16 v[28:31], v[156:159], v[204:207], v[28:31]
	v_mfma_f32_16x16x32_bf16 v[24:27], v[164:167], v[204:207], v[24:27]
	v_mfma_f32_16x16x32_bf16 v[12:15], v[156:159], v[212:215], v[12:15]
	v_mfma_f32_16x16x32_bf16 v[8:11], v[164:167], v[212:215], v[8:11]
	s_setprio 0
	s_setprio 1
	v_mfma_f32_16x16x32_bf16 v[52:55], v[168:171], v[184:187], v[52:55]
	v_mfma_f32_16x16x32_bf16 v[48:51], v[176:179], v[184:187], v[48:51]
	v_mfma_f32_16x16x32_bf16 v[36:39], v[168:171], v[192:195], v[36:39]
	v_mfma_f32_16x16x32_bf16 v[32:35], v[176:179], v[192:195], v[32:35]
	v_mfma_f32_16x16x32_bf16 v[20:23], v[168:171], v[200:203], v[20:23]
	v_mfma_f32_16x16x32_bf16 v[16:19], v[176:179], v[200:203], v[16:19]
	v_mfma_f32_16x16x32_bf16 v[4:7], v[168:171], v[208:211], v[4:7]
	v_mfma_f32_16x16x32_bf16 v[0:3], v[176:179], v[208:211], v[0:3]
	v_mfma_f32_16x16x32_bf16 v[52:55], v[172:175], v[188:191], v[52:55]
	v_mfma_f32_16x16x32_bf16 v[48:51], v[180:183], v[188:191], v[48:51]
	v_mfma_f32_16x16x32_bf16 v[36:39], v[172:175], v[196:199], v[36:39]
	v_mfma_f32_16x16x32_bf16 v[32:35], v[180:183], v[196:199], v[32:35]
	v_mfma_f32_16x16x32_bf16 v[20:23], v[172:175], v[204:207], v[20:23]
	v_mfma_f32_16x16x32_bf16 v[16:19], v[180:183], v[204:207], v[16:19]
	v_mfma_f32_16x16x32_bf16 v[4:7], v[172:175], v[212:215], v[4:7]
	v_mfma_f32_16x16x32_bf16 v[0:3], v[180:183], v[212:215], v[0:3]
	s_setprio 0
	s_barrier
	s_add_i32 s66, s66, 2
	s_add_u32 s46, s46, 0x100
	s_addc_u32 s47, s47, 0
	s_cmpk_gt_u32 s66, 0x55
	s_mov_b64 s[30:31], s[34:35]
	s_cbranch_scc0 .LBB0_1137
	s_and_b64 vcc, exec, s[24:25]
	s_cbranch_vccz .LBB0_1140
	s_barrier

.LBB0_1227:
	v_add_u32_e32 v164, s56, v150
	v_add_u32_e32 v180, s57, v150
	s_add_u32 s34, s16, s30
	ds_read_b128 v[152:155], v164
	ds_read_b128 v[156:159], v164 offset:1024
	ds_read_b128 v[160:163], v164 offset:2048
	ds_read_b128 v[164:167], v164 offset:3072
	ds_read_b128 v[168:171], v180
	ds_read_b128 v[172:175], v180 offset:1024
	ds_read_b128 v[176:179], v180 offset:2048
	ds_read_b128 v[180:183], v180 offset:3072
	s_addc_u32 s35, s17, s31
	s_add_u32 s34, s34, 0x100
	s_addc_u32 s35, s35, 0
	s_add_u32 s64, s59, s30
	s_addc_u32 s65, s60, s31
	s_cmpk_eq_i32 s30, 0xf00
	s_cselect_b32 s37, s23, s35
	s_cselect_b32 s36, s61, s34
	s_cselect_b32 s35, s21, s65
	s_cselect_b32 s34, s62, s64
	v_lshl_add_u64 v[216:217], v[146:147], 0, s[30:31]
	s_add_i32 m0, s48, 0xc000
	ds_read_b128 v[184:187], v151
	ds_read_b128 v[188:191], v151 offset:1024
	ds_read_b128 v[192:195], v151 offset:2048
	ds_read_b128 v[196:199], v151 offset:3072
	ds_read_b128 v[200:203], v151 offset:4096
	ds_read_b128 v[204:207], v151 offset:5120
	ds_read_b128 v[208:211], v151 offset:6144
	ds_read_b128 v[212:215], v151 offset:7168
	global_load_lds_dwordx4 v[216:217], off
	v_lshl_add_u64 v[216:217], v[144:145], 0, s[30:31]
	s_add_i32 m0, s48, 0xe000
	s_nop 0
	global_load_lds_dwordx4 v[216:217], off
	s_waitcnt vmcnt(8)
	s_waitcnt lgkmcnt(0)
	s_barrier
	s_setprio 1
	s_waitcnt lgkmcnt(0)
	v_mfma_f32_16x16x32_bf16 v[124:127], v[152:155], v[184:187], v[124:127]
	v_mfma_f32_16x16x32_bf16 v[120:123], v[160:163], v[184:187], v[120:123]
	v_mfma_f32_16x16x32_bf16 v[108:111], v[152:155], v[192:195], v[108:111]
	v_mfma_f32_16x16x32_bf16 v[104:107], v[160:163], v[192:195], v[104:107]
	v_mfma_f32_16x16x32_bf16 v[92:95], v[152:155], v[200:203], v[92:95]
	v_mfma_f32_16x16x32_bf16 v[88:91], v[160:163], v[200:203], v[88:91]
	v_mfma_f32_16x16x32_bf16 v[76:79], v[152:155], v[208:211], v[76:79]
	v_mfma_f32_16x16x32_bf16 v[72:75], v[160:163], v[208:211], v[72:75]
	v_mfma_f32_16x16x32_bf16 v[124:127], v[156:159], v[188:191], v[124:127]
	v_mfma_f32_16x16x32_bf16 v[120:123], v[164:167], v[188:191], v[120:123]
	v_mfma_f32_16x16x32_bf16 v[108:111], v[156:159], v[196:199], v[108:111]
	v_mfma_f32_16x16x32_bf16 v[104:107], v[164:167], v[196:199], v[104:107]
	v_mfma_f32_16x16x32_bf16 v[92:95], v[156:159], v[204:207], v[92:95]
	v_mfma_f32_16x16x32_bf16 v[88:91], v[164:167], v[204:207], v[88:91]
	v_mfma_f32_16x16x32_bf16 v[76:79], v[156:159], v[212:215], v[76:79]
	v_mfma_f32_16x16x32_bf16 v[72:75], v[164:167], v[212:215], v[72:75]
	s_setprio 0
	s_setprio 1
	v_mfma_f32_16x16x32_bf16 v[116:119], v[168:171], v[184:187], v[116:119]
	v_mfma_f32_16x16x32_bf16 v[112:115], v[176:179], v[184:187], v[112:115]
	v_mfma_f32_16x16x32_bf16 v[100:103], v[168:171], v[192:195], v[100:103]
	v_mfma_f32_16x16x32_bf16 v[96:99], v[176:179], v[192:195], v[96:99]
	v_mfma_f32_16x16x32_bf16 v[84:87], v[168:171], v[200:203], v[84:87]
	v_mfma_f32_16x16x32_bf16 v[80:83], v[176:179], v[200:203], v[80:83]
	v_mfma_f32_16x16x32_bf16 v[68:71], v[168:171], v[208:211], v[68:71]
	v_mfma_f32_16x16x32_bf16 v[64:67], v[176:179], v[208:211], v[64:67]
	v_mfma_f32_16x16x32_bf16 v[116:119], v[172:175], v[188:191], v[116:119]
	v_mfma_f32_16x16x32_bf16 v[112:115], v[180:183], v[188:191], v[112:115]
	v_mfma_f32_16x16x32_bf16 v[100:103], v[172:175], v[196:199], v[100:103]
	v_mfma_f32_16x16x32_bf16 v[96:99], v[180:183], v[196:199], v[96:99]
	v_mfma_f32_16x16x32_bf16 v[84:87], v[172:175], v[204:207], v[84:87]
	v_mfma_f32_16x16x32_bf16 v[80:83], v[180:183], v[204:207], v[80:83]
	v_mfma_f32_16x16x32_bf16 v[68:71], v[172:175], v[212:215], v[68:71]
	v_mfma_f32_16x16x32_bf16 v[64:67], v[180:183], v[212:215], v[64:67]
	s_setprio 0
	s_barrier
	s_add_i32 s64, s56, s47
	v_lshl_add_u64 v[216:217], s[34:35], 0, v[130:131]
	s_mov_b32 m0, s64
	ds_read_b128 v[184:187], v151 offset:16384
	ds_read_b128 v[188:191], v151 offset:17408
	ds_read_b128 v[192:195], v151 offset:18432
	ds_read_b128 v[196:199], v151 offset:19456
	ds_read_b128 v[200:203], v151 offset:20480
	ds_read_b128 v[204:207], v151 offset:21504
	ds_read_b128 v[208:211], v151 offset:22528
	ds_read_b128 v[212:215], v151 offset:23552
	global_load_lds_dwordx4 v[216:217], off
	s_add_i32 m0, s64, 0x2000
	s_add_u32 s64, s34, 0x80000
	v_lshl_add_u64 v[218:219], s[34:35], 0, v[134:135]
	s_addc_u32 s65, s35, 0
	s_add_i32 s66, s57, s47
	global_load_lds_dwordx4 v[218:219], off
	v_lshl_add_u64 v[220:221], s[64:65], 0, v[130:131]
	s_mov_b32 m0, s66
	v_lshl_add_u64 v[222:223], s[36:37], 0, v[132:133]
	global_load_lds_dwordx4 v[220:221], off
	v_lshl_add_u64 v[220:221], s[64:65], 0, v[134:135]
	s_add_i32 m0, s66, 0x2000
	s_nop 0
	global_load_lds_dwordx4 v[220:221], off
	s_waitcnt vmcnt(6)
	s_waitcnt lgkmcnt(0)
	s_barrier
	v_lshl_add_u64 v[220:221], s[36:37], 0, v[128:129]
	s_mov_b32 m0, s48
	s_nop 0
	global_load_lds_dwordx4 v[220:221], off
	s_mov_b32 m0, s49
	s_nop 0
	global_load_lds_dwordx4 v[222:223], off
	s_setprio 1
	s_waitcnt lgkmcnt(0)
	v_mfma_f32_16x16x32_bf16 v[60:63], v[152:155], v[184:187], v[60:63]
	v_mfma_f32_16x16x32_bf16 v[56:59], v[160:163], v[184:187], v[56:59]
	v_mfma_f32_16x16x32_bf16 v[44:47], v[152:155], v[192:195], v[44:47]
	v_mfma_f32_16x16x32_bf16 v[40:43], v[160:163], v[192:195], v[40:43]
	v_mfma_f32_16x16x32_bf16 v[28:31], v[152:155], v[200:203], v[28:31]
	v_mfma_f32_16x16x32_bf16 v[24:27], v[160:163], v[200:203], v[24:27]
	v_mfma_f32_16x16x32_bf16 v[12:15], v[152:155], v[208:211], v[12:15]
	v_mfma_f32_16x16x32_bf16 v[8:11], v[160:163], v[208:211], v[8:11]
	v_mfma_f32_16x16x32_bf16 v[60:63], v[156:159], v[188:191], v[60:63]
	v_mfma_f32_16x16x32_bf16 v[56:59], v[164:167], v[188:191], v[56:59]
	v_mfma_f32_16x16x32_bf16 v[44:47], v[156:159], v[196:199], v[44:47]
	v_mfma_f32_16x16x32_bf16 v[40:43], v[164:167], v[196:199], v[40:43]
	v_mfma_f32_16x16x32_bf16 v[28:31], v[156:159], v[204:207], v[28:31]
	v_mfma_f32_16x16x32_bf16 v[24:27], v[164:167], v[204:207], v[24:27]
	v_mfma_f32_16x16x32_bf16 v[12:15], v[156:159], v[212:215], v[12:15]
	v_mfma_f32_16x16x32_bf16 v[8:11], v[164:167], v[212:215], v[8:11]
	s_setprio 0
	s_setprio 1
	v_mfma_f32_16x16x32_bf16 v[52:55], v[168:171], v[184:187], v[52:55]
	v_mfma_f32_16x16x32_bf16 v[48:51], v[176:179], v[184:187], v[48:51]
	v_mfma_f32_16x16x32_bf16 v[36:39], v[168:171], v[192:195], v[36:39]
	v_mfma_f32_16x16x32_bf16 v[32:35], v[176:179], v[192:195], v[32:35]
	v_mfma_f32_16x16x32_bf16 v[20:23], v[168:171], v[200:203], v[20:23]
	v_mfma_f32_16x16x32_bf16 v[16:19], v[176:179], v[200:203], v[16:19]
	v_mfma_f32_16x16x32_bf16 v[4:7], v[168:171], v[208:211], v[4:7]
	v_mfma_f32_16x16x32_bf16 v[0:3], v[176:179], v[208:211], v[0:3]
	v_mfma_f32_16x16x32_bf16 v[52:55], v[172:175], v[188:191], v[52:55]
	v_mfma_f32_16x16x32_bf16 v[48:51], v[180:183], v[188:191], v[48:51]
	v_mfma_f32_16x16x32_bf16 v[36:39], v[172:175], v[196:199], v[36:39]
	v_mfma_f32_16x16x32_bf16 v[32:35], v[180:183], v[196:199], v[32:35]
	v_mfma_f32_16x16x32_bf16 v[20:23], v[172:175], v[204:207], v[20:23]
	v_mfma_f32_16x16x32_bf16 v[16:19], v[180:183], v[204:207], v[16:19]
	v_mfma_f32_16x16x32_bf16 v[4:7], v[172:175], v[212:215], v[4:7]
	v_mfma_f32_16x16x32_bf16 v[0:3], v[180:183], v[212:215], v[0:3]
	s_setprio 0
	s_barrier
	s_add_i32 s64, 0, 0x18000
	s_add_i32 s65, 0, 0x1c000
	v_add_u32_e32 v164, s64, v150
	v_add_u32_e32 v180, s65, v150
	ds_read_b128 v[152:155], v164
	ds_read_b128 v[156:159], v164 offset:1024
	ds_read_b128 v[160:163], v164 offset:2048
	ds_read_b128 v[164:167], v164 offset:3072
	ds_read_b128 v[168:171], v180
	ds_read_b128 v[172:175], v180 offset:1024
	ds_read_b128 v[176:179], v180 offset:2048
	ds_read_b128 v[180:183], v180 offset:3072
	s_add_u32 s36, s36, 0x80000
	s_addc_u32 s37, s37, 0
	s_mov_b32 m0, s50
	v_lshl_add_u64 v[224:225], s[36:37], 0, v[128:129]
	ds_read_b128 v[184:187], v151 offset:32768
	ds_read_b128 v[188:191], v151 offset:33792
	ds_read_b128 v[192:195], v151 offset:34816
	ds_read_b128 v[196:199], v151 offset:35840
	ds_read_b128 v[200:203], v151 offset:36864
	ds_read_b128 v[204:207], v151 offset:37888
	ds_read_b128 v[208:211], v151 offset:38912
	ds_read_b128 v[212:215], v151 offset:39936
	global_load_lds_dwordx4 v[224:225], off
	v_lshl_add_u64 v[224:225], s[36:37], 0, v[132:133]
	s_mov_b32 m0, s51
	s_nop 0
	global_load_lds_dwordx4 v[224:225], off
	s_waitcnt vmcnt(8)
	s_waitcnt lgkmcnt(0)
	s_barrier
	s_setprio 1
	s_waitcnt lgkmcnt(0)
	v_mfma_f32_16x16x32_bf16 v[124:127], v[152:155], v[184:187], v[124:127]
	v_mfma_f32_16x16x32_bf16 v[120:123], v[160:163], v[184:187], v[120:123]
	v_mfma_f32_16x16x32_bf16 v[108:111], v[152:155], v[192:195], v[108:111]
	v_mfma_f32_16x16x32_bf16 v[104:107], v[160:163], v[192:195], v[104:107]
	v_mfma_f32_16x16x32_bf16 v[92:95], v[152:155], v[200:203], v[92:95]
	v_mfma_f32_16x16x32_bf16 v[88:91], v[160:163], v[200:203], v[88:91]
	v_mfma_f32_16x16x32_bf16 v[76:79], v[152:155], v[208:211], v[76:79]
	v_mfma_f32_16x16x32_bf16 v[72:75], v[160:163], v[208:211], v[72:75]
	v_mfma_f32_16x16x32_bf16 v[124:127], v[156:159], v[188:191], v[124:127]
	v_mfma_f32_16x16x32_bf16 v[120:123], v[164:167], v[188:191], v[120:123]
	v_mfma_f32_16x16x32_bf16 v[108:111], v[156:159], v[196:199], v[108:111]
	v_mfma_f32_16x16x32_bf16 v[104:107], v[164:167], v[196:199], v[104:107]
	v_mfma_f32_16x16x32_bf16 v[92:95], v[156:159], v[204:207], v[92:95]
	v_mfma_f32_16x16x32_bf16 v[88:91], v[164:167], v[204:207], v[88:91]
	v_mfma_f32_16x16x32_bf16 v[76:79], v[156:159], v[212:215], v[76:79]
	v_mfma_f32_16x16x32_bf16 v[72:75], v[164:167], v[212:215], v[72:75]
	s_setprio 0
	s_setprio 1
	v_mfma_f32_16x16x32_bf16 v[116:119], v[168:171], v[184:187], v[116:119]
	v_mfma_f32_16x16x32_bf16 v[112:115], v[176:179], v[184:187], v[112:115]
	v_mfma_f32_16x16x32_bf16 v[100:103], v[168:171], v[192:195], v[100:103]
	v_mfma_f32_16x16x32_bf16 v[96:99], v[176:179], v[192:195], v[96:99]
	v_mfma_f32_16x16x32_bf16 v[84:87], v[168:171], v[200:203], v[84:87]
	v_mfma_f32_16x16x32_bf16 v[80:83], v[176:179], v[200:203], v[80:83]
	v_mfma_f32_16x16x32_bf16 v[68:71], v[168:171], v[208:211], v[68:71]
	v_mfma_f32_16x16x32_bf16 v[64:67], v[176:179], v[208:211], v[64:67]
	v_mfma_f32_16x16x32_bf16 v[116:119], v[172:175], v[188:191], v[116:119]
	v_mfma_f32_16x16x32_bf16 v[112:115], v[180:183], v[188:191], v[112:115]
	v_mfma_f32_16x16x32_bf16 v[100:103], v[172:175], v[196:199], v[100:103]
	v_mfma_f32_16x16x32_bf16 v[96:99], v[180:183], v[196:199], v[96:99]
	v_mfma_f32_16x16x32_bf16 v[84:87], v[172:175], v[204:207], v[84:87]
	v_mfma_f32_16x16x32_bf16 v[80:83], v[180:183], v[204:207], v[80:83]
	v_mfma_f32_16x16x32_bf16 v[68:71], v[172:175], v[212:215], v[68:71]
	v_mfma_f32_16x16x32_bf16 v[64:67], v[180:183], v[212:215], v[64:67]
	s_setprio 0
	s_barrier
	s_add_i32 s36, s64, s47
	v_lshl_add_u64 v[216:217], v[216:217], 0, s[18:19]
	s_mov_b32 m0, s36
	ds_read_b128 v[184:187], v151 offset:49152
	ds_read_b128 v[188:191], v151 offset:50176
	ds_read_b128 v[192:195], v151 offset:51200
	ds_read_b128 v[196:199], v151 offset:52224
	ds_read_b128 v[200:203], v151 offset:53248
	ds_read_b128 v[204:207], v151 offset:54272
	ds_read_b128 v[208:211], v151 offset:55296
	ds_read_b128 v[212:215], v151 offset:56320
	global_load_lds_dwordx4 v[216:217], off
	s_add_i32 m0, s36, 0x2000
	s_add_u32 s34, s34, 0x80080
	v_lshl_add_u64 v[216:217], v[218:219], 0, s[18:19]
	s_addc_u32 s35, s35, 0
	s_add_i32 s36, s65, s47
	global_load_lds_dwordx4 v[216:217], off
	v_lshl_add_u64 v[216:217], s[34:35], 0, v[130:131]
	s_mov_b32 m0, s36
	s_nop 0
	global_load_lds_dwordx4 v[216:217], off
	v_lshl_add_u64 v[216:217], s[34:35], 0, v[134:135]
	s_add_i32 m0, s36, 0x2000
	s_nop 0
	global_load_lds_dwordx4 v[216:217], off
	s_waitcnt vmcnt(6)
	s_waitcnt lgkmcnt(0)
	s_barrier
	v_lshl_add_u64 v[216:217], v[220:221], 0, s[18:19]
	s_mov_b32 m0, s54
	s_nop 0
	global_load_lds_dwordx4 v[216:217], off
	v_lshl_add_u64 v[216:217], v[222:223], 0, s[18:19]
	s_mov_b32 m0, s55
	s_nop 0
	global_load_lds_dwordx4 v[216:217], off
	s_setprio 1
	s_waitcnt lgkmcnt(0)
	v_mfma_f32_16x16x32_bf16 v[60:63], v[152:155], v[184:187], v[60:63]
	v_mfma_f32_16x16x32_bf16 v[56:59], v[160:163], v[184:187], v[56:59]
	v_mfma_f32_16x16x32_bf16 v[44:47], v[152:155], v[192:195], v[44:47]
	v_mfma_f32_16x16x32_bf16 v[40:43], v[160:163], v[192:195], v[40:43]
	v_mfma_f32_16x16x32_bf16 v[28:31], v[152:155], v[200:203], v[28:31]
	v_mfma_f32_16x16x32_bf16 v[24:27], v[160:163], v[200:203], v[24:27]
	v_mfma_f32_16x16x32_bf16 v[12:15], v[152:155], v[208:211], v[12:15]
	v_mfma_f32_16x16x32_bf16 v[8:11], v[160:163], v[208:211], v[8:11]
	v_mfma_f32_16x16x32_bf16 v[60:63], v[156:159], v[188:191], v[60:63]
	v_mfma_f32_16x16x32_bf16 v[56:59], v[164:167], v[188:191], v[56:59]
	v_mfma_f32_16x16x32_bf16 v[44:47], v[156:159], v[196:199], v[44:47]
	v_mfma_f32_16x16x32_bf16 v[40:43], v[164:167], v[196:199], v[40:43]
	v_mfma_f32_16x16x32_bf16 v[28:31], v[156:159], v[204:207], v[28:31]
	v_mfma_f32_16x16x32_bf16 v[24:27], v[164:167], v[204:207], v[24:27]
	v_mfma_f32_16x16x32_bf16 v[12:15], v[156:159], v[212:215], v[12:15]
	v_mfma_f32_16x16x32_bf16 v[8:11], v[164:167], v[212:215], v[8:11]
	s_setprio 0
	s_setprio 1
	v_mfma_f32_16x16x32_bf16 v[52:55], v[168:171], v[184:187], v[52:55]
	v_mfma_f32_16x16x32_bf16 v[48:51], v[176:179], v[184:187], v[48:51]
	v_mfma_f32_16x16x32_bf16 v[36:39], v[168:171], v[192:195], v[36:39]
	v_mfma_f32_16x16x32_bf16 v[32:35], v[176:179], v[192:195], v[32:35]
	v_mfma_f32_16x16x32_bf16 v[20:23], v[168:171], v[200:203], v[20:23]
	v_mfma_f32_16x16x32_bf16 v[16:19], v[176:179], v[200:203], v[16:19]
	v_mfma_f32_16x16x32_bf16 v[4:7], v[168:171], v[208:211], v[4:7]
	v_mfma_f32_16x16x32_bf16 v[0:3], v[176:179], v[208:211], v[0:3]
	v_mfma_f32_16x16x32_bf16 v[52:55], v[172:175], v[188:191], v[52:55]
	v_mfma_f32_16x16x32_bf16 v[48:51], v[180:183], v[188:191], v[48:51]
	v_mfma_f32_16x16x32_bf16 v[36:39], v[172:175], v[196:199], v[36:39]
	v_mfma_f32_16x16x32_bf16 v[32:35], v[180:183], v[196:199], v[32:35]
	v_mfma_f32_16x16x32_bf16 v[20:23], v[172:175], v[204:207], v[20:23]
	v_mfma_f32_16x16x32_bf16 v[16:19], v[180:183], v[204:207], v[16:19]
	v_mfma_f32_16x16x32_bf16 v[4:7], v[172:175], v[212:215], v[4:7]
	v_mfma_f32_16x16x32_bf16 v[0:3], v[180:183], v[212:215], v[0:3]
	s_setprio 0
	s_barrier
	s_add_i32 s63, s63, 2
	s_add_u32 s30, s30, 0x100
	s_addc_u32 s31, s31, 0
	s_cmp_gt_u32 s63, 29
	s_cbranch_scc0 .LBB0_1227
	s_add_u32 s30, s59, 0xffffff00
	s_addc_u32 s31, s60, -1
	s_andn2_b64 vcc, exec, s[4:5]
	s_cbranch_vccnz .LBB0_1230
	v_mov_b32_e32 v0, 0
	s_mov_b32 s15, s20
	s_mov_b32 s14, s22
	s_mov_b64 s[16:17], s[26:27]
	s_mov_b32 s53, s58
	v_mov_b32_e32 v1, v0
	v_mov_b32_e32 v2, v0
	v_mov_b32_e32 v3, v0
	v_mov_b32_e32 v4, v0
	v_mov_b32_e32 v5, v0
	v_mov_b32_e32 v6, v0
	v_mov_b32_e32 v7, v0
	v_mov_b32_e32 v16, v0
	v_mov_b32_e32 v17, v0
	v_mov_b32_e32 v18, v0
	v_mov_b32_e32 v19, v0
	v_mov_b32_e32 v20, v0
	v_mov_b32_e32 v21, v0
	v_mov_b32_e32 v22, v0
	v_mov_b32_e32 v23, v0
	v_mov_b32_e32 v32, v0
	v_mov_b32_e32 v33, v0
	v_mov_b32_e32 v34, v0
	v_mov_b32_e32 v35, v0
	v_mov_b32_e32 v36, v0
	v_mov_b32_e32 v37, v0
	v_mov_b32_e32 v38, v0
	v_mov_b32_e32 v39, v0
	v_mov_b32_e32 v48, v0
	v_mov_b32_e32 v49, v0
	v_mov_b32_e32 v50, v0
	v_mov_b32_e32 v51, v0
	v_mov_b32_e32 v52, v0
	v_mov_b32_e32 v53, v0
	v_mov_b32_e32 v54, v0
	v_mov_b32_e32 v55, v0
	v_mov_b32_e32 v8, v0
	v_mov_b32_e32 v9, v0
	v_mov_b32_e32 v10, v0
	v_mov_b32_e32 v11, v0
	v_mov_b32_e32 v12, v0
	v_mov_b32_e32 v13, v0
	v_mov_b32_e32 v14, v0
	v_mov_b32_e32 v15, v0
	v_mov_b32_e32 v24, v0
	v_mov_b32_e32 v25, v0
	v_mov_b32_e32 v26, v0
	v_mov_b32_e32 v27, v0
	v_mov_b32_e32 v28, v0
	v_mov_b32_e32 v29, v0
	v_mov_b32_e32 v30, v0
	v_mov_b32_e32 v31, v0
	v_mov_b32_e32 v40, v0
	v_mov_b32_e32 v41, v0
	v_mov_b32_e32 v42, v0
	v_mov_b32_e32 v43, v0
	v_mov_b32_e32 v44, v0
	v_mov_b32_e32 v45, v0
	v_mov_b32_e32 v46, v0
	v_mov_b32_e32 v47, v0
	v_mov_b32_e32 v56, v0
	v_mov_b32_e32 v57, v0
	v_mov_b32_e32 v58, v0
	v_mov_b32_e32 v59, v0
	v_mov_b32_e32 v60, v0
	v_mov_b32_e32 v61, v0
	v_mov_b32_e32 v62, v0
	v_mov_b32_e32 v63, v0
	v_mov_b32_e32 v64, v0
	v_mov_b32_e32 v65, v0
	v_mov_b32_e32 v66, v0
	v_mov_b32_e32 v67, v0
	v_mov_b32_e32 v68, v0
	v_mov_b32_e32 v69, v0
	v_mov_b32_e32 v70, v0
	v_mov_b32_e32 v71, v0
	v_mov_b32_e32 v80, v0
	v_mov_b32_e32 v81, v0
	v_mov_b32_e32 v82, v0
	v_mov_b32_e32 v83, v0
	v_mov_b32_e32 v84, v0
	v_mov_b32_e32 v85, v0
	v_mov_b32_e32 v86, v0
	v_mov_b32_e32 v87, v0
	v_mov_b32_e32 v96, v0
	v_mov_b32_e32 v97, v0
	v_mov_b32_e32 v98, v0
	v_mov_b32_e32 v99, v0
	v_mov_b32_e32 v100, v0
	v_mov_b32_e32 v101, v0
	v_mov_b32_e32 v102, v0
	v_mov_b32_e32 v103, v0
	v_mov_b32_e32 v112, v0
	v_mov_b32_e32 v113, v0
	v_mov_b32_e32 v114, v0
	v_mov_b32_e32 v115, v0
	v_mov_b32_e32 v116, v0
	v_mov_b32_e32 v117, v0
	v_mov_b32_e32 v118, v0
	v_mov_b32_e32 v119, v0
	v_mov_b32_e32 v72, v0
	v_mov_b32_e32 v73, v0
	v_mov_b32_e32 v74, v0
	v_mov_b32_e32 v75, v0
	v_mov_b32_e32 v76, v0
	v_mov_b32_e32 v77, v0
	v_mov_b32_e32 v78, v0
	v_mov_b32_e32 v79, v0
	v_mov_b32_e32 v88, v0
	v_mov_b32_e32 v89, v0
	v_mov_b32_e32 v90, v0
	v_mov_b32_e32 v91, v0
	v_mov_b32_e32 v92, v0
	v_mov_b32_e32 v93, v0
	v_mov_b32_e32 v94, v0
	v_mov_b32_e32 v95, v0
	v_mov_b32_e32 v104, v0
	v_mov_b32_e32 v105, v0
	v_mov_b32_e32 v106, v0
	v_mov_b32_e32 v107, v0
	v_mov_b32_e32 v108, v0
	v_mov_b32_e32 v109, v0
	v_mov_b32_e32 v110, v0
	v_mov_b32_e32 v111, v0
	v_mov_b32_e32 v120, v0
	v_mov_b32_e32 v121, v0
	v_mov_b32_e32 v122, v0
	v_mov_b32_e32 v123, v0
	v_mov_b32_e32 v124, v0
	v_mov_b32_e32 v125, v0
	v_mov_b32_e32 v126, v0
	v_mov_b32_e32 v127, v0
	s_andn2_b64 vcc, exec, s[0:1]
	s_cbranch_vccnz .LBB0_1231
	s_branch .LBB0_1232
